# P4 epilogue: second-pass conv weight/bias loads hoisted into the first pass (free registers), on v30
# baseline (speedup 1.0000x reference)
.LBB0_868:
	s_mov_b64 s[14:15], 0
	s_cbranch_execz .LBB0_886
	global_load_dwordx4 v[34:37], v[216:217], off
	global_load_dwordx4 v[38:41], v[118:119], off
	global_load_dwordx4 v[18:21], v[218:219], off
	global_load_dwordx4 v[22:25], v[220:221], off
	global_load_dwordx4 v[30:33], v[212:213], off
	global_load_dwordx4 v[26:29], v[116:117], off
	global_load_dwordx4 v[10:13], v[214:215], off
	global_load_dwordx4 v[6:9], v[210:211], off
	v_mov_b32_dpp v0, v202 row_shl:15 row_mask:0xf bank_mask:0xf bound_ctrl:1
	v_mov_b32_dpp v2, v202 row_shl:14 row_mask:0xf bank_mask:0xf bound_ctrl:1
	v_mov_b32_dpp v1, v203 row_shl:15 row_mask:0xf bank_mask:0xf bound_ctrl:1
	v_mov_b32_dpp v3, v203 row_shl:14 row_mask:0xf bank_mask:0xf bound_ctrl:1
	v_mov_b32_dpp v4, v204 row_shl:15 row_mask:0xf bank_mask:0xf bound_ctrl:1
	v_mov_b32_dpp v14, v204 row_shl:14 row_mask:0xf bank_mask:0xf bound_ctrl:1
	v_mov_b32_dpp v5, v205 row_shl:15 row_mask:0xf bank_mask:0xf bound_ctrl:1
	v_mov_b32_dpp v15, v205 row_shl:14 row_mask:0xf bank_mask:0xf bound_ctrl:1
	v_mov_b32_e32 v48, v0
	v_mov_b32_e32 v50, v2
	v_mov_b32_e32 v49, v1
	v_mov_b32_e32 v51, v3
	v_mov_b32_e32 v52, v4
	v_mov_b32_e32 v54, v14
	v_mov_b32_e32 v53, v5
	v_mov_b32_e32 v55, v15
	v_mov_b32_dpp v48, v202 row_shr:1 row_mask:0xf bank_mask:0xf
	v_mov_b32_dpp v50, v202 row_shr:2 row_mask:0xf bank_mask:0xf
	v_mov_b32_dpp v49, v203 row_shr:1 row_mask:0xf bank_mask:0xf
	v_mov_b32_dpp v51, v203 row_shr:2 row_mask:0xf bank_mask:0xf
	v_mov_b32_dpp v52, v204 row_shr:1 row_mask:0xf bank_mask:0xf
	v_mov_b32_dpp v54, v204 row_shr:2 row_mask:0xf bank_mask:0xf
	v_mov_b32_dpp v53, v205 row_shr:1 row_mask:0xf bank_mask:0xf
	v_mov_b32_dpp v55, v205 row_shr:2 row_mask:0xf bank_mask:0xf
	v_mov_b32_dpp v16, v206 row_shl:15 row_mask:0xf bank_mask:0xf bound_ctrl:1
	v_mov_b32_dpp v42, v206 row_shl:14 row_mask:0xf bank_mask:0xf bound_ctrl:1
	v_mov_b32_dpp v17, v207 row_shl:15 row_mask:0xf bank_mask:0xf bound_ctrl:1
	v_mov_b32_dpp v43, v207 row_shl:14 row_mask:0xf bank_mask:0xf bound_ctrl:1
	v_mov_b32_dpp v44, v208 row_shl:15 row_mask:0xf bank_mask:0xf bound_ctrl:1
	v_mov_b32_dpp v46, v208 row_shl:14 row_mask:0xf bank_mask:0xf bound_ctrl:1
	v_mov_b32_dpp v45, v209 row_shl:15 row_mask:0xf bank_mask:0xf bound_ctrl:1
	v_mov_b32_dpp v47, v209 row_shl:14 row_mask:0xf bank_mask:0xf bound_ctrl:1
	v_mov_b32_e32 v56, v16
	v_mov_b32_e32 v210, v42
	v_mov_b32_e32 v57, v17
	v_mov_b32_e32 v211, v43
	v_mov_b32_e32 v212, v44
	v_mov_b32_e32 v214, v46
	v_mov_b32_e32 v213, v45
	v_mov_b32_e32 v215, v47
	v_mov_b32_dpp v56, v206 row_shr:1 row_mask:0xf bank_mask:0xf
	v_mov_b32_dpp v210, v206 row_shr:2 row_mask:0xf bank_mask:0xf
	v_mov_b32_dpp v57, v207 row_shr:1 row_mask:0xf bank_mask:0xf
	v_mov_b32_dpp v211, v207 row_shr:2 row_mask:0xf bank_mask:0xf
	v_mov_b32_dpp v212, v208 row_shr:1 row_mask:0xf bank_mask:0xf
	v_mov_b32_dpp v214, v208 row_shr:2 row_mask:0xf bank_mask:0xf
	v_mov_b32_dpp v213, v209 row_shr:1 row_mask:0xf bank_mask:0xf
	v_mov_b32_dpp v215, v209 row_shr:2 row_mask:0xf bank_mask:0xf
	v_mov_b32_dpp v0, v200 row_shr:1 row_mask:0xf bank_mask:0xf
	v_mov_b32_dpp v1, v201 row_shr:1 row_mask:0xf bank_mask:0xf
	v_mov_b32_dpp v4, v196 row_shr:1 row_mask:0xf bank_mask:0xf
	v_mov_b32_dpp v5, v197 row_shr:1 row_mask:0xf bank_mask:0xf
	v_mov_b32_dpp v2, v200 row_shr:2 row_mask:0xf bank_mask:0xf
	v_mov_b32_dpp v3, v201 row_shr:2 row_mask:0xf bank_mask:0xf
	v_mov_b32_dpp v14, v196 row_shr:2 row_mask:0xf bank_mask:0xf
	v_mov_b32_dpp v15, v197 row_shr:2 row_mask:0xf bank_mask:0xf
	v_mov_b32_dpp v44, v194 row_shr:1 row_mask:0xf bank_mask:0xf
	v_mov_b32_dpp v45, v195 row_shr:1 row_mask:0xf bank_mask:0xf
	v_mov_b32_dpp v16, v198 row_shr:1 row_mask:0xf bank_mask:0xf
	v_mov_b32_dpp v17, v199 row_shr:1 row_mask:0xf bank_mask:0xf
	v_mov_b32_dpp v42, v198 row_shr:2 row_mask:0xf bank_mask:0xf
	v_mov_b32_dpp v43, v199 row_shr:2 row_mask:0xf bank_mask:0xf
	v_mov_b32_dpp v46, v194 row_shr:2 row_mask:0xf bank_mask:0xf
	v_mov_b32_dpp v47, v195 row_shr:2 row_mask:0xf bank_mask:0xf
	v_cmp_gt_i32_e32 vcc, s93, v232
	s_and_b64 s[22:23], s[12:13], vcc
	s_waitcnt vmcnt(0)
	v_pk_fma_f32 v[204:205], v[204:205], v[36:37], v[40:41]
	v_pk_fma_f32 v[202:203], v[202:203], v[34:35], v[38:39]
	v_pk_fma_f32 v[208:209], v[208:209], v[20:21], v[24:25]
	v_pk_fma_f32 v[52:53], v[32:33], v[52:53], v[204:205]
	v_pk_fma_f32 v[48:49], v[30:31], v[48:49], v[202:203]
	v_pk_fma_f32 v[206:207], v[206:207], v[18:19], v[22:23]
	v_pk_fma_f32 v[48:49], v[26:27], v[50:51], v[48:49]
	v_pk_fma_f32 v[50:51], v[28:29], v[54:55], v[52:53]
	v_pk_mul_f32 v[54:55], v[48:49], v[48:49]
	v_pk_mul_f32 v[52:53], v[50:51], v[50:51]
	v_pk_fma_f32 v[54:55], v[54:55], s[52:53], 1.0 op_sel_hi:[1,0,0]
	v_pk_fma_f32 v[52:53], v[52:53], s[52:53], 1.0 op_sel_hi:[1,0,0]
	v_pk_mul_f32 v[54:55], v[48:49], v[54:55]
	v_pk_mul_f32 v[52:53], v[50:51], v[52:53]
	v_pk_mul_f32 v[54:55], v[54:55], s[54:55] op_sel_hi:[1,0]
	v_pk_mul_f32 v[52:53], v[52:53], s[54:55] op_sel_hi:[1,0]
	v_exp_f32_e32 v54, v54
	v_exp_f32_e32 v55, v55
	v_exp_f32_e32 v52, v52
	v_exp_f32_e32 v53, v53
	v_pk_fma_f32 v[56:57], v[10:11], v[56:57], v[206:207]
	v_pk_add_f32 v[54:55], v[54:55], 1.0 op_sel_hi:[1,0]
	v_pk_fma_f32 v[202:203], v[12:13], v[212:213], v[208:209]
	v_pk_add_f32 v[52:53], v[52:53], 1.0 op_sel_hi:[1,0]
	v_rcp_f32_e32 v54, v54
	v_rcp_f32_e32 v55, v55
	v_rcp_f32_e32 v52, v52
	v_rcp_f32_e32 v53, v53
	v_pk_fma_f32 v[202:203], v[8:9], v[214:215], v[202:203]
	v_pk_fma_f32 v[56:57], v[6:7], v[210:211], v[56:57]
	v_pk_mul_f32 v[48:49], v[48:49], v[54:55]
	v_pk_mul_f32 v[50:51], v[50:51], v[52:53]
	v_pk_mul_f32 v[48:49], v[56:57], v[48:49]
	v_pk_mul_f32 v[52:53], v[202:203], v[50:51]
	v_cvt_pk_bf16_f32 v50, v48, v49
	v_pk_fma_f32 v[48:49], v[196:197], v[36:37], v[40:41]
	v_cvt_pk_bf16_f32 v51, v52, v53
	v_pk_fma_f32 v[52:53], v[200:201], v[34:35], v[38:39]
	v_pk_fma_f32 v[4:5], v[32:33], v[4:5], v[48:49]
	v_pk_fma_f32 v[0:1], v[30:31], v[0:1], v[52:53]
	v_pk_fma_f32 v[52:53], v[186:187], v[18:19], v[22:23]
	v_pk_fma_f32 v[0:1], v[26:27], v[2:3], v[0:1]
	v_pk_fma_f32 v[2:3], v[28:29], v[14:15], v[4:5]
	v_pk_fma_f32 v[4:5], v[194:195], v[20:21], v[24:25]
	v_pk_fma_f32 v[14:15], v[198:199], v[18:19], v[22:23]
	v_pk_fma_f32 v[4:5], v[12:13], v[44:45], v[4:5]
	v_pk_mul_f32 v[44:45], v[0:1], v[0:1]
	v_pk_fma_f32 v[14:15], v[10:11], v[16:17], v[14:15]
	v_pk_mul_f32 v[16:17], v[2:3], v[2:3]
	v_pk_fma_f32 v[44:45], v[44:45], s[52:53], 1.0 op_sel_hi:[1,0,0]
	v_pk_fma_f32 v[16:17], v[16:17], s[52:53], 1.0 op_sel_hi:[1,0,0]
	v_pk_mul_f32 v[44:45], v[0:1], v[44:45]
	v_pk_mul_f32 v[16:17], v[2:3], v[16:17]
	v_pk_mul_f32 v[44:45], v[44:45], s[54:55] op_sel_hi:[1,0]
	v_pk_mul_f32 v[16:17], v[16:17], s[54:55] op_sel_hi:[1,0]
	v_exp_f32_e32 v44, v44
	v_exp_f32_e32 v45, v45
	v_exp_f32_e32 v16, v16
	v_exp_f32_e32 v17, v17
	v_pk_fma_f32 v[14:15], v[6:7], v[42:43], v[14:15]
	v_pk_add_f32 v[44:45], v[44:45], 1.0 op_sel_hi:[1,0]
	v_pk_fma_f32 v[4:5], v[8:9], v[46:47], v[4:5]
	v_rcp_f32_e32 v44, v44
	v_rcp_f32_e32 v45, v45
	v_pk_add_f32 v[16:17], v[16:17], 1.0 op_sel_hi:[1,0]
	v_pk_fma_f32 v[42:43], v[188:189], v[34:35], v[38:39]
	v_rcp_f32_e32 v16, v16
	v_rcp_f32_e32 v17, v17
	v_pk_mul_f32 v[0:1], v[0:1], v[44:45]
	v_pk_fma_f32 v[44:45], v[178:179], v[20:21], v[24:25]
	v_pk_mul_f32 v[0:1], v[14:15], v[0:1]
	v_pk_mul_f32 v[2:3], v[2:3], v[16:17]
	v_cvt_pk_bf16_f32 v48, v0, v1
	v_pk_fma_f32 v[16:17], v[182:183], v[36:37], v[40:41]
	v_pk_mul_f32 v[2:3], v[4:5], v[2:3]
	v_mov_b32_dpp v0, v200 row_shl:15 row_mask:0xf bank_mask:0xf bound_ctrl:1
	v_mov_b32_dpp v1, v201 row_shl:15 row_mask:0xf bank_mask:0xf bound_ctrl:1
	v_mov_b32_dpp v4, v196 row_shl:15 row_mask:0xf bank_mask:0xf bound_ctrl:1
	v_mov_b32_dpp v5, v197 row_shl:15 row_mask:0xf bank_mask:0xf bound_ctrl:1
	v_cvt_pk_bf16_f32 v49, v2, v3
	v_mov_b32_dpp v0, v188 row_shr:1 row_mask:0xf bank_mask:0xf
	v_mov_b32_dpp v2, v200 row_shl:14 row_mask:0xf bank_mask:0xf bound_ctrl:1
	v_mov_b32_dpp v1, v189 row_shr:1 row_mask:0xf bank_mask:0xf
	v_mov_b32_dpp v3, v201 row_shl:14 row_mask:0xf bank_mask:0xf bound_ctrl:1
	v_mov_b32_dpp v4, v182 row_shr:1 row_mask:0xf bank_mask:0xf
	v_mov_b32_dpp v5, v183 row_shr:1 row_mask:0xf bank_mask:0xf
	v_mov_b32_dpp v2, v188 row_shr:2 row_mask:0xf bank_mask:0xf
	v_mov_b32_dpp v3, v189 row_shr:2 row_mask:0xf bank_mask:0xf
	v_mov_b32_dpp v14, v196 row_shl:14 row_mask:0xf bank_mask:0xf bound_ctrl:1
	v_mov_b32_dpp v15, v197 row_shl:14 row_mask:0xf bank_mask:0xf bound_ctrl:1
	v_pk_fma_f32 v[4:5], v[32:33], v[4:5], v[16:17]
	v_pk_fma_f32 v[0:1], v[30:31], v[0:1], v[42:43]
	v_mov_b32_dpp v16, v194 row_shl:15 row_mask:0xf bank_mask:0xf bound_ctrl:1
	v_mov_b32_dpp v17, v195 row_shl:15 row_mask:0xf bank_mask:0xf bound_ctrl:1
	v_mov_b32_dpp v14, v182 row_shr:2 row_mask:0xf bank_mask:0xf
	v_mov_b32_dpp v15, v183 row_shr:2 row_mask:0xf bank_mask:0xf
	v_pk_fma_f32 v[0:1], v[26:27], v[2:3], v[0:1]
	v_mov_b32_dpp v16, v178 row_shr:1 row_mask:0xf bank_mask:0xf
	v_mov_b32_dpp v42, v194 row_shl:14 row_mask:0xf bank_mask:0xf bound_ctrl:1
	v_mov_b32_dpp v17, v179 row_shr:1 row_mask:0xf bank_mask:0xf
	v_mov_b32_dpp v43, v195 row_shl:14 row_mask:0xf bank_mask:0xf bound_ctrl:1
	v_pk_fma_f32 v[2:3], v[28:29], v[14:15], v[4:5]
	v_mov_b32_dpp v42, v178 row_shr:2 row_mask:0xf bank_mask:0xf
	v_mov_b32_dpp v43, v179 row_shr:2 row_mask:0xf bank_mask:0xf
	v_pk_fma_f32 v[16:17], v[12:13], v[16:17], v[44:45]
	v_pk_mul_f32 v[44:45], v[0:1], v[0:1]
	v_pk_fma_f32 v[16:17], v[8:9], v[42:43], v[16:17]
	v_pk_mul_f32 v[42:43], v[2:3], v[2:3]
	v_pk_fma_f32 v[44:45], v[44:45], s[52:53], 1.0 op_sel_hi:[1,0,0]
	v_pk_fma_f32 v[42:43], v[42:43], s[52:53], 1.0 op_sel_hi:[1,0,0]
	v_pk_mul_f32 v[44:45], v[0:1], v[44:45]
	v_pk_mul_f32 v[42:43], v[2:3], v[42:43]
	v_pk_mul_f32 v[44:45], v[44:45], s[54:55] op_sel_hi:[1,0]
	v_pk_mul_f32 v[42:43], v[42:43], s[54:55] op_sel_hi:[1,0]
	v_exp_f32_e32 v44, v44
	v_exp_f32_e32 v45, v45
	v_exp_f32_e32 v42, v42
	v_exp_f32_e32 v43, v43
	v_mov_b32_dpp v4, v198 row_shl:15 row_mask:0xf bank_mask:0xf bound_ctrl:1
	v_pk_add_f32 v[44:45], v[44:45], 1.0 op_sel_hi:[1,0]
	v_mov_b32_dpp v5, v199 row_shl:15 row_mask:0xf bank_mask:0xf bound_ctrl:1
	v_rcp_f32_e32 v44, v44
	v_rcp_f32_e32 v45, v45
	v_pk_add_f32 v[42:43], v[42:43], 1.0 op_sel_hi:[1,0]
	v_mov_b32_dpp v4, v180 row_shr:1 row_mask:0xf bank_mask:0xf
	v_rcp_f32_e32 v42, v42
	v_rcp_f32_e32 v43, v43
	v_mov_b32_dpp v14, v198 row_shl:14 row_mask:0xf bank_mask:0xf bound_ctrl:1
	v_mov_b32_dpp v5, v181 row_shr:1 row_mask:0xf bank_mask:0xf
	v_mov_b32_dpp v15, v199 row_shl:14 row_mask:0xf bank_mask:0xf bound_ctrl:1
	v_pk_fma_f32 v[46:47], v[180:181], v[18:19], v[22:23]
	v_mov_b32_dpp v14, v180 row_shr:2 row_mask:0xf bank_mask:0xf
	v_mov_b32_dpp v15, v181 row_shr:2 row_mask:0xf bank_mask:0xf
	v_pk_fma_f32 v[4:5], v[10:11], v[4:5], v[46:47]
	v_pk_mul_f32 v[0:1], v[0:1], v[44:45]
	v_pk_fma_f32 v[4:5], v[6:7], v[14:15], v[4:5]
	v_pk_mul_f32 v[2:3], v[2:3], v[42:43]
	v_pk_mul_f32 v[0:1], v[4:5], v[0:1]
	v_pk_mul_f32 v[2:3], v[16:17], v[2:3]
	v_cvt_pk_bf16_f32 v46, v0, v1
	v_mov_b32_dpp v4, v182 row_shl:15 row_mask:0xf bank_mask:0xf bound_ctrl:1
	v_mov_b32_dpp v0, v188 row_shl:15 row_mask:0xf bank_mask:0xf bound_ctrl:1
	v_mov_b32_dpp v1, v189 row_shl:15 row_mask:0xf bank_mask:0xf bound_ctrl:1
	v_mov_b32_dpp v5, v183 row_shl:15 row_mask:0xf bank_mask:0xf bound_ctrl:1
	v_cvt_pk_bf16_f32 v47, v2, v3
	v_mov_b32_dpp v0, v192 row_shr:1 row_mask:0xf bank_mask:0xf
	v_mov_b32_dpp v2, v188 row_shl:14 row_mask:0xf bank_mask:0xf bound_ctrl:1
	v_mov_b32_dpp v1, v193 row_shr:1 row_mask:0xf bank_mask:0xf
	v_mov_b32_dpp v3, v189 row_shl:14 row_mask:0xf bank_mask:0xf bound_ctrl:1
	v_mov_b32_dpp v4, v190 row_shr:1 row_mask:0xf bank_mask:0xf
	v_mov_b32_dpp v5, v191 row_shr:1 row_mask:0xf bank_mask:0xf
	v_pk_fma_f32 v[16:17], v[190:191], v[36:37], v[40:41]
	v_pk_fma_f32 v[42:43], v[192:193], v[34:35], v[38:39]
	v_mov_b32_dpp v2, v192 row_shr:2 row_mask:0xf bank_mask:0xf
	v_mov_b32_dpp v3, v193 row_shr:2 row_mask:0xf bank_mask:0xf
	v_mov_b32_dpp v14, v182 row_shl:14 row_mask:0xf bank_mask:0xf bound_ctrl:1
	v_mov_b32_dpp v15, v183 row_shl:14 row_mask:0xf bank_mask:0xf bound_ctrl:1
	v_pk_fma_f32 v[4:5], v[32:33], v[4:5], v[16:17]
	v_pk_fma_f32 v[0:1], v[30:31], v[0:1], v[42:43]
	v_mov_b32_dpp v16, v178 row_shl:15 row_mask:0xf bank_mask:0xf bound_ctrl:1
	v_mov_b32_dpp v17, v179 row_shl:15 row_mask:0xf bank_mask:0xf bound_ctrl:1
	v_mov_b32_dpp v14, v190 row_shr:2 row_mask:0xf bank_mask:0xf
	v_mov_b32_dpp v15, v191 row_shr:2 row_mask:0xf bank_mask:0xf
	v_pk_fma_f32 v[0:1], v[26:27], v[2:3], v[0:1]
	v_mov_b32_dpp v16, v184 row_shr:1 row_mask:0xf bank_mask:0xf
	v_mov_b32_dpp v42, v178 row_shl:14 row_mask:0xf bank_mask:0xf bound_ctrl:1
	v_mov_b32_dpp v17, v185 row_shr:1 row_mask:0xf bank_mask:0xf
	v_mov_b32_dpp v43, v179 row_shl:14 row_mask:0xf bank_mask:0xf bound_ctrl:1
	v_pk_fma_f32 v[44:45], v[184:185], v[20:21], v[24:25]
	v_pk_fma_f32 v[2:3], v[28:29], v[14:15], v[4:5]
	v_mov_b32_dpp v42, v184 row_shr:2 row_mask:0xf bank_mask:0xf
	v_mov_b32_dpp v43, v185 row_shr:2 row_mask:0xf bank_mask:0xf
	v_pk_fma_f32 v[16:17], v[12:13], v[16:17], v[44:45]
	v_pk_mul_f32 v[44:45], v[0:1], v[0:1]
	v_pk_fma_f32 v[16:17], v[8:9], v[42:43], v[16:17]
	v_pk_mul_f32 v[42:43], v[2:3], v[2:3]
	v_pk_fma_f32 v[44:45], v[44:45], s[52:53], 1.0 op_sel_hi:[1,0,0]
	v_pk_fma_f32 v[42:43], v[42:43], s[52:53], 1.0 op_sel_hi:[1,0,0]
	v_pk_mul_f32 v[44:45], v[0:1], v[44:45]
	v_pk_mul_f32 v[42:43], v[2:3], v[42:43]
	v_pk_mul_f32 v[44:45], v[44:45], s[54:55] op_sel_hi:[1,0]
	v_pk_mul_f32 v[42:43], v[42:43], s[54:55] op_sel_hi:[1,0]
	v_exp_f32_e32 v44, v44
	v_exp_f32_e32 v45, v45
	v_exp_f32_e32 v42, v42
	v_exp_f32_e32 v43, v43
	v_mov_b32_dpp v4, v180 row_shl:15 row_mask:0xf bank_mask:0xf bound_ctrl:1
	v_pk_add_f32 v[44:45], v[44:45], 1.0 op_sel_hi:[1,0]
	v_mov_b32_dpp v5, v181 row_shl:15 row_mask:0xf bank_mask:0xf bound_ctrl:1
	v_rcp_f32_e32 v44, v44
	v_rcp_f32_e32 v45, v45
	v_pk_add_f32 v[42:43], v[42:43], 1.0 op_sel_hi:[1,0]
	v_mov_b32_dpp v4, v186 row_shr:1 row_mask:0xf bank_mask:0xf
	v_rcp_f32_e32 v42, v42
	v_rcp_f32_e32 v43, v43
	v_mov_b32_dpp v14, v180 row_shl:14 row_mask:0xf bank_mask:0xf bound_ctrl:1
	v_mov_b32_dpp v5, v187 row_shr:1 row_mask:0xf bank_mask:0xf
	v_mov_b32_dpp v15, v181 row_shl:14 row_mask:0xf bank_mask:0xf bound_ctrl:1
	v_mov_b32_dpp v14, v186 row_shr:2 row_mask:0xf bank_mask:0xf
	v_pk_fma_f32 v[4:5], v[10:11], v[4:5], v[52:53]
	v_mov_b32_dpp v15, v187 row_shr:2 row_mask:0xf bank_mask:0xf
	v_or_b32_e32 v216, 4, v58
	v_ashrrev_i32_e32 v217, 31, v216
	v_lshlrev_b64 v[216:217], 2, v[216:217]
	v_lshl_add_u64 v[218:219], s[46:47], 0, v[216:217]
	v_lshl_add_u64 v[216:217], s[44:45], 0, v[216:217]
	global_load_dwordx4 v[184:187], v[218:219], off
	global_load_dwordx4 v[188:191], v[118:119], off offset:16
	global_load_dwordx4 v[192:195], v[216:217], off
	global_load_dwordx4 v[196:199], v[116:117], off offset:16
	v_lshl_add_u64 v[216:217], v[58:59], 2, v[144:145]
	v_lshl_add_u64 v[218:219], s[46:47], 0, v[216:217]
	global_load_dwordx4 v[200:203], v[218:219], off
	v_lshl_add_u64 v[218:219], s[18:19], 0, v[216:217]
	global_load_dwordx4 v[204:207], v[218:219], off
	v_lshl_add_u64 v[218:219], s[44:45], 0, v[216:217]
	global_load_dwordx4 v[208:211], v[218:219], off
	v_lshl_add_u64 v[216:217], s[16:17], 0, v[216:217]
	global_load_dwordx4 v[212:215], v[216:217], off
	v_pk_fma_f32 v[4:5], v[6:7], v[14:15], v[4:5]
	v_pk_mul_f32 v[0:1], v[0:1], v[44:45]
	v_pk_mul_f32 v[2:3], v[2:3], v[42:43]
	v_pk_mul_f32 v[0:1], v[4:5], v[0:1]
	v_pk_mul_f32 v[2:3], v[16:17], v[2:3]
	v_cvt_pk_bf16_f32 v44, v0, v1
	v_mov_b32_dpp v4, v174 row_shl:14 row_mask:0xf bank_mask:0xf bound_ctrl:1
	v_mov_b32_dpp v0, v174 row_shl:15 row_mask:0xf bank_mask:0xf bound_ctrl:1
	v_mov_b32_dpp v1, v175 row_shl:15 row_mask:0xf bank_mask:0xf bound_ctrl:1
	v_mov_b32_dpp v5, v175 row_shl:14 row_mask:0xf bank_mask:0xf bound_ctrl:1
	v_mov_b32_dpp v42, v176 row_shl:15 row_mask:0xf bank_mask:0xf bound_ctrl:1
	v_mov_b32_dpp v43, v177 row_shl:15 row_mask:0xf bank_mask:0xf bound_ctrl:1
	v_cvt_pk_bf16_f32 v45, v2, v3
	v_mov_b32_e32 v2, v0
	v_mov_b32_e32 v14, v4
	v_mov_b32_e32 v3, v1
	v_mov_b32_e32 v15, v5
	v_mov_b32_e32 v16, v42
	v_mov_b32_dpp v52, v176 row_shl:14 row_mask:0xf bank_mask:0xf bound_ctrl:1
	v_mov_b32_e32 v17, v43
	v_mov_b32_dpp v53, v177 row_shl:14 row_mask:0xf bank_mask:0xf bound_ctrl:1
	v_mov_b32_dpp v2, v174 row_shr:1 row_mask:0xf bank_mask:0xf
	v_mov_b32_dpp v14, v174 row_shr:2 row_mask:0xf bank_mask:0xf
	v_mov_b32_dpp v3, v175 row_shr:1 row_mask:0xf bank_mask:0xf
	v_mov_b32_dpp v15, v175 row_shr:2 row_mask:0xf bank_mask:0xf
	v_mov_b32_dpp v16, v176 row_shr:1 row_mask:0xf bank_mask:0xf
	v_mov_b32_e32 v54, v52
	v_mov_b32_dpp v17, v177 row_shr:1 row_mask:0xf bank_mask:0xf
	v_mov_b32_e32 v55, v53
	v_pk_fma_f32 v[56:57], v[176:177], v[36:37], v[40:41]
	v_pk_fma_f32 v[174:175], v[174:175], v[34:35], v[38:39]
	v_mov_b32_dpp v54, v176 row_shr:2 row_mask:0xf bank_mask:0xf
	v_mov_b32_dpp v55, v177 row_shr:2 row_mask:0xf bank_mask:0xf
	v_pk_fma_f32 v[16:17], v[32:33], v[16:17], v[56:57]
	v_pk_fma_f32 v[2:3], v[30:31], v[2:3], v[174:175]
	v_mov_b32_dpp v56, v170 row_shl:14 row_mask:0xf bank_mask:0xf bound_ctrl:1
	v_pk_fma_f32 v[2:3], v[26:27], v[14:15], v[2:3]
	v_pk_fma_f32 v[14:15], v[28:29], v[54:55], v[16:17]
	v_mov_b32_dpp v54, v170 row_shl:15 row_mask:0xf bank_mask:0xf bound_ctrl:1
	v_mov_b32_dpp v55, v171 row_shl:15 row_mask:0xf bank_mask:0xf bound_ctrl:1
	v_mov_b32_dpp v57, v171 row_shl:14 row_mask:0xf bank_mask:0xf bound_ctrl:1
	v_mov_b32_dpp v176, v172 row_shl:15 row_mask:0xf bank_mask:0xf bound_ctrl:1
	v_mov_b32_dpp v180, v172 row_shl:14 row_mask:0xf bank_mask:0xf bound_ctrl:1
	v_mov_b32_dpp v177, v173 row_shl:15 row_mask:0xf bank_mask:0xf bound_ctrl:1
	v_mov_b32_dpp v181, v173 row_shl:14 row_mask:0xf bank_mask:0xf bound_ctrl:1
	v_mov_b32_e32 v16, v54
	v_mov_b32_e32 v174, v56
	v_mov_b32_e32 v17, v55
	v_mov_b32_e32 v175, v57
	v_mov_b32_e32 v178, v176
	v_mov_b32_e32 v182, v180
	v_mov_b32_e32 v179, v177
	v_mov_b32_e32 v183, v181
	v_mov_b32_dpp v16, v170 row_shr:1 row_mask:0xf bank_mask:0xf
	v_mov_b32_dpp v174, v170 row_shr:2 row_mask:0xf bank_mask:0xf
	v_mov_b32_dpp v17, v171 row_shr:1 row_mask:0xf bank_mask:0xf
	v_mov_b32_dpp v175, v171 row_shr:2 row_mask:0xf bank_mask:0xf
	v_mov_b32_dpp v178, v172 row_shr:1 row_mask:0xf bank_mask:0xf
	v_mov_b32_dpp v182, v172 row_shr:2 row_mask:0xf bank_mask:0xf
	v_mov_b32_dpp v179, v173 row_shr:1 row_mask:0xf bank_mask:0xf
	v_mov_b32_dpp v183, v173 row_shr:2 row_mask:0xf bank_mask:0xf
	v_pk_fma_f32 v[172:173], v[172:173], v[20:21], v[24:25]
	v_pk_fma_f32 v[170:171], v[170:171], v[18:19], v[22:23]
	v_mov_b32_dpp v0, v168 row_shr:1 row_mask:0xf bank_mask:0xf
	v_pk_fma_f32 v[16:17], v[10:11], v[16:17], v[170:171]
	v_pk_fma_f32 v[170:171], v[12:13], v[178:179], v[172:173]
	v_pk_mul_f32 v[172:173], v[14:15], v[14:15]
	v_pk_mul_f32 v[178:179], v[2:3], v[2:3]
	v_pk_fma_f32 v[172:173], v[172:173], s[52:53], 1.0 op_sel_hi:[1,0,0]
	v_pk_fma_f32 v[178:179], v[178:179], s[52:53], 1.0 op_sel_hi:[1,0,0]
	v_pk_mul_f32 v[172:173], v[14:15], v[172:173]
	v_pk_mul_f32 v[178:179], v[2:3], v[178:179]
	v_pk_mul_f32 v[172:173], v[172:173], s[54:55] op_sel_hi:[1,0]
	v_pk_mul_f32 v[178:179], v[178:179], s[54:55] op_sel_hi:[1,0]
	v_exp_f32_e32 v172, v172
	v_exp_f32_e32 v173, v173
	v_exp_f32_e32 v178, v178
	v_exp_f32_e32 v179, v179
	v_pk_fma_f32 v[170:171], v[8:9], v[182:183], v[170:171]
	v_pk_add_f32 v[172:173], v[172:173], 1.0 op_sel_hi:[1,0]
	v_pk_fma_f32 v[16:17], v[6:7], v[174:175], v[16:17]
	v_pk_add_f32 v[178:179], v[178:179], 1.0 op_sel_hi:[1,0]
	v_rcp_f32_e32 v172, v172
	v_rcp_f32_e32 v173, v173
	v_rcp_f32_e32 v178, v178
	v_rcp_f32_e32 v179, v179
	v_mov_b32_dpp v1, v169 row_shr:1 row_mask:0xf bank_mask:0xf
	v_pk_mul_f32 v[14:15], v[14:15], v[172:173]
	v_mov_b32_dpp v4, v168 row_shr:2 row_mask:0xf bank_mask:0xf
	v_pk_mul_f32 v[2:3], v[2:3], v[178:179]
	v_pk_mul_f32 v[14:15], v[170:171], v[14:15]
	v_pk_mul_f32 v[2:3], v[16:17], v[2:3]
	v_mov_b32_dpp v5, v169 row_shr:2 row_mask:0xf bank_mask:0xf
	v_cvt_pk_bf16_f32 v16, v2, v3
	v_cvt_pk_bf16_f32 v17, v14, v15
	v_pk_fma_f32 v[14:15], v[168:169], v[34:35], v[38:39]
	v_mov_b32_dpp v42, v164 row_shr:1 row_mask:0xf bank_mask:0xf
	v_mov_b32_dpp v43, v165 row_shr:1 row_mask:0xf bank_mask:0xf
	v_pk_fma_f32 v[2:3], v[164:165], v[36:37], v[40:41]
	v_pk_fma_f32 v[0:1], v[30:31], v[0:1], v[14:15]
	v_mov_b32_dpp v52, v164 row_shr:2 row_mask:0xf bank_mask:0xf
	v_mov_b32_dpp v53, v165 row_shr:2 row_mask:0xf bank_mask:0xf
	v_pk_fma_f32 v[2:3], v[32:33], v[42:43], v[2:3]
	v_pk_fma_f32 v[0:1], v[26:27], v[4:5], v[0:1]
	v_pk_fma_f32 v[2:3], v[28:29], v[52:53], v[2:3]
	v_pk_mul_f32 v[52:53], v[0:1], v[0:1]
	v_pk_mul_f32 v[42:43], v[2:3], v[2:3]
	v_pk_fma_f32 v[52:53], v[52:53], s[52:53], 1.0 op_sel_hi:[1,0,0]
	v_pk_fma_f32 v[42:43], v[42:43], s[52:53], 1.0 op_sel_hi:[1,0,0]
	v_pk_mul_f32 v[52:53], v[0:1], v[52:53]
	v_pk_mul_f32 v[42:43], v[2:3], v[42:43]
	v_pk_mul_f32 v[52:53], v[52:53], s[54:55] op_sel_hi:[1,0]
	v_pk_mul_f32 v[42:43], v[42:43], s[54:55] op_sel_hi:[1,0]
	v_exp_f32_e32 v52, v52
	v_exp_f32_e32 v53, v53
	v_exp_f32_e32 v42, v42
	v_exp_f32_e32 v43, v43
	v_mov_b32_dpp v54, v166 row_shr:1 row_mask:0xf bank_mask:0xf
	v_pk_add_f32 v[52:53], v[52:53], 1.0 op_sel_hi:[1,0]
	v_mov_b32_dpp v55, v167 row_shr:1 row_mask:0xf bank_mask:0xf
	v_rcp_f32_e32 v52, v52
	v_rcp_f32_e32 v53, v53
	v_pk_add_f32 v[42:43], v[42:43], 1.0 op_sel_hi:[1,0]
	v_pk_fma_f32 v[14:15], v[166:167], v[18:19], v[22:23]
	v_rcp_f32_e32 v42, v42
	v_rcp_f32_e32 v43, v43
	v_mov_b32_dpp v56, v166 row_shr:2 row_mask:0xf bank_mask:0xf
	v_mov_b32_dpp v57, v167 row_shr:2 row_mask:0xf bank_mask:0xf
	v_mov_b32_dpp v176, v162 row_shr:1 row_mask:0xf bank_mask:0xf
	v_mov_b32_dpp v177, v163 row_shr:1 row_mask:0xf bank_mask:0xf
	v_pk_fma_f32 v[4:5], v[162:163], v[20:21], v[24:25]
	v_pk_fma_f32 v[14:15], v[10:11], v[54:55], v[14:15]
	v_mov_b32_dpp v180, v162 row_shr:2 row_mask:0xf bank_mask:0xf
	v_mov_b32_dpp v181, v163 row_shr:2 row_mask:0xf bank_mask:0xf
	v_pk_fma_f32 v[4:5], v[12:13], v[176:177], v[4:5]
	v_pk_fma_f32 v[14:15], v[6:7], v[56:57], v[14:15]
	v_pk_mul_f32 v[0:1], v[0:1], v[52:53]
	v_pk_fma_f32 v[4:5], v[8:9], v[180:181], v[4:5]
	v_pk_mul_f32 v[0:1], v[14:15], v[0:1]
	v_pk_mul_f32 v[2:3], v[2:3], v[42:43]
	v_mov_b32_dpp v14, v164 row_shl:15 row_mask:0xf bank_mask:0xf bound_ctrl:1
	v_pk_mul_f32 v[2:3], v[4:5], v[2:3]
	v_cvt_pk_bf16_f32 v4, v0, v1
	v_mov_b32_dpp v0, v168 row_shl:15 row_mask:0xf bank_mask:0xf bound_ctrl:1
	v_mov_b32_dpp v1, v169 row_shl:15 row_mask:0xf bank_mask:0xf bound_ctrl:1
	v_mov_b32_dpp v15, v165 row_shl:15 row_mask:0xf bank_mask:0xf bound_ctrl:1
	v_cvt_pk_bf16_f32 v5, v2, v3
	v_mov_b32_dpp v0, v156 row_shr:1 row_mask:0xf bank_mask:0xf
	v_mov_b32_dpp v2, v168 row_shl:14 row_mask:0xf bank_mask:0xf bound_ctrl:1
	v_mov_b32_dpp v1, v157 row_shr:1 row_mask:0xf bank_mask:0xf
	v_mov_b32_dpp v3, v169 row_shl:14 row_mask:0xf bank_mask:0xf bound_ctrl:1
	v_mov_b32_dpp v14, v154 row_shr:1 row_mask:0xf bank_mask:0xf
	v_mov_b32_dpp v15, v155 row_shr:1 row_mask:0xf bank_mask:0xf
	v_pk_fma_f32 v[52:53], v[154:155], v[36:37], v[40:41]
	v_pk_fma_f32 v[54:55], v[156:157], v[34:35], v[38:39]
	v_mov_b32_dpp v2, v156 row_shr:2 row_mask:0xf bank_mask:0xf
	v_mov_b32_dpp v3, v157 row_shr:2 row_mask:0xf bank_mask:0xf
	v_mov_b32_dpp v42, v164 row_shl:14 row_mask:0xf bank_mask:0xf bound_ctrl:1
	v_mov_b32_dpp v43, v165 row_shl:14 row_mask:0xf bank_mask:0xf bound_ctrl:1
	v_pk_fma_f32 v[14:15], v[32:33], v[14:15], v[52:53]
	v_pk_fma_f32 v[0:1], v[30:31], v[0:1], v[54:55]
	v_mov_b32_dpp v52, v162 row_shl:15 row_mask:0xf bank_mask:0xf bound_ctrl:1
	v_mov_b32_dpp v53, v163 row_shl:15 row_mask:0xf bank_mask:0xf bound_ctrl:1
	v_mov_b32_dpp v42, v154 row_shr:2 row_mask:0xf bank_mask:0xf
	v_mov_b32_dpp v43, v155 row_shr:2 row_mask:0xf bank_mask:0xf
	v_pk_fma_f32 v[0:1], v[26:27], v[2:3], v[0:1]
	v_mov_b32_dpp v52, v146 row_shr:1 row_mask:0xf bank_mask:0xf
	v_mov_b32_dpp v54, v162 row_shl:14 row_mask:0xf bank_mask:0xf bound_ctrl:1
	v_mov_b32_dpp v53, v147 row_shr:1 row_mask:0xf bank_mask:0xf
	v_mov_b32_dpp v55, v163 row_shl:14 row_mask:0xf bank_mask:0xf bound_ctrl:1
	v_pk_fma_f32 v[56:57], v[146:147], v[20:21], v[24:25]
	v_pk_fma_f32 v[2:3], v[28:29], v[42:43], v[14:15]
	v_mov_b32_dpp v54, v146 row_shr:2 row_mask:0xf bank_mask:0xf
	v_mov_b32_dpp v55, v147 row_shr:2 row_mask:0xf bank_mask:0xf
	v_pk_fma_f32 v[52:53], v[12:13], v[52:53], v[56:57]
	v_pk_mul_f32 v[56:57], v[0:1], v[0:1]
	v_pk_fma_f32 v[52:53], v[8:9], v[54:55], v[52:53]
	v_pk_mul_f32 v[54:55], v[2:3], v[2:3]
	v_pk_fma_f32 v[56:57], v[56:57], s[52:53], 1.0 op_sel_hi:[1,0,0]
	v_pk_fma_f32 v[54:55], v[54:55], s[52:53], 1.0 op_sel_hi:[1,0,0]
	v_pk_mul_f32 v[56:57], v[0:1], v[56:57]
	v_pk_mul_f32 v[54:55], v[2:3], v[54:55]
	v_pk_mul_f32 v[56:57], v[56:57], s[54:55] op_sel_hi:[1,0]
	v_pk_mul_f32 v[54:55], v[54:55], s[54:55] op_sel_hi:[1,0]
	v_exp_f32_e32 v56, v56
	v_exp_f32_e32 v57, v57
	v_exp_f32_e32 v54, v54
	v_exp_f32_e32 v55, v55
	v_mov_b32_dpp v14, v166 row_shl:15 row_mask:0xf bank_mask:0xf bound_ctrl:1
	v_pk_add_f32 v[56:57], v[56:57], 1.0 op_sel_hi:[1,0]
	v_mov_b32_dpp v15, v167 row_shl:15 row_mask:0xf bank_mask:0xf bound_ctrl:1
	v_rcp_f32_e32 v56, v56
	v_rcp_f32_e32 v57, v57
	v_pk_add_f32 v[54:55], v[54:55], 1.0 op_sel_hi:[1,0]
	v_mov_b32_dpp v14, v148 row_shr:1 row_mask:0xf bank_mask:0xf
	v_rcp_f32_e32 v54, v54
	v_rcp_f32_e32 v55, v55
	v_mov_b32_dpp v42, v166 row_shl:14 row_mask:0xf bank_mask:0xf bound_ctrl:1
	v_mov_b32_dpp v15, v149 row_shr:1 row_mask:0xf bank_mask:0xf
	v_mov_b32_dpp v43, v167 row_shl:14 row_mask:0xf bank_mask:0xf bound_ctrl:1
	v_pk_fma_f32 v[162:163], v[148:149], v[18:19], v[22:23]
	v_mov_b32_dpp v42, v148 row_shr:2 row_mask:0xf bank_mask:0xf
	v_mov_b32_dpp v43, v149 row_shr:2 row_mask:0xf bank_mask:0xf
	v_pk_fma_f32 v[14:15], v[10:11], v[14:15], v[162:163]
	v_pk_mul_f32 v[0:1], v[0:1], v[56:57]
	v_pk_fma_f32 v[14:15], v[6:7], v[42:43], v[14:15]
	v_pk_mul_f32 v[2:3], v[2:3], v[54:55]
	v_pk_mul_f32 v[0:1], v[14:15], v[0:1]
	v_pk_mul_f32 v[14:15], v[52:53], v[2:3]
	v_cvt_pk_bf16_f32 v2, v0, v1
	v_mov_b32_dpp v42, v154 row_shl:15 row_mask:0xf bank_mask:0xf bound_ctrl:1
	v_mov_b32_dpp v0, v156 row_shl:15 row_mask:0xf bank_mask:0xf bound_ctrl:1
	v_mov_b32_dpp v1, v157 row_shl:15 row_mask:0xf bank_mask:0xf bound_ctrl:1
	v_cvt_pk_bf16_f32 v3, v14, v15
	v_mov_b32_dpp v14, v156 row_shl:14 row_mask:0xf bank_mask:0xf bound_ctrl:1
	v_mov_b32_dpp v0, v160 row_shr:1 row_mask:0xf bank_mask:0xf
	v_mov_b32_dpp v1, v161 row_shr:1 row_mask:0xf bank_mask:0xf
	v_mov_b32_dpp v15, v157 row_shl:14 row_mask:0xf bank_mask:0xf bound_ctrl:1
	v_mov_b32_dpp v43, v155 row_shl:15 row_mask:0xf bank_mask:0xf bound_ctrl:1
	v_pk_fma_f32 v[34:35], v[160:161], v[34:35], v[38:39]
	v_mov_b32_dpp v14, v160 row_shr:2 row_mask:0xf bank_mask:0xf
	v_mov_b32_dpp v15, v161 row_shr:2 row_mask:0xf bank_mask:0xf
	v_mov_b32_dpp v42, v158 row_shr:1 row_mask:0xf bank_mask:0xf
	v_mov_b32_dpp v52, v154 row_shl:14 row_mask:0xf bank_mask:0xf bound_ctrl:1
	v_mov_b32_dpp v43, v159 row_shr:1 row_mask:0xf bank_mask:0xf
	v_mov_b32_dpp v53, v155 row_shl:14 row_mask:0xf bank_mask:0xf bound_ctrl:1
	v_pk_fma_f32 v[36:37], v[158:159], v[36:37], v[40:41]
	v_pk_fma_f32 v[0:1], v[30:31], v[0:1], v[34:35]
	v_mov_b32_dpp v52, v158 row_shr:2 row_mask:0xf bank_mask:0xf
	v_mov_b32_dpp v53, v159 row_shr:2 row_mask:0xf bank_mask:0xf
	v_pk_fma_f32 v[32:33], v[32:33], v[42:43], v[36:37]
	v_pk_fma_f32 v[0:1], v[26:27], v[14:15], v[0:1]
	v_mov_b32_dpp v26, v148 row_shl:15 row_mask:0xf bank_mask:0xf bound_ctrl:1
	v_mov_b32_dpp v27, v149 row_shl:15 row_mask:0xf bank_mask:0xf bound_ctrl:1
	v_mov_b32_dpp v30, v146 row_shl:15 row_mask:0xf bank_mask:0xf bound_ctrl:1
	v_mov_b32_dpp v31, v147 row_shl:15 row_mask:0xf bank_mask:0xf bound_ctrl:1
	v_pk_fma_f32 v[14:15], v[28:29], v[52:53], v[32:33]
	v_mov_b32_dpp v26, v152 row_shr:1 row_mask:0xf bank_mask:0xf
	v_mov_b32_dpp v27, v153 row_shr:1 row_mask:0xf bank_mask:0xf
	v_mov_b32_dpp v30, v150 row_shr:1 row_mask:0xf bank_mask:0xf
	v_mov_b32_dpp v32, v146 row_shl:14 row_mask:0xf bank_mask:0xf bound_ctrl:1
	v_mov_b32_dpp v31, v151 row_shr:1 row_mask:0xf bank_mask:0xf
	v_mov_b32_dpp v33, v147 row_shl:14 row_mask:0xf bank_mask:0xf bound_ctrl:1
	v_pk_fma_f32 v[20:21], v[150:151], v[20:21], v[24:25]
	v_pk_fma_f32 v[18:19], v[152:153], v[18:19], v[22:23]
	v_mov_b32_dpp v32, v150 row_shr:2 row_mask:0xf bank_mask:0xf
	v_mov_b32_dpp v33, v151 row_shr:2 row_mask:0xf bank_mask:0xf
	v_pk_fma_f32 v[10:11], v[10:11], v[26:27], v[18:19]
	v_pk_fma_f32 v[12:13], v[12:13], v[30:31], v[20:21]
	v_pk_mul_f32 v[18:19], v[0:1], v[0:1]
	v_pk_fma_f32 v[8:9], v[8:9], v[32:33], v[12:13]
	v_pk_mul_f32 v[12:13], v[14:15], v[14:15]
	v_pk_fma_f32 v[18:19], v[18:19], s[52:53], 1.0 op_sel_hi:[1,0,0]
	v_pk_fma_f32 v[12:13], v[12:13], s[52:53], 1.0 op_sel_hi:[1,0,0]
	v_pk_mul_f32 v[18:19], v[0:1], v[18:19]
	v_pk_mul_f32 v[12:13], v[14:15], v[12:13]
	v_pk_mul_f32 v[18:19], v[18:19], s[54:55] op_sel_hi:[1,0]
	v_pk_mul_f32 v[12:13], v[12:13], s[54:55] op_sel_hi:[1,0]
	v_exp_f32_e32 v18, v18
	v_exp_f32_e32 v19, v19
	v_exp_f32_e32 v12, v12
	v_exp_f32_e32 v13, v13
	v_mov_b32_dpp v28, v148 row_shl:14 row_mask:0xf bank_mask:0xf bound_ctrl:1
	v_pk_add_f32 v[18:19], v[18:19], 1.0 op_sel_hi:[1,0]
	v_mov_b32_dpp v29, v149 row_shl:14 row_mask:0xf bank_mask:0xf bound_ctrl:1
	v_rcp_f32_e32 v18, v18
	v_rcp_f32_e32 v19, v19
	v_pk_add_f32 v[12:13], v[12:13], 1.0 op_sel_hi:[1,0]
	v_mov_b32_dpp v28, v152 row_shr:2 row_mask:0xf bank_mask:0xf
	v_rcp_f32_e32 v12, v12
	v_rcp_f32_e32 v13, v13
	v_mov_b32_dpp v29, v153 row_shr:2 row_mask:0xf bank_mask:0xf
	v_pk_fma_f32 v[6:7], v[6:7], v[28:29], v[10:11]
	v_pk_mul_f32 v[0:1], v[0:1], v[18:19]
	v_mov_b32_dpp v52, v124 row_shl:15 row_mask:0xf bank_mask:0xf bound_ctrl:1
	v_pk_mul_f32 v[0:1], v[6:7], v[0:1]
	v_pk_mul_f32 v[6:7], v[14:15], v[12:13]
	v_cvt_pk_bf16_f32 v0, v0, v1
	v_mov_b32_dpp v53, v125 row_shl:15 row_mask:0xf bank_mask:0xf bound_ctrl:1
	v_pk_mul_f32 v[6:7], v[8:9], v[6:7]
	v_mov_b32_dpp v52, v124 row_shr:1 row_mask:0xf bank_mask:0xf
	v_cvt_pk_bf16_f32 v1, v6, v7
	v_mov_b32_dpp v53, v125 row_shr:1 row_mask:0xf bank_mask:0xf
	v_mov_b32_dpp v6, v126 row_shl:15 row_mask:0xf bank_mask:0xf bound_ctrl:1
	v_mov_b32_dpp v7, v127 row_shl:15 row_mask:0xf bank_mask:0xf bound_ctrl:1
	v_mov_b32_dpp v18, v126 row_shl:14 row_mask:0xf bank_mask:0xf bound_ctrl:1
	v_mov_b32_dpp v6, v126 row_shr:1 row_mask:0xf bank_mask:0xf
	v_mov_b32_dpp v7, v127 row_shr:1 row_mask:0xf bank_mask:0xf
	v_mov_b32_dpp v19, v127 row_shl:14 row_mask:0xf bank_mask:0xf bound_ctrl:1
	v_mov_b32_dpp v54, v124 row_shl:14 row_mask:0xf bank_mask:0xf bound_ctrl:1
	v_mov_b32_dpp v55, v125 row_shl:14 row_mask:0xf bank_mask:0xf bound_ctrl:1
	v_mov_b32_dpp v18, v126 row_shr:2 row_mask:0xf bank_mask:0xf
	v_mov_b32_dpp v19, v127 row_shr:2 row_mask:0xf bank_mask:0xf
	v_mov_b32_dpp v54, v124 row_shr:2 row_mask:0xf bank_mask:0xf
	v_mov_b32_dpp v55, v125 row_shr:2 row_mask:0xf bank_mask:0xf
	s_waitcnt vmcnt(6)
	v_pk_fma_f32 v[56:57], v[124:125], v[186:187], v[190:191]
	v_pk_fma_f32 v[116:117], v[126:127], v[184:185], v[188:189]
	s_waitcnt vmcnt(5)
	v_pk_fma_f32 v[52:53], v[194:195], v[52:53], v[56:57]
	v_mov_b32_dpp v56, v120 row_shl:15 row_mask:0xf bank_mask:0xf bound_ctrl:1
	v_mov_b32_dpp v57, v121 row_shl:15 row_mask:0xf bank_mask:0xf bound_ctrl:1
	v_pk_fma_f32 v[6:7], v[192:193], v[6:7], v[116:117]
	v_mov_b32_dpp v56, v120 row_shr:1 row_mask:0xf bank_mask:0xf
	v_mov_b32_dpp v116, v120 row_shl:14 row_mask:0xf bank_mask:0xf bound_ctrl:1
	v_mov_b32_dpp v57, v121 row_shr:1 row_mask:0xf bank_mask:0xf
	v_mov_b32_dpp v117, v121 row_shl:14 row_mask:0xf bank_mask:0xf bound_ctrl:1
	s_waitcnt vmcnt(2)
	v_pk_fma_f32 v[118:119], v[120:121], v[202:203], v[206:207]
	v_pk_fma_f32 v[6:7], v[196:197], v[18:19], v[6:7]
	v_pk_fma_f32 v[18:19], v[198:199], v[54:55], v[52:53]
	v_mov_b32_dpp v116, v120 row_shr:2 row_mask:0xf bank_mask:0xf
	v_mov_b32_dpp v117, v121 row_shr:2 row_mask:0xf bank_mask:0xf
	s_waitcnt vmcnt(1)
	v_pk_fma_f32 v[56:57], v[210:211], v[56:57], v[118:119]
	v_pk_mul_f32 v[118:119], v[6:7], v[6:7]
	s_waitcnt vmcnt(0)
	v_pk_fma_f32 v[56:57], v[214:215], v[116:117], v[56:57]
	v_pk_mul_f32 v[116:117], v[18:19], v[18:19]
	v_pk_fma_f32 v[118:119], v[118:119], s[52:53], 1.0 op_sel_hi:[1,0,0]
	v_pk_fma_f32 v[116:117], v[116:117], s[52:53], 1.0 op_sel_hi:[1,0,0]
	v_pk_mul_f32 v[118:119], v[6:7], v[118:119]
	v_pk_mul_f32 v[116:117], v[18:19], v[116:117]
	v_pk_mul_f32 v[118:119], v[118:119], s[54:55] op_sel_hi:[1,0]
	v_pk_mul_f32 v[116:117], v[116:117], s[54:55] op_sel_hi:[1,0]
	v_exp_f32_e32 v118, v118
	v_exp_f32_e32 v119, v119
	v_exp_f32_e32 v116, v116
	v_exp_f32_e32 v117, v117
	v_mov_b32_dpp v52, v122 row_shl:15 row_mask:0xf bank_mask:0xf bound_ctrl:1
	v_pk_add_f32 v[118:119], v[118:119], 1.0 op_sel_hi:[1,0]
	v_mov_b32_dpp v53, v123 row_shl:15 row_mask:0xf bank_mask:0xf bound_ctrl:1
	v_pk_add_f32 v[116:117], v[116:117], 1.0 op_sel_hi:[1,0]
	v_rcp_f32_e32 v118, v118
	v_rcp_f32_e32 v119, v119
	v_rcp_f32_e32 v116, v116
	v_rcp_f32_e32 v117, v117
	v_mov_b32_dpp v52, v122 row_shr:1 row_mask:0xf bank_mask:0xf
	v_mov_b32_dpp v54, v122 row_shl:14 row_mask:0xf bank_mask:0xf bound_ctrl:1
	v_mov_b32_dpp v53, v123 row_shr:1 row_mask:0xf bank_mask:0xf
	v_mov_b32_dpp v55, v123 row_shl:14 row_mask:0xf bank_mask:0xf bound_ctrl:1
	v_pk_fma_f32 v[146:147], v[122:123], v[200:201], v[204:205]
	v_mov_b32_dpp v54, v122 row_shr:2 row_mask:0xf bank_mask:0xf
	v_mov_b32_dpp v55, v123 row_shr:2 row_mask:0xf bank_mask:0xf
	v_pk_fma_f32 v[52:53], v[208:209], v[52:53], v[146:147]
	v_pk_mul_f32 v[6:7], v[6:7], v[118:119]
	v_pk_fma_f32 v[52:53], v[212:213], v[54:55], v[52:53]
	v_pk_mul_f32 v[18:19], v[18:19], v[116:117]
	v_pk_mul_f32 v[6:7], v[52:53], v[6:7]
	v_pk_mul_f32 v[18:19], v[56:57], v[18:19]
	v_cvt_pk_bf16_f32 v52, v6, v7
	s_nop 0
	v_cvt_pk_bf16_f32 v53, v18, v19
	s_and_saveexec_b64 s[62:63], s[22:23]
	s_cbranch_execz .LBB0_871
	v_add_u32_e32 v18, -2, v232
	v_mov_b64_e32 v[6:7], s[42:43]
	v_mad_i64_i32 v[6:7], s[22:23], v18, s94, v[6:7]
	v_lshl_add_u64 v[6:7], v[58:59], 1, v[6:7]
	global_store_dwordx4 v[6:7], v[50:53], off
.LBB0_871:
	s_or_b64 exec, exec, s[62:63]
	s_nop 0
	v_mov_b32_dpp v52, v124 row_shl:15 row_mask:0xf bank_mask:0xf bound_ctrl:1
	v_mov_b32_dpp v53, v125 row_shl:15 row_mask:0xf bank_mask:0xf bound_ctrl:1
	v_mov_b32_dpp v18, v126 row_shl:15 row_mask:0xf bank_mask:0xf bound_ctrl:1
	v_mov_b32_dpp v19, v127 row_shl:15 row_mask:0xf bank_mask:0xf bound_ctrl:1
	v_mov_b32_dpp v52, v112 row_shr:1 row_mask:0xf bank_mask:0xf
	v_mov_b32_dpp v53, v113 row_shr:1 row_mask:0xf bank_mask:0xf
	v_pk_fma_f32 v[56:57], v[112:113], v[186:187], v[190:191]
	v_mov_b32_dpp v18, v114 row_shr:1 row_mask:0xf bank_mask:0xf
	v_mov_b32_dpp v50, v126 row_shl:14 row_mask:0xf bank_mask:0xf bound_ctrl:1
	v_mov_b32_dpp v19, v115 row_shr:1 row_mask:0xf bank_mask:0xf
	v_mov_b32_dpp v51, v127 row_shl:14 row_mask:0xf bank_mask:0xf bound_ctrl:1
	v_mov_b32_dpp v54, v124 row_shl:14 row_mask:0xf bank_mask:0xf bound_ctrl:1
	v_mov_b32_dpp v55, v125 row_shl:14 row_mask:0xf bank_mask:0xf bound_ctrl:1
	v_pk_fma_f32 v[116:117], v[114:115], v[184:185], v[188:189]
	v_pk_fma_f32 v[52:53], v[194:195], v[52:53], v[56:57]
	v_mov_b32_dpp v56, v120 row_shl:15 row_mask:0xf bank_mask:0xf bound_ctrl:1
	v_mov_b32_dpp v57, v121 row_shl:15 row_mask:0xf bank_mask:0xf bound_ctrl:1
	v_mov_b32_dpp v50, v114 row_shr:2 row_mask:0xf bank_mask:0xf
	v_mov_b32_dpp v51, v115 row_shr:2 row_mask:0xf bank_mask:0xf
	v_mov_b32_dpp v54, v112 row_shr:2 row_mask:0xf bank_mask:0xf
	v_mov_b32_dpp v55, v113 row_shr:2 row_mask:0xf bank_mask:0xf
	v_pk_fma_f32 v[18:19], v[192:193], v[18:19], v[116:117]
	v_mov_b32_dpp v56, v108 row_shr:1 row_mask:0xf bank_mask:0xf
	v_mov_b32_dpp v116, v120 row_shl:14 row_mask:0xf bank_mask:0xf bound_ctrl:1
	v_mov_b32_dpp v57, v109 row_shr:1 row_mask:0xf bank_mask:0xf
	v_mov_b32_dpp v117, v121 row_shl:14 row_mask:0xf bank_mask:0xf bound_ctrl:1
	v_pk_fma_f32 v[118:119], v[108:109], v[202:203], v[206:207]
	v_pk_fma_f32 v[18:19], v[196:197], v[50:51], v[18:19]
	v_pk_fma_f32 v[50:51], v[198:199], v[54:55], v[52:53]
	v_mov_b32_dpp v116, v108 row_shr:2 row_mask:0xf bank_mask:0xf
	v_mov_b32_dpp v117, v109 row_shr:2 row_mask:0xf bank_mask:0xf
	v_pk_fma_f32 v[56:57], v[210:211], v[56:57], v[118:119]
	v_pk_mul_f32 v[118:119], v[18:19], v[18:19]
	v_pk_fma_f32 v[56:57], v[214:215], v[116:117], v[56:57]
	v_pk_mul_f32 v[116:117], v[50:51], v[50:51]
	v_pk_fma_f32 v[118:119], v[118:119], s[52:53], 1.0 op_sel_hi:[1,0,0]
	v_pk_fma_f32 v[116:117], v[116:117], s[52:53], 1.0 op_sel_hi:[1,0,0]
	v_pk_mul_f32 v[118:119], v[18:19], v[118:119]
	v_pk_mul_f32 v[116:117], v[50:51], v[116:117]
	v_pk_mul_f32 v[118:119], v[118:119], s[54:55] op_sel_hi:[1,0]
	v_pk_mul_f32 v[116:117], v[116:117], s[54:55] op_sel_hi:[1,0]
	v_exp_f32_e32 v118, v118
	v_exp_f32_e32 v119, v119
	v_exp_f32_e32 v116, v116
	v_exp_f32_e32 v117, v117
	v_mov_b32_dpp v52, v122 row_shl:15 row_mask:0xf bank_mask:0xf bound_ctrl:1
	v_pk_add_f32 v[118:119], v[118:119], 1.0 op_sel_hi:[1,0]
	v_mov_b32_dpp v53, v123 row_shl:15 row_mask:0xf bank_mask:0xf bound_ctrl:1
	v_pk_add_f32 v[116:117], v[116:117], 1.0 op_sel_hi:[1,0]
	v_rcp_f32_e32 v118, v118
	v_rcp_f32_e32 v119, v119
	v_rcp_f32_e32 v116, v116
	v_rcp_f32_e32 v117, v117
	s_add_i32 s26, s57, 16
	v_mov_b32_dpp v52, v110 row_shr:1 row_mask:0xf bank_mask:0xf
	v_mov_b32_dpp v54, v122 row_shl:14 row_mask:0xf bank_mask:0xf bound_ctrl:1
	v_mov_b32_dpp v53, v111 row_shr:1 row_mask:0xf bank_mask:0xf
	v_mov_b32_dpp v55, v123 row_shl:14 row_mask:0xf bank_mask:0xf bound_ctrl:1
	v_pk_fma_f32 v[120:121], v[110:111], v[200:201], v[204:205]
	v_add_u32_e32 v6, s26, v231
	v_mov_b32_dpp v54, v110 row_shr:2 row_mask:0xf bank_mask:0xf
	v_mov_b32_dpp v55, v111 row_shr:2 row_mask:0xf bank_mask:0xf
	v_pk_fma_f32 v[52:53], v[208:209], v[52:53], v[120:121]
	v_pk_mul_f32 v[18:19], v[18:19], v[118:119]
	v_pk_fma_f32 v[52:53], v[212:213], v[54:55], v[52:53]
	v_pk_mul_f32 v[50:51], v[50:51], v[116:117]
	v_cmp_gt_i32_e32 vcc, s93, v6
	v_pk_mul_f32 v[18:19], v[52:53], v[18:19]
	v_pk_mul_f32 v[52:53], v[56:57], v[50:51]
	v_cvt_pk_bf16_f32 v50, v18, v19
	s_nop 0
	v_cvt_pk_bf16_f32 v51, v52, v53
	s_and_saveexec_b64 s[62:63], vcc
	s_cbranch_execz .LBB0_873
	v_add_u32_e32 v18, -2, v6
	v_mov_b64_e32 v[6:7], s[42:43]
	v_mad_i64_i32 v[6:7], s[22:23], v18, s94, v[6:7]
	v_lshl_add_u64 v[6:7], v[58:59], 1, v[6:7]
	global_store_dwordx4 v[6:7], v[48:51], off
.LBB0_873:
	s_or_b64 exec, exec, s[62:63]
	s_nop 0
	v_mov_b32_dpp v50, v112 row_shl:15 row_mask:0xf bank_mask:0xf bound_ctrl:1
	v_mov_b32_dpp v51, v113 row_shl:15 row_mask:0xf bank_mask:0xf bound_ctrl:1
	v_mov_b32_dpp v18, v114 row_shl:15 row_mask:0xf bank_mask:0xf bound_ctrl:1
	v_mov_b32_dpp v19, v115 row_shl:15 row_mask:0xf bank_mask:0xf bound_ctrl:1
	v_mov_b32_dpp v50, v98 row_shr:1 row_mask:0xf bank_mask:0xf
	v_mov_b32_dpp v51, v99 row_shr:1 row_mask:0xf bank_mask:0xf
	v_pk_fma_f32 v[54:55], v[98:99], v[186:187], v[190:191]
	v_mov_b32_dpp v18, v102 row_shr:1 row_mask:0xf bank_mask:0xf
	v_mov_b32_dpp v48, v114 row_shl:14 row_mask:0xf bank_mask:0xf bound_ctrl:1
	v_mov_b32_dpp v19, v103 row_shr:1 row_mask:0xf bank_mask:0xf
	v_mov_b32_dpp v49, v115 row_shl:14 row_mask:0xf bank_mask:0xf bound_ctrl:1
	v_mov_b32_dpp v52, v112 row_shl:14 row_mask:0xf bank_mask:0xf bound_ctrl:1
	v_mov_b32_dpp v53, v113 row_shl:14 row_mask:0xf bank_mask:0xf bound_ctrl:1
	v_pk_fma_f32 v[56:57], v[102:103], v[184:185], v[188:189]
	v_pk_fma_f32 v[50:51], v[194:195], v[50:51], v[54:55]
	v_mov_b32_dpp v54, v108 row_shl:15 row_mask:0xf bank_mask:0xf bound_ctrl:1
	v_mov_b32_dpp v55, v109 row_shl:15 row_mask:0xf bank_mask:0xf bound_ctrl:1
	v_mov_b32_dpp v48, v102 row_shr:2 row_mask:0xf bank_mask:0xf
	v_mov_b32_dpp v49, v103 row_shr:2 row_mask:0xf bank_mask:0xf
	v_mov_b32_dpp v52, v98 row_shr:2 row_mask:0xf bank_mask:0xf
	v_mov_b32_dpp v53, v99 row_shr:2 row_mask:0xf bank_mask:0xf
	v_pk_fma_f32 v[18:19], v[192:193], v[18:19], v[56:57]
	v_mov_b32_dpp v54, v92 row_shr:1 row_mask:0xf bank_mask:0xf
	v_mov_b32_dpp v56, v108 row_shl:14 row_mask:0xf bank_mask:0xf bound_ctrl:1
	v_mov_b32_dpp v55, v93 row_shr:1 row_mask:0xf bank_mask:0xf
	v_mov_b32_dpp v57, v109 row_shl:14 row_mask:0xf bank_mask:0xf bound_ctrl:1
	v_pk_fma_f32 v[108:109], v[92:93], v[202:203], v[206:207]
	v_pk_fma_f32 v[18:19], v[196:197], v[48:49], v[18:19]
	v_pk_fma_f32 v[48:49], v[198:199], v[52:53], v[50:51]
	v_mov_b32_dpp v56, v92 row_shr:2 row_mask:0xf bank_mask:0xf
	v_mov_b32_dpp v57, v93 row_shr:2 row_mask:0xf bank_mask:0xf
	v_pk_fma_f32 v[54:55], v[210:211], v[54:55], v[108:109]
	v_pk_mul_f32 v[108:109], v[18:19], v[18:19]
	v_pk_fma_f32 v[54:55], v[214:215], v[56:57], v[54:55]
	v_pk_mul_f32 v[56:57], v[48:49], v[48:49]
	v_pk_fma_f32 v[108:109], v[108:109], s[52:53], 1.0 op_sel_hi:[1,0,0]
	v_pk_fma_f32 v[56:57], v[56:57], s[52:53], 1.0 op_sel_hi:[1,0,0]
	v_pk_mul_f32 v[108:109], v[18:19], v[108:109]
	v_pk_mul_f32 v[56:57], v[48:49], v[56:57]
	v_pk_mul_f32 v[108:109], v[108:109], s[54:55] op_sel_hi:[1,0]
	v_pk_mul_f32 v[56:57], v[56:57], s[54:55] op_sel_hi:[1,0]
	v_exp_f32_e32 v108, v108
	v_exp_f32_e32 v109, v109
	v_exp_f32_e32 v56, v56
	v_exp_f32_e32 v57, v57
	v_mov_b32_dpp v50, v110 row_shl:15 row_mask:0xf bank_mask:0xf bound_ctrl:1
	v_pk_add_f32 v[108:109], v[108:109], 1.0 op_sel_hi:[1,0]
	v_mov_b32_dpp v51, v111 row_shl:15 row_mask:0xf bank_mask:0xf bound_ctrl:1
	v_pk_add_f32 v[56:57], v[56:57], 1.0 op_sel_hi:[1,0]
	v_rcp_f32_e32 v108, v108
	v_rcp_f32_e32 v109, v109
	v_rcp_f32_e32 v56, v56
	v_rcp_f32_e32 v57, v57
	s_add_i32 s27, s57, 32
	v_mov_b32_dpp v50, v94 row_shr:1 row_mask:0xf bank_mask:0xf
	v_mov_b32_dpp v52, v110 row_shl:14 row_mask:0xf bank_mask:0xf bound_ctrl:1
	v_mov_b32_dpp v51, v95 row_shr:1 row_mask:0xf bank_mask:0xf
	v_mov_b32_dpp v53, v111 row_shl:14 row_mask:0xf bank_mask:0xf bound_ctrl:1
	v_pk_fma_f32 v[110:111], v[94:95], v[200:201], v[204:205]
	v_add_u32_e32 v6, s27, v231
	v_mov_b32_dpp v52, v94 row_shr:2 row_mask:0xf bank_mask:0xf
	v_mov_b32_dpp v53, v95 row_shr:2 row_mask:0xf bank_mask:0xf
	v_pk_fma_f32 v[50:51], v[208:209], v[50:51], v[110:111]
	v_pk_mul_f32 v[18:19], v[18:19], v[108:109]
	v_pk_fma_f32 v[50:51], v[212:213], v[52:53], v[50:51]
	v_pk_mul_f32 v[48:49], v[48:49], v[56:57]
	v_cmp_gt_i32_e32 vcc, s93, v6
	v_pk_mul_f32 v[18:19], v[50:51], v[18:19]
	v_pk_mul_f32 v[50:51], v[54:55], v[48:49]
	v_cvt_pk_bf16_f32 v48, v18, v19
	s_nop 0
	v_cvt_pk_bf16_f32 v49, v50, v51
	s_and_saveexec_b64 s[62:63], vcc
	s_cbranch_execz .LBB0_875
	v_add_u32_e32 v18, -2, v6
	v_mov_b64_e32 v[6:7], s[42:43]
	v_mad_i64_i32 v[6:7], s[22:23], v18, s94, v[6:7]
	v_lshl_add_u64 v[6:7], v[58:59], 1, v[6:7]
	global_store_dwordx4 v[6:7], v[46:49], off
.LBB0_875:
	s_or_b64 exec, exec, s[62:63]
	s_nop 0
	v_mov_b32_dpp v48, v98 row_shl:15 row_mask:0xf bank_mask:0xf bound_ctrl:1
	v_mov_b32_dpp v49, v99 row_shl:15 row_mask:0xf bank_mask:0xf bound_ctrl:1
	v_mov_b32_dpp v18, v102 row_shl:15 row_mask:0xf bank_mask:0xf bound_ctrl:1
	v_mov_b32_dpp v19, v103 row_shl:15 row_mask:0xf bank_mask:0xf bound_ctrl:1
	v_mov_b32_dpp v48, v104 row_shr:1 row_mask:0xf bank_mask:0xf
	v_mov_b32_dpp v49, v105 row_shr:1 row_mask:0xf bank_mask:0xf
	v_pk_fma_f32 v[52:53], v[104:105], v[186:187], v[190:191]
	v_mov_b32_dpp v18, v106 row_shr:1 row_mask:0xf bank_mask:0xf
	v_mov_b32_dpp v46, v102 row_shl:14 row_mask:0xf bank_mask:0xf bound_ctrl:1
	v_mov_b32_dpp v19, v107 row_shr:1 row_mask:0xf bank_mask:0xf
	v_mov_b32_dpp v47, v103 row_shl:14 row_mask:0xf bank_mask:0xf bound_ctrl:1
	v_mov_b32_dpp v50, v98 row_shl:14 row_mask:0xf bank_mask:0xf bound_ctrl:1
	v_mov_b32_dpp v51, v99 row_shl:14 row_mask:0xf bank_mask:0xf bound_ctrl:1
	v_pk_fma_f32 v[54:55], v[106:107], v[184:185], v[188:189]
	v_pk_fma_f32 v[48:49], v[194:195], v[48:49], v[52:53]
	v_mov_b32_dpp v52, v92 row_shl:15 row_mask:0xf bank_mask:0xf bound_ctrl:1
	v_mov_b32_dpp v53, v93 row_shl:15 row_mask:0xf bank_mask:0xf bound_ctrl:1
	v_mov_b32_dpp v46, v106 row_shr:2 row_mask:0xf bank_mask:0xf
	v_mov_b32_dpp v47, v107 row_shr:2 row_mask:0xf bank_mask:0xf
	v_mov_b32_dpp v50, v104 row_shr:2 row_mask:0xf bank_mask:0xf
	v_mov_b32_dpp v51, v105 row_shr:2 row_mask:0xf bank_mask:0xf
	v_pk_fma_f32 v[18:19], v[192:193], v[18:19], v[54:55]
	v_mov_b32_dpp v52, v96 row_shr:1 row_mask:0xf bank_mask:0xf
	v_mov_b32_dpp v54, v92 row_shl:14 row_mask:0xf bank_mask:0xf bound_ctrl:1
	v_mov_b32_dpp v53, v97 row_shr:1 row_mask:0xf bank_mask:0xf
	v_mov_b32_dpp v55, v93 row_shl:14 row_mask:0xf bank_mask:0xf bound_ctrl:1
	v_pk_fma_f32 v[56:57], v[96:97], v[202:203], v[206:207]
	v_pk_fma_f32 v[18:19], v[196:197], v[46:47], v[18:19]
	v_pk_fma_f32 v[46:47], v[198:199], v[50:51], v[48:49]
	v_mov_b32_dpp v54, v96 row_shr:2 row_mask:0xf bank_mask:0xf
	v_mov_b32_dpp v55, v97 row_shr:2 row_mask:0xf bank_mask:0xf
	v_pk_fma_f32 v[52:53], v[210:211], v[52:53], v[56:57]
	v_pk_mul_f32 v[56:57], v[18:19], v[18:19]
	v_pk_fma_f32 v[52:53], v[214:215], v[54:55], v[52:53]
	v_pk_mul_f32 v[54:55], v[46:47], v[46:47]
	v_pk_fma_f32 v[56:57], v[56:57], s[52:53], 1.0 op_sel_hi:[1,0,0]
	v_pk_fma_f32 v[54:55], v[54:55], s[52:53], 1.0 op_sel_hi:[1,0,0]
	v_pk_mul_f32 v[56:57], v[18:19], v[56:57]
	v_pk_mul_f32 v[54:55], v[46:47], v[54:55]
	v_pk_mul_f32 v[56:57], v[56:57], s[54:55] op_sel_hi:[1,0]
	v_pk_mul_f32 v[54:55], v[54:55], s[54:55] op_sel_hi:[1,0]
	v_exp_f32_e32 v56, v56
	v_exp_f32_e32 v57, v57
	v_exp_f32_e32 v54, v54
	v_exp_f32_e32 v55, v55
	v_mov_b32_dpp v48, v94 row_shl:15 row_mask:0xf bank_mask:0xf bound_ctrl:1
	v_pk_add_f32 v[56:57], v[56:57], 1.0 op_sel_hi:[1,0]
	v_mov_b32_dpp v49, v95 row_shl:15 row_mask:0xf bank_mask:0xf bound_ctrl:1
	v_pk_add_f32 v[54:55], v[54:55], 1.0 op_sel_hi:[1,0]
	v_rcp_f32_e32 v56, v56
	v_rcp_f32_e32 v57, v57
	v_rcp_f32_e32 v54, v54
	v_rcp_f32_e32 v55, v55
	s_add_i32 s64, s57, 48
	v_mov_b32_dpp v48, v100 row_shr:1 row_mask:0xf bank_mask:0xf
	v_mov_b32_dpp v50, v94 row_shl:14 row_mask:0xf bank_mask:0xf bound_ctrl:1
	v_mov_b32_dpp v49, v101 row_shr:1 row_mask:0xf bank_mask:0xf
	v_mov_b32_dpp v51, v95 row_shl:14 row_mask:0xf bank_mask:0xf bound_ctrl:1
	v_pk_fma_f32 v[92:93], v[100:101], v[200:201], v[204:205]
	v_add_u32_e32 v6, s64, v231
	v_mov_b32_dpp v50, v100 row_shr:2 row_mask:0xf bank_mask:0xf
	v_mov_b32_dpp v51, v101 row_shr:2 row_mask:0xf bank_mask:0xf
	v_pk_fma_f32 v[48:49], v[208:209], v[48:49], v[92:93]
	v_pk_mul_f32 v[18:19], v[18:19], v[56:57]
	v_pk_fma_f32 v[48:49], v[212:213], v[50:51], v[48:49]
	v_pk_mul_f32 v[46:47], v[46:47], v[54:55]
	v_cmp_gt_i32_e32 vcc, s93, v6
	v_pk_mul_f32 v[18:19], v[48:49], v[18:19]
	v_pk_mul_f32 v[48:49], v[52:53], v[46:47]
	v_cvt_pk_bf16_f32 v46, v18, v19
	s_nop 0
	v_cvt_pk_bf16_f32 v47, v48, v49
	s_and_saveexec_b64 s[62:63], vcc
	s_cbranch_execz .LBB0_877
	v_add_u32_e32 v18, -2, v6
	v_mov_b64_e32 v[6:7], s[42:43]
	v_mad_i64_i32 v[6:7], s[22:23], v18, s94, v[6:7]
	v_lshl_add_u64 v[6:7], v[58:59], 1, v[6:7]
	global_store_dwordx4 v[6:7], v[44:47], off
.LBB0_877:
	s_or_b64 exec, exec, s[62:63]
	v_mov_b32_dpp v18, v90 row_shl:15 row_mask:0xf bank_mask:0xf bound_ctrl:1
	v_mov_b32_dpp v19, v91 row_shl:15 row_mask:0xf bank_mask:0xf bound_ctrl:1
	v_mov_b32_dpp v46, v88 row_shl:15 row_mask:0xf bank_mask:0xf bound_ctrl:1
	v_mov_b32_dpp v47, v89 row_shl:15 row_mask:0xf bank_mask:0xf bound_ctrl:1
	v_mov_b32_dpp v18, v90 row_shr:1 row_mask:0xf bank_mask:0xf
	v_mov_b32_dpp v44, v90 row_shl:14 row_mask:0xf bank_mask:0xf bound_ctrl:1
	v_mov_b32_dpp v19, v91 row_shr:1 row_mask:0xf bank_mask:0xf
	v_mov_b32_dpp v45, v91 row_shl:14 row_mask:0xf bank_mask:0xf bound_ctrl:1
	v_mov_b32_dpp v46, v88 row_shr:1 row_mask:0xf bank_mask:0xf
	v_mov_b32_dpp v47, v89 row_shr:1 row_mask:0xf bank_mask:0xf
	v_pk_fma_f32 v[50:51], v[88:89], v[186:187], v[190:191]
	v_pk_fma_f32 v[52:53], v[90:91], v[184:185], v[188:189]
	v_mov_b32_dpp v44, v90 row_shr:2 row_mask:0xf bank_mask:0xf
	v_mov_b32_dpp v45, v91 row_shr:2 row_mask:0xf bank_mask:0xf
	v_mov_b32_dpp v48, v88 row_shl:14 row_mask:0xf bank_mask:0xf bound_ctrl:1
	v_mov_b32_dpp v49, v89 row_shl:14 row_mask:0xf bank_mask:0xf bound_ctrl:1
	v_pk_fma_f32 v[46:47], v[194:195], v[46:47], v[50:51]
	v_pk_fma_f32 v[18:19], v[192:193], v[18:19], v[52:53]
	v_mov_b32_dpp v50, v84 row_shl:15 row_mask:0xf bank_mask:0xf bound_ctrl:1
	v_mov_b32_dpp v51, v85 row_shl:15 row_mask:0xf bank_mask:0xf bound_ctrl:1
	v_mov_b32_dpp v48, v88 row_shr:2 row_mask:0xf bank_mask:0xf
	v_mov_b32_dpp v49, v89 row_shr:2 row_mask:0xf bank_mask:0xf
	v_pk_fma_f32 v[18:19], v[196:197], v[44:45], v[18:19]
	v_mov_b32_dpp v50, v84 row_shr:1 row_mask:0xf bank_mask:0xf
	v_mov_b32_dpp v52, v84 row_shl:14 row_mask:0xf bank_mask:0xf bound_ctrl:1
	v_mov_b32_dpp v51, v85 row_shr:1 row_mask:0xf bank_mask:0xf
	v_mov_b32_dpp v53, v85 row_shl:14 row_mask:0xf bank_mask:0xf bound_ctrl:1
	v_pk_fma_f32 v[54:55], v[84:85], v[202:203], v[206:207]
	v_pk_fma_f32 v[44:45], v[198:199], v[48:49], v[46:47]
	v_mov_b32_dpp v52, v84 row_shr:2 row_mask:0xf bank_mask:0xf
	v_mov_b32_dpp v53, v85 row_shr:2 row_mask:0xf bank_mask:0xf
	v_pk_fma_f32 v[50:51], v[210:211], v[50:51], v[54:55]
	v_pk_mul_f32 v[54:55], v[18:19], v[18:19]
	v_pk_fma_f32 v[50:51], v[214:215], v[52:53], v[50:51]
	v_pk_mul_f32 v[52:53], v[44:45], v[44:45]
	v_pk_fma_f32 v[54:55], v[54:55], s[52:53], 1.0 op_sel_hi:[1,0,0]
	v_pk_fma_f32 v[52:53], v[52:53], s[52:53], 1.0 op_sel_hi:[1,0,0]
	v_pk_mul_f32 v[54:55], v[18:19], v[54:55]
	v_pk_mul_f32 v[52:53], v[44:45], v[52:53]
	v_pk_mul_f32 v[54:55], v[54:55], s[54:55] op_sel_hi:[1,0]
	v_pk_mul_f32 v[52:53], v[52:53], s[54:55] op_sel_hi:[1,0]
	v_exp_f32_e32 v54, v54
	v_exp_f32_e32 v55, v55
	v_exp_f32_e32 v52, v52
	v_exp_f32_e32 v53, v53
	v_mov_b32_dpp v46, v86 row_shl:15 row_mask:0xf bank_mask:0xf bound_ctrl:1
	v_pk_add_f32 v[54:55], v[54:55], 1.0 op_sel_hi:[1,0]
	v_mov_b32_dpp v47, v87 row_shl:15 row_mask:0xf bank_mask:0xf bound_ctrl:1
	v_rcp_f32_e32 v54, v54
	v_rcp_f32_e32 v55, v55
	v_pk_add_f32 v[52:53], v[52:53], 1.0 op_sel_hi:[1,0]
	v_mov_b32_dpp v46, v86 row_shr:1 row_mask:0xf bank_mask:0xf
	v_rcp_f32_e32 v52, v52
	v_rcp_f32_e32 v53, v53
	v_mov_b32_dpp v48, v86 row_shl:14 row_mask:0xf bank_mask:0xf bound_ctrl:1
	v_mov_b32_dpp v47, v87 row_shr:1 row_mask:0xf bank_mask:0xf
	v_mov_b32_dpp v49, v87 row_shl:14 row_mask:0xf bank_mask:0xf bound_ctrl:1
	v_pk_fma_f32 v[56:57], v[86:87], v[200:201], v[204:205]
	v_add_u32_e32 v6, s57, v230
	v_mov_b32_dpp v48, v86 row_shr:2 row_mask:0xf bank_mask:0xf
	v_mov_b32_dpp v49, v87 row_shr:2 row_mask:0xf bank_mask:0xf
	v_pk_fma_f32 v[46:47], v[208:209], v[46:47], v[56:57]
	v_pk_mul_f32 v[18:19], v[18:19], v[54:55]
	v_pk_fma_f32 v[46:47], v[212:213], v[48:49], v[46:47]
	v_cmp_gt_i32_e32 vcc, s93, v6
	v_pk_mul_f32 v[18:19], v[46:47], v[18:19]
	v_pk_mul_f32 v[44:45], v[44:45], v[52:53]
	s_and_b64 s[22:23], s[12:13], vcc
	v_pk_mul_f32 v[44:45], v[50:51], v[44:45]
	v_cvt_pk_bf16_f32 v18, v18, v19
	s_nop 0
	v_cvt_pk_bf16_f32 v19, v44, v45
	s_and_saveexec_b64 s[12:13], s[22:23]
	s_cbranch_execz .LBB0_879
	v_add_u32_e32 v44, -2, v6
	v_mov_b64_e32 v[6:7], s[42:43]
	v_mad_i64_i32 v[6:7], s[22:23], v44, s94, v[6:7]
	v_lshl_add_u64 v[6:7], v[58:59], 1, v[6:7]
	global_store_dwordx4 v[6:7], v[16:19], off
.LBB0_879:
	s_or_b64 exec, exec, s[12:13]
	v_mov_b32_dpp v6, v90 row_shl:15 row_mask:0xf bank_mask:0xf bound_ctrl:1
	v_mov_b32_dpp v7, v91 row_shl:15 row_mask:0xf bank_mask:0xf bound_ctrl:1
	v_mov_b32_dpp v44, v88 row_shl:15 row_mask:0xf bank_mask:0xf bound_ctrl:1
	v_mov_b32_dpp v45, v89 row_shl:15 row_mask:0xf bank_mask:0xf bound_ctrl:1
	v_mov_b32_dpp v6, v82 row_shr:1 row_mask:0xf bank_mask:0xf
	v_mov_b32_dpp v18, v90 row_shl:14 row_mask:0xf bank_mask:0xf bound_ctrl:1
	v_mov_b32_dpp v7, v83 row_shr:1 row_mask:0xf bank_mask:0xf
	v_mov_b32_dpp v19, v91 row_shl:14 row_mask:0xf bank_mask:0xf bound_ctrl:1
	v_mov_b32_dpp v44, v80 row_shr:1 row_mask:0xf bank_mask:0xf
	v_mov_b32_dpp v45, v81 row_shr:1 row_mask:0xf bank_mask:0xf
	v_pk_fma_f32 v[48:49], v[80:81], v[186:187], v[190:191]
	v_pk_fma_f32 v[50:51], v[82:83], v[184:185], v[188:189]
	v_mov_b32_dpp v18, v82 row_shr:2 row_mask:0xf bank_mask:0xf
	v_mov_b32_dpp v19, v83 row_shr:2 row_mask:0xf bank_mask:0xf
	v_mov_b32_dpp v46, v88 row_shl:14 row_mask:0xf bank_mask:0xf bound_ctrl:1
	v_mov_b32_dpp v47, v89 row_shl:14 row_mask:0xf bank_mask:0xf bound_ctrl:1
	v_pk_fma_f32 v[44:45], v[194:195], v[44:45], v[48:49]
	v_pk_fma_f32 v[6:7], v[192:193], v[6:7], v[50:51]
	v_mov_b32_dpp v48, v84 row_shl:15 row_mask:0xf bank_mask:0xf bound_ctrl:1
	v_mov_b32_dpp v49, v85 row_shl:15 row_mask:0xf bank_mask:0xf bound_ctrl:1
	v_mov_b32_dpp v46, v80 row_shr:2 row_mask:0xf bank_mask:0xf
	v_mov_b32_dpp v47, v81 row_shr:2 row_mask:0xf bank_mask:0xf
	v_pk_fma_f32 v[6:7], v[196:197], v[18:19], v[6:7]
	v_mov_b32_dpp v48, v76 row_shr:1 row_mask:0xf bank_mask:0xf
	v_mov_b32_dpp v50, v84 row_shl:14 row_mask:0xf bank_mask:0xf bound_ctrl:1
	v_mov_b32_dpp v49, v77 row_shr:1 row_mask:0xf bank_mask:0xf
	v_mov_b32_dpp v51, v85 row_shl:14 row_mask:0xf bank_mask:0xf bound_ctrl:1
	v_pk_fma_f32 v[52:53], v[76:77], v[202:203], v[206:207]
	v_pk_fma_f32 v[18:19], v[198:199], v[46:47], v[44:45]
	v_mov_b32_dpp v50, v76 row_shr:2 row_mask:0xf bank_mask:0xf
	v_mov_b32_dpp v51, v77 row_shr:2 row_mask:0xf bank_mask:0xf
	v_pk_fma_f32 v[48:49], v[210:211], v[48:49], v[52:53]
	v_pk_mul_f32 v[52:53], v[6:7], v[6:7]
	v_pk_fma_f32 v[48:49], v[214:215], v[50:51], v[48:49]
	v_pk_mul_f32 v[50:51], v[18:19], v[18:19]
	v_pk_fma_f32 v[52:53], v[52:53], s[52:53], 1.0 op_sel_hi:[1,0,0]
	v_pk_fma_f32 v[50:51], v[50:51], s[52:53], 1.0 op_sel_hi:[1,0,0]
	v_pk_mul_f32 v[52:53], v[6:7], v[52:53]
	v_pk_mul_f32 v[50:51], v[18:19], v[50:51]
	v_pk_mul_f32 v[52:53], v[52:53], s[54:55] op_sel_hi:[1,0]
	v_pk_mul_f32 v[50:51], v[50:51], s[54:55] op_sel_hi:[1,0]
	v_exp_f32_e32 v52, v52
	v_exp_f32_e32 v53, v53
	v_exp_f32_e32 v50, v50
	v_exp_f32_e32 v51, v51
	v_mov_b32_dpp v44, v86 row_shl:15 row_mask:0xf bank_mask:0xf bound_ctrl:1
	v_pk_add_f32 v[52:53], v[52:53], 1.0 op_sel_hi:[1,0]
	v_mov_b32_dpp v45, v87 row_shl:15 row_mask:0xf bank_mask:0xf bound_ctrl:1
	v_rcp_f32_e32 v52, v52
	v_rcp_f32_e32 v53, v53
	v_pk_add_f32 v[50:51], v[50:51], 1.0 op_sel_hi:[1,0]
	v_mov_b32_dpp v44, v78 row_shr:1 row_mask:0xf bank_mask:0xf
	v_rcp_f32_e32 v50, v50
	v_rcp_f32_e32 v51, v51
	v_mov_b32_dpp v46, v86 row_shl:14 row_mask:0xf bank_mask:0xf bound_ctrl:1
	v_mov_b32_dpp v45, v79 row_shr:1 row_mask:0xf bank_mask:0xf
	v_mov_b32_dpp v47, v87 row_shl:14 row_mask:0xf bank_mask:0xf bound_ctrl:1
	v_pk_fma_f32 v[54:55], v[78:79], v[200:201], v[204:205]
	v_mov_b32_dpp v46, v78 row_shr:2 row_mask:0xf bank_mask:0xf
	v_mov_b32_dpp v47, v79 row_shr:2 row_mask:0xf bank_mask:0xf
	v_pk_fma_f32 v[44:45], v[208:209], v[44:45], v[54:55]
	v_add_u32_e32 v16, s26, v230
	v_pk_fma_f32 v[44:45], v[212:213], v[46:47], v[44:45]
	v_pk_mul_f32 v[6:7], v[6:7], v[52:53]
	v_pk_mul_f32 v[18:19], v[18:19], v[50:51]
	v_pk_mul_f32 v[6:7], v[44:45], v[6:7]
	v_cmp_gt_i32_e32 vcc, s93, v16
	v_pk_mul_f32 v[18:19], v[48:49], v[18:19]
	v_cvt_pk_bf16_f32 v6, v6, v7
	s_nop 0
	v_cvt_pk_bf16_f32 v7, v18, v19
	s_and_saveexec_b64 s[12:13], vcc
	s_cbranch_execz .LBB0_881
	v_add_u32_e32 v18, -2, v16
	v_mov_b64_e32 v[16:17], s[42:43]
	v_mad_i64_i32 v[16:17], s[22:23], v18, s94, v[16:17]
	v_lshl_add_u64 v[16:17], v[58:59], 1, v[16:17]
	global_store_dwordx4 v[16:17], v[4:7], off
.LBB0_881:
	s_or_b64 exec, exec, s[12:13]
	s_nop 0
	v_mov_b32_dpp v4, v82 row_shl:15 row_mask:0xf bank_mask:0xf bound_ctrl:1
	v_mov_b32_dpp v5, v83 row_shl:15 row_mask:0xf bank_mask:0xf bound_ctrl:1
	v_mov_b32_dpp v18, v80 row_shl:15 row_mask:0xf bank_mask:0xf bound_ctrl:1
	v_mov_b32_dpp v19, v81 row_shl:15 row_mask:0xf bank_mask:0xf bound_ctrl:1
	v_mov_b32_dpp v4, v70 row_shr:1 row_mask:0xf bank_mask:0xf
	v_mov_b32_dpp v16, v82 row_shl:14 row_mask:0xf bank_mask:0xf bound_ctrl:1
	v_mov_b32_dpp v5, v71 row_shr:1 row_mask:0xf bank_mask:0xf
	v_mov_b32_dpp v17, v83 row_shl:14 row_mask:0xf bank_mask:0xf bound_ctrl:1
	v_mov_b32_dpp v18, v68 row_shr:1 row_mask:0xf bank_mask:0xf
	v_mov_b32_dpp v19, v69 row_shr:1 row_mask:0xf bank_mask:0xf
	v_pk_fma_f32 v[46:47], v[68:69], v[186:187], v[190:191]
	v_pk_fma_f32 v[48:49], v[70:71], v[184:185], v[188:189]
	v_mov_b32_dpp v16, v70 row_shr:2 row_mask:0xf bank_mask:0xf
	v_mov_b32_dpp v17, v71 row_shr:2 row_mask:0xf bank_mask:0xf
	v_mov_b32_dpp v44, v80 row_shl:14 row_mask:0xf bank_mask:0xf bound_ctrl:1
	v_mov_b32_dpp v45, v81 row_shl:14 row_mask:0xf bank_mask:0xf bound_ctrl:1
	v_pk_fma_f32 v[18:19], v[194:195], v[18:19], v[46:47]
	v_pk_fma_f32 v[4:5], v[192:193], v[4:5], v[48:49]
	v_mov_b32_dpp v46, v76 row_shl:15 row_mask:0xf bank_mask:0xf bound_ctrl:1
	v_mov_b32_dpp v47, v77 row_shl:15 row_mask:0xf bank_mask:0xf bound_ctrl:1
	v_mov_b32_dpp v44, v68 row_shr:2 row_mask:0xf bank_mask:0xf
	v_mov_b32_dpp v45, v69 row_shr:2 row_mask:0xf bank_mask:0xf
	v_pk_fma_f32 v[4:5], v[196:197], v[16:17], v[4:5]
	v_mov_b32_dpp v46, v60 row_shr:1 row_mask:0xf bank_mask:0xf
	v_mov_b32_dpp v48, v76 row_shl:14 row_mask:0xf bank_mask:0xf bound_ctrl:1
	v_mov_b32_dpp v47, v61 row_shr:1 row_mask:0xf bank_mask:0xf
	v_mov_b32_dpp v49, v77 row_shl:14 row_mask:0xf bank_mask:0xf bound_ctrl:1
	v_pk_fma_f32 v[50:51], v[60:61], v[202:203], v[206:207]
	v_pk_fma_f32 v[16:17], v[198:199], v[44:45], v[18:19]
	v_mov_b32_dpp v48, v60 row_shr:2 row_mask:0xf bank_mask:0xf
	v_mov_b32_dpp v49, v61 row_shr:2 row_mask:0xf bank_mask:0xf
	v_pk_fma_f32 v[46:47], v[210:211], v[46:47], v[50:51]
	v_pk_mul_f32 v[50:51], v[4:5], v[4:5]
	v_pk_fma_f32 v[46:47], v[214:215], v[48:49], v[46:47]
	v_pk_mul_f32 v[48:49], v[16:17], v[16:17]
	v_pk_fma_f32 v[50:51], v[50:51], s[52:53], 1.0 op_sel_hi:[1,0,0]
	v_pk_fma_f32 v[48:49], v[48:49], s[52:53], 1.0 op_sel_hi:[1,0,0]
	v_pk_mul_f32 v[50:51], v[4:5], v[50:51]
	v_pk_mul_f32 v[48:49], v[16:17], v[48:49]
	v_pk_mul_f32 v[50:51], v[50:51], s[54:55] op_sel_hi:[1,0]
	v_pk_mul_f32 v[48:49], v[48:49], s[54:55] op_sel_hi:[1,0]
	v_exp_f32_e32 v50, v50
	v_exp_f32_e32 v51, v51
	v_exp_f32_e32 v48, v48
	v_exp_f32_e32 v49, v49
	v_mov_b32_dpp v18, v78 row_shl:15 row_mask:0xf bank_mask:0xf bound_ctrl:1
	v_pk_add_f32 v[50:51], v[50:51], 1.0 op_sel_hi:[1,0]
	v_mov_b32_dpp v19, v79 row_shl:15 row_mask:0xf bank_mask:0xf bound_ctrl:1
	v_rcp_f32_e32 v50, v50
	v_rcp_f32_e32 v51, v51
	v_pk_add_f32 v[48:49], v[48:49], 1.0 op_sel_hi:[1,0]
	v_mov_b32_dpp v18, v62 row_shr:1 row_mask:0xf bank_mask:0xf
	v_rcp_f32_e32 v48, v48
	v_rcp_f32_e32 v49, v49
	v_mov_b32_dpp v44, v78 row_shl:14 row_mask:0xf bank_mask:0xf bound_ctrl:1
	v_mov_b32_dpp v19, v63 row_shr:1 row_mask:0xf bank_mask:0xf
	v_mov_b32_dpp v45, v79 row_shl:14 row_mask:0xf bank_mask:0xf bound_ctrl:1
	v_pk_fma_f32 v[52:53], v[62:63], v[200:201], v[204:205]
	v_mov_b32_dpp v44, v62 row_shr:2 row_mask:0xf bank_mask:0xf
	v_mov_b32_dpp v45, v63 row_shr:2 row_mask:0xf bank_mask:0xf
	v_pk_fma_f32 v[18:19], v[208:209], v[18:19], v[52:53]
	v_add_u32_e32 v6, s27, v230
	v_pk_fma_f32 v[18:19], v[212:213], v[44:45], v[18:19]
	v_pk_mul_f32 v[4:5], v[4:5], v[50:51]
	v_pk_mul_f32 v[16:17], v[16:17], v[48:49]
	v_pk_mul_f32 v[4:5], v[18:19], v[4:5]
	v_cmp_gt_i32_e32 vcc, s93, v6
	v_pk_mul_f32 v[16:17], v[46:47], v[16:17]
	v_cvt_pk_bf16_f32 v4, v4, v5
	s_nop 0
	v_cvt_pk_bf16_f32 v5, v16, v17
	s_and_saveexec_b64 s[12:13], vcc
	s_cbranch_execz .LBB0_883
	v_add_u32_e32 v16, -2, v6
	v_mov_b64_e32 v[6:7], s[42:43]
	v_mad_i64_i32 v[6:7], s[22:23], v16, s94, v[6:7]
	v_lshl_add_u64 v[6:7], v[58:59], 1, v[6:7]
	global_store_dwordx4 v[6:7], v[2:5], off
.LBB0_883:
	s_or_b64 exec, exec, s[12:13]
	s_nop 0
	v_mov_b32_dpp v2, v70 row_shl:15 row_mask:0xf bank_mask:0xf bound_ctrl:1
	v_mov_b32_dpp v3, v71 row_shl:15 row_mask:0xf bank_mask:0xf bound_ctrl:1
	v_mov_b32_dpp v16, v68 row_shl:15 row_mask:0xf bank_mask:0xf bound_ctrl:1
	v_mov_b32_dpp v17, v69 row_shl:15 row_mask:0xf bank_mask:0xf bound_ctrl:1
	v_mov_b32_dpp v2, v74 row_shr:1 row_mask:0xf bank_mask:0xf
	v_mov_b32_dpp v6, v70 row_shl:14 row_mask:0xf bank_mask:0xf bound_ctrl:1
	v_mov_b32_dpp v3, v75 row_shr:1 row_mask:0xf bank_mask:0xf
	v_mov_b32_dpp v7, v71 row_shl:14 row_mask:0xf bank_mask:0xf bound_ctrl:1
	v_mov_b32_dpp v16, v72 row_shr:1 row_mask:0xf bank_mask:0xf
	v_mov_b32_dpp v18, v68 row_shl:14 row_mask:0xf bank_mask:0xf bound_ctrl:1
	v_mov_b32_dpp v17, v73 row_shr:1 row_mask:0xf bank_mask:0xf
	v_mov_b32_dpp v19, v69 row_shl:14 row_mask:0xf bank_mask:0xf bound_ctrl:1
	v_pk_fma_f32 v[38:39], v[72:73], v[186:187], v[190:191]
	v_pk_fma_f32 v[36:37], v[74:75], v[184:185], v[188:189]
	v_mov_b32_dpp v6, v74 row_shr:2 row_mask:0xf bank_mask:0xf
	v_mov_b32_dpp v7, v75 row_shr:2 row_mask:0xf bank_mask:0xf
	v_mov_b32_dpp v18, v72 row_shr:2 row_mask:0xf bank_mask:0xf
	v_mov_b32_dpp v19, v73 row_shr:2 row_mask:0xf bank_mask:0xf
	v_pk_fma_f32 v[16:17], v[194:195], v[16:17], v[38:39]
	v_pk_fma_f32 v[2:3], v[192:193], v[2:3], v[36:37]
	v_pk_fma_f32 v[22:23], v[64:65], v[202:203], v[206:207]
	v_pk_fma_f32 v[2:3], v[196:197], v[6:7], v[2:3]
	v_pk_fma_f32 v[6:7], v[198:199], v[18:19], v[16:17]
	v_mov_b32_dpp v16, v62 row_shl:15 row_mask:0xf bank_mask:0xf bound_ctrl:1
	v_mov_b32_dpp v17, v63 row_shl:15 row_mask:0xf bank_mask:0xf bound_ctrl:1
	v_mov_b32_dpp v28, v60 row_shl:15 row_mask:0xf bank_mask:0xf bound_ctrl:1
	v_mov_b32_dpp v29, v61 row_shl:15 row_mask:0xf bank_mask:0xf bound_ctrl:1
	v_mov_b32_dpp v16, v66 row_shr:1 row_mask:0xf bank_mask:0xf
	v_mov_b32_dpp v17, v67 row_shr:1 row_mask:0xf bank_mask:0xf
	v_mov_b32_dpp v28, v64 row_shr:1 row_mask:0xf bank_mask:0xf
	v_mov_b32_dpp v30, v60 row_shl:14 row_mask:0xf bank_mask:0xf bound_ctrl:1
	v_mov_b32_dpp v29, v65 row_shr:1 row_mask:0xf bank_mask:0xf
	v_mov_b32_dpp v31, v61 row_shl:14 row_mask:0xf bank_mask:0xf bound_ctrl:1
	v_pk_fma_f32 v[20:21], v[66:67], v[200:201], v[204:205]
	v_mov_b32_dpp v30, v64 row_shr:2 row_mask:0xf bank_mask:0xf
	v_mov_b32_dpp v31, v65 row_shr:2 row_mask:0xf bank_mask:0xf
	v_pk_fma_f32 v[12:13], v[208:209], v[16:17], v[20:21]
	v_pk_fma_f32 v[14:15], v[210:211], v[28:29], v[22:23]
	v_pk_mul_f32 v[16:17], v[2:3], v[2:3]
	v_pk_fma_f32 v[10:11], v[214:215], v[30:31], v[14:15]
	v_pk_mul_f32 v[14:15], v[6:7], v[6:7]
	v_pk_fma_f32 v[16:17], v[16:17], s[52:53], 1.0 op_sel_hi:[1,0,0]
	v_pk_fma_f32 v[14:15], v[14:15], s[52:53], 1.0 op_sel_hi:[1,0,0]
	v_pk_mul_f32 v[16:17], v[2:3], v[16:17]
	v_pk_mul_f32 v[14:15], v[6:7], v[14:15]
	v_pk_mul_f32 v[16:17], v[16:17], s[54:55] op_sel_hi:[1,0]
	v_pk_mul_f32 v[14:15], v[14:15], s[54:55] op_sel_hi:[1,0]
	v_exp_f32_e32 v16, v16
	v_exp_f32_e32 v17, v17
	v_exp_f32_e32 v14, v14
	v_exp_f32_e32 v15, v15
	v_mov_b32_dpp v18, v62 row_shl:14 row_mask:0xf bank_mask:0xf bound_ctrl:1
	v_pk_add_f32 v[16:17], v[16:17], 1.0 op_sel_hi:[1,0]
	v_mov_b32_dpp v19, v63 row_shl:14 row_mask:0xf bank_mask:0xf bound_ctrl:1
	v_rcp_f32_e32 v16, v16
	v_rcp_f32_e32 v17, v17
	v_pk_add_f32 v[14:15], v[14:15], 1.0 op_sel_hi:[1,0]
	v_mov_b32_dpp v18, v66 row_shr:2 row_mask:0xf bank_mask:0xf
	v_rcp_f32_e32 v14, v14
	v_rcp_f32_e32 v15, v15
	v_mov_b32_dpp v19, v67 row_shr:2 row_mask:0xf bank_mask:0xf
	v_add_u32_e32 v5, s64, v230
	v_pk_fma_f32 v[8:9], v[212:213], v[18:19], v[12:13]
	v_pk_mul_f32 v[2:3], v[2:3], v[16:17]
	v_pk_mul_f32 v[6:7], v[6:7], v[14:15]
	v_pk_mul_f32 v[2:3], v[8:9], v[2:3]
	v_cmp_gt_i32_e32 vcc, s93, v5
	v_pk_mul_f32 v[6:7], v[10:11], v[6:7]
	v_cvt_pk_bf16_f32 v2, v2, v3
	s_nop 0
	v_cvt_pk_bf16_f32 v3, v6, v7
	s_and_saveexec_b64 s[12:13], vcc
	v_add_u32_e32 v4, -2, v5
	s_or_b64 s[14:15], s[14:15], exec
	s_or_b64 exec, exec, s[12:13]

.LBB0_1738:
	s_mov_b64 s[12:13], 0
	s_cbranch_execz .LBB0_1756
	global_load_dwordx4 v[34:37], v[214:215], off
	global_load_dwordx4 v[38:41], v[216:217], off
	global_load_dwordx4 v[18:21], v[218:219], off
	global_load_dwordx4 v[22:25], v[220:221], off
	global_load_dwordx4 v[30:33], v[208:209], off
	global_load_dwordx4 v[26:29], v[206:207], off
	global_load_dwordx4 v[14:17], v[212:213], off
	global_load_dwordx4 v[6:9], v[210:211], off
	v_mov_b32_dpp v0, v198 row_shl:15 row_mask:0xf bank_mask:0xf bound_ctrl:1
	v_mov_b32_dpp v2, v198 row_shl:14 row_mask:0xf bank_mask:0xf bound_ctrl:1
	v_mov_b32_dpp v1, v199 row_shl:15 row_mask:0xf bank_mask:0xf bound_ctrl:1
	v_mov_b32_dpp v3, v199 row_shl:14 row_mask:0xf bank_mask:0xf bound_ctrl:1
	v_mov_b32_dpp v4, v200 row_shl:15 row_mask:0xf bank_mask:0xf bound_ctrl:1
	v_mov_b32_dpp v10, v200 row_shl:14 row_mask:0xf bank_mask:0xf bound_ctrl:1
	v_mov_b32_dpp v5, v201 row_shl:15 row_mask:0xf bank_mask:0xf bound_ctrl:1
	v_mov_b32_dpp v11, v201 row_shl:14 row_mask:0xf bank_mask:0xf bound_ctrl:1
	v_mov_b32_e32 v48, v0
	v_mov_b32_e32 v50, v2
	v_mov_b32_e32 v49, v1
	v_mov_b32_e32 v51, v3
	v_mov_b32_e32 v52, v4
	v_mov_b32_e32 v54, v10
	v_mov_b32_e32 v53, v5
	v_mov_b32_e32 v55, v11
	v_mov_b32_dpp v48, v198 row_shr:1 row_mask:0xf bank_mask:0xf
	v_mov_b32_dpp v50, v198 row_shr:2 row_mask:0xf bank_mask:0xf
	v_mov_b32_dpp v49, v199 row_shr:1 row_mask:0xf bank_mask:0xf
	v_mov_b32_dpp v51, v199 row_shr:2 row_mask:0xf bank_mask:0xf
	v_mov_b32_dpp v52, v200 row_shr:1 row_mask:0xf bank_mask:0xf
	v_mov_b32_dpp v54, v200 row_shr:2 row_mask:0xf bank_mask:0xf
	v_mov_b32_dpp v53, v201 row_shr:1 row_mask:0xf bank_mask:0xf
	v_mov_b32_dpp v55, v201 row_shr:2 row_mask:0xf bank_mask:0xf
	v_mov_b32_dpp v12, v202 row_shl:15 row_mask:0xf bank_mask:0xf bound_ctrl:1
	v_mov_b32_dpp v42, v202 row_shl:14 row_mask:0xf bank_mask:0xf bound_ctrl:1
	v_mov_b32_dpp v13, v203 row_shl:15 row_mask:0xf bank_mask:0xf bound_ctrl:1
	v_mov_b32_dpp v43, v203 row_shl:14 row_mask:0xf bank_mask:0xf bound_ctrl:1
	v_mov_b32_dpp v44, v204 row_shl:15 row_mask:0xf bank_mask:0xf bound_ctrl:1
	v_mov_b32_dpp v46, v204 row_shl:14 row_mask:0xf bank_mask:0xf bound_ctrl:1
	v_mov_b32_dpp v45, v205 row_shl:15 row_mask:0xf bank_mask:0xf bound_ctrl:1
	v_mov_b32_dpp v47, v205 row_shl:14 row_mask:0xf bank_mask:0xf bound_ctrl:1
	v_mov_b32_e32 v56, v12
	v_mov_b32_e32 v206, v42
	v_mov_b32_e32 v57, v13
	v_mov_b32_e32 v207, v43
	v_mov_b32_e32 v208, v44
	v_mov_b32_e32 v210, v46
	v_mov_b32_e32 v209, v45
	v_mov_b32_e32 v211, v47
	v_mov_b32_dpp v56, v202 row_shr:1 row_mask:0xf bank_mask:0xf
	v_mov_b32_dpp v206, v202 row_shr:2 row_mask:0xf bank_mask:0xf
	v_mov_b32_dpp v57, v203 row_shr:1 row_mask:0xf bank_mask:0xf
	v_mov_b32_dpp v207, v203 row_shr:2 row_mask:0xf bank_mask:0xf
	v_mov_b32_dpp v208, v204 row_shr:1 row_mask:0xf bank_mask:0xf
	v_mov_b32_dpp v210, v204 row_shr:2 row_mask:0xf bank_mask:0xf
	v_mov_b32_dpp v209, v205 row_shr:1 row_mask:0xf bank_mask:0xf
	v_mov_b32_dpp v211, v205 row_shr:2 row_mask:0xf bank_mask:0xf
	v_mov_b32_dpp v0, v196 row_shr:1 row_mask:0xf bank_mask:0xf
	v_mov_b32_dpp v1, v197 row_shr:1 row_mask:0xf bank_mask:0xf
	v_mov_b32_dpp v4, v192 row_shr:1 row_mask:0xf bank_mask:0xf
	v_mov_b32_dpp v5, v193 row_shr:1 row_mask:0xf bank_mask:0xf
	v_mov_b32_dpp v2, v196 row_shr:2 row_mask:0xf bank_mask:0xf
	v_mov_b32_dpp v3, v197 row_shr:2 row_mask:0xf bank_mask:0xf
	v_mov_b32_dpp v10, v192 row_shr:2 row_mask:0xf bank_mask:0xf
	v_mov_b32_dpp v11, v193 row_shr:2 row_mask:0xf bank_mask:0xf
	v_mov_b32_dpp v44, v190 row_shr:1 row_mask:0xf bank_mask:0xf
	v_mov_b32_dpp v45, v191 row_shr:1 row_mask:0xf bank_mask:0xf
	v_mov_b32_dpp v12, v194 row_shr:1 row_mask:0xf bank_mask:0xf
	v_mov_b32_dpp v13, v195 row_shr:1 row_mask:0xf bank_mask:0xf
	v_mov_b32_dpp v42, v194 row_shr:2 row_mask:0xf bank_mask:0xf
	v_mov_b32_dpp v43, v195 row_shr:2 row_mask:0xf bank_mask:0xf
	v_mov_b32_dpp v46, v190 row_shr:2 row_mask:0xf bank_mask:0xf
	v_mov_b32_dpp v47, v191 row_shr:2 row_mask:0xf bank_mask:0xf
	v_cmp_gt_i32_e32 vcc, s76, v231
	s_and_b64 s[26:27], s[10:11], vcc
	s_waitcnt vmcnt(0)
	v_pk_fma_f32 v[200:201], v[200:201], v[36:37], v[40:41]
	v_pk_fma_f32 v[198:199], v[198:199], v[34:35], v[38:39]
	v_pk_fma_f32 v[204:205], v[204:205], v[20:21], v[24:25]
	v_pk_fma_f32 v[52:53], v[32:33], v[52:53], v[200:201]
	v_pk_fma_f32 v[48:49], v[30:31], v[48:49], v[198:199]
	v_pk_fma_f32 v[202:203], v[202:203], v[18:19], v[22:23]
	v_pk_fma_f32 v[48:49], v[26:27], v[50:51], v[48:49]
	v_pk_fma_f32 v[50:51], v[28:29], v[54:55], v[52:53]
	v_pk_mul_f32 v[54:55], v[48:49], v[48:49]
	v_pk_mul_f32 v[52:53], v[50:51], v[50:51]
	v_pk_fma_f32 v[54:55], v[54:55], s[42:43], 1.0 op_sel_hi:[1,0,0]
	v_pk_fma_f32 v[52:53], v[52:53], s[42:43], 1.0 op_sel_hi:[1,0,0]
	v_pk_mul_f32 v[54:55], v[48:49], v[54:55]
	v_pk_mul_f32 v[52:53], v[50:51], v[52:53]
	v_pk_mul_f32 v[54:55], v[54:55], s[44:45] op_sel_hi:[1,0]
	v_pk_mul_f32 v[52:53], v[52:53], s[44:45] op_sel_hi:[1,0]
	v_exp_f32_e32 v54, v54
	v_exp_f32_e32 v55, v55
	v_exp_f32_e32 v52, v52
	v_exp_f32_e32 v53, v53
	v_pk_fma_f32 v[56:57], v[14:15], v[56:57], v[202:203]
	v_pk_add_f32 v[54:55], v[54:55], 1.0 op_sel_hi:[1,0]
	v_pk_fma_f32 v[198:199], v[16:17], v[208:209], v[204:205]
	v_pk_add_f32 v[52:53], v[52:53], 1.0 op_sel_hi:[1,0]
	v_rcp_f32_e32 v54, v54
	v_rcp_f32_e32 v55, v55
	v_rcp_f32_e32 v52, v52
	v_rcp_f32_e32 v53, v53
	v_pk_fma_f32 v[198:199], v[8:9], v[210:211], v[198:199]
	v_pk_fma_f32 v[56:57], v[6:7], v[206:207], v[56:57]
	v_pk_mul_f32 v[48:49], v[48:49], v[54:55]
	v_pk_mul_f32 v[50:51], v[50:51], v[52:53]
	v_pk_mul_f32 v[48:49], v[56:57], v[48:49]
	v_pk_mul_f32 v[52:53], v[198:199], v[50:51]
	v_cvt_pk_bf16_f32 v50, v48, v49
	v_pk_fma_f32 v[48:49], v[192:193], v[36:37], v[40:41]
	v_cvt_pk_bf16_f32 v51, v52, v53
	v_pk_fma_f32 v[52:53], v[196:197], v[34:35], v[38:39]
	v_pk_fma_f32 v[4:5], v[32:33], v[4:5], v[48:49]
	v_pk_fma_f32 v[0:1], v[30:31], v[0:1], v[52:53]
	v_pk_fma_f32 v[52:53], v[182:183], v[18:19], v[22:23]
	v_pk_fma_f32 v[0:1], v[26:27], v[2:3], v[0:1]
	v_pk_fma_f32 v[2:3], v[28:29], v[10:11], v[4:5]
	v_pk_fma_f32 v[4:5], v[190:191], v[20:21], v[24:25]
	v_pk_fma_f32 v[10:11], v[194:195], v[18:19], v[22:23]
	v_pk_fma_f32 v[4:5], v[16:17], v[44:45], v[4:5]
	v_pk_mul_f32 v[44:45], v[0:1], v[0:1]
	v_pk_fma_f32 v[10:11], v[14:15], v[12:13], v[10:11]
	v_pk_mul_f32 v[12:13], v[2:3], v[2:3]
	v_pk_fma_f32 v[44:45], v[44:45], s[42:43], 1.0 op_sel_hi:[1,0,0]
	v_pk_fma_f32 v[12:13], v[12:13], s[42:43], 1.0 op_sel_hi:[1,0,0]
	v_pk_mul_f32 v[44:45], v[0:1], v[44:45]
	v_pk_mul_f32 v[12:13], v[2:3], v[12:13]
	v_pk_mul_f32 v[44:45], v[44:45], s[44:45] op_sel_hi:[1,0]
	v_pk_mul_f32 v[12:13], v[12:13], s[44:45] op_sel_hi:[1,0]
	v_exp_f32_e32 v44, v44
	v_exp_f32_e32 v45, v45
	v_exp_f32_e32 v12, v12
	v_exp_f32_e32 v13, v13
	v_pk_fma_f32 v[10:11], v[6:7], v[42:43], v[10:11]
	v_pk_add_f32 v[44:45], v[44:45], 1.0 op_sel_hi:[1,0]
	v_pk_fma_f32 v[4:5], v[8:9], v[46:47], v[4:5]
	v_rcp_f32_e32 v44, v44
	v_rcp_f32_e32 v45, v45
	v_pk_add_f32 v[12:13], v[12:13], 1.0 op_sel_hi:[1,0]
	v_pk_fma_f32 v[42:43], v[184:185], v[34:35], v[38:39]
	v_rcp_f32_e32 v12, v12
	v_rcp_f32_e32 v13, v13
	v_pk_mul_f32 v[0:1], v[0:1], v[44:45]
	v_pk_fma_f32 v[44:45], v[174:175], v[20:21], v[24:25]
	v_pk_mul_f32 v[0:1], v[10:11], v[0:1]
	v_pk_mul_f32 v[2:3], v[2:3], v[12:13]
	v_cvt_pk_bf16_f32 v48, v0, v1
	v_pk_fma_f32 v[12:13], v[178:179], v[36:37], v[40:41]
	v_pk_mul_f32 v[2:3], v[4:5], v[2:3]
	v_mov_b32_dpp v0, v196 row_shl:15 row_mask:0xf bank_mask:0xf bound_ctrl:1
	v_mov_b32_dpp v1, v197 row_shl:15 row_mask:0xf bank_mask:0xf bound_ctrl:1
	v_mov_b32_dpp v4, v192 row_shl:15 row_mask:0xf bank_mask:0xf bound_ctrl:1
	v_mov_b32_dpp v5, v193 row_shl:15 row_mask:0xf bank_mask:0xf bound_ctrl:1
	v_cvt_pk_bf16_f32 v49, v2, v3
	v_mov_b32_dpp v0, v184 row_shr:1 row_mask:0xf bank_mask:0xf
	v_mov_b32_dpp v2, v196 row_shl:14 row_mask:0xf bank_mask:0xf bound_ctrl:1
	v_mov_b32_dpp v1, v185 row_shr:1 row_mask:0xf bank_mask:0xf
	v_mov_b32_dpp v3, v197 row_shl:14 row_mask:0xf bank_mask:0xf bound_ctrl:1
	v_mov_b32_dpp v4, v178 row_shr:1 row_mask:0xf bank_mask:0xf
	v_mov_b32_dpp v5, v179 row_shr:1 row_mask:0xf bank_mask:0xf
	v_mov_b32_dpp v2, v184 row_shr:2 row_mask:0xf bank_mask:0xf
	v_mov_b32_dpp v3, v185 row_shr:2 row_mask:0xf bank_mask:0xf
	v_mov_b32_dpp v10, v192 row_shl:14 row_mask:0xf bank_mask:0xf bound_ctrl:1
	v_mov_b32_dpp v11, v193 row_shl:14 row_mask:0xf bank_mask:0xf bound_ctrl:1
	v_pk_fma_f32 v[4:5], v[32:33], v[4:5], v[12:13]
	v_pk_fma_f32 v[0:1], v[30:31], v[0:1], v[42:43]
	v_mov_b32_dpp v12, v190 row_shl:15 row_mask:0xf bank_mask:0xf bound_ctrl:1
	v_mov_b32_dpp v13, v191 row_shl:15 row_mask:0xf bank_mask:0xf bound_ctrl:1
	v_mov_b32_dpp v10, v178 row_shr:2 row_mask:0xf bank_mask:0xf
	v_mov_b32_dpp v11, v179 row_shr:2 row_mask:0xf bank_mask:0xf
	v_pk_fma_f32 v[0:1], v[26:27], v[2:3], v[0:1]
	v_mov_b32_dpp v12, v174 row_shr:1 row_mask:0xf bank_mask:0xf
	v_mov_b32_dpp v42, v190 row_shl:14 row_mask:0xf bank_mask:0xf bound_ctrl:1
	v_mov_b32_dpp v13, v175 row_shr:1 row_mask:0xf bank_mask:0xf
	v_mov_b32_dpp v43, v191 row_shl:14 row_mask:0xf bank_mask:0xf bound_ctrl:1
	v_pk_fma_f32 v[2:3], v[28:29], v[10:11], v[4:5]
	v_mov_b32_dpp v42, v174 row_shr:2 row_mask:0xf bank_mask:0xf
	v_mov_b32_dpp v43, v175 row_shr:2 row_mask:0xf bank_mask:0xf
	v_pk_fma_f32 v[12:13], v[16:17], v[12:13], v[44:45]
	v_pk_mul_f32 v[44:45], v[0:1], v[0:1]
	v_pk_fma_f32 v[12:13], v[8:9], v[42:43], v[12:13]
	v_pk_mul_f32 v[42:43], v[2:3], v[2:3]
	v_pk_fma_f32 v[44:45], v[44:45], s[42:43], 1.0 op_sel_hi:[1,0,0]
	v_pk_fma_f32 v[42:43], v[42:43], s[42:43], 1.0 op_sel_hi:[1,0,0]
	v_pk_mul_f32 v[44:45], v[0:1], v[44:45]
	v_pk_mul_f32 v[42:43], v[2:3], v[42:43]
	v_pk_mul_f32 v[44:45], v[44:45], s[44:45] op_sel_hi:[1,0]
	v_pk_mul_f32 v[42:43], v[42:43], s[44:45] op_sel_hi:[1,0]
	v_exp_f32_e32 v44, v44
	v_exp_f32_e32 v45, v45
	v_exp_f32_e32 v42, v42
	v_exp_f32_e32 v43, v43
	v_mov_b32_dpp v4, v194 row_shl:15 row_mask:0xf bank_mask:0xf bound_ctrl:1
	v_pk_add_f32 v[44:45], v[44:45], 1.0 op_sel_hi:[1,0]
	v_mov_b32_dpp v5, v195 row_shl:15 row_mask:0xf bank_mask:0xf bound_ctrl:1
	v_rcp_f32_e32 v44, v44
	v_rcp_f32_e32 v45, v45
	v_pk_add_f32 v[42:43], v[42:43], 1.0 op_sel_hi:[1,0]
	v_mov_b32_dpp v4, v176 row_shr:1 row_mask:0xf bank_mask:0xf
	v_rcp_f32_e32 v42, v42
	v_rcp_f32_e32 v43, v43
	v_mov_b32_dpp v10, v194 row_shl:14 row_mask:0xf bank_mask:0xf bound_ctrl:1
	v_mov_b32_dpp v5, v177 row_shr:1 row_mask:0xf bank_mask:0xf
	v_mov_b32_dpp v11, v195 row_shl:14 row_mask:0xf bank_mask:0xf bound_ctrl:1
	v_pk_fma_f32 v[46:47], v[176:177], v[18:19], v[22:23]
	v_mov_b32_dpp v10, v176 row_shr:2 row_mask:0xf bank_mask:0xf
	v_mov_b32_dpp v11, v177 row_shr:2 row_mask:0xf bank_mask:0xf
	v_pk_fma_f32 v[4:5], v[14:15], v[4:5], v[46:47]
	v_pk_mul_f32 v[0:1], v[0:1], v[44:45]
	v_pk_fma_f32 v[4:5], v[6:7], v[10:11], v[4:5]
	v_pk_mul_f32 v[2:3], v[2:3], v[42:43]
	v_pk_mul_f32 v[0:1], v[4:5], v[0:1]
	v_pk_mul_f32 v[2:3], v[12:13], v[2:3]
	v_cvt_pk_bf16_f32 v46, v0, v1
	v_mov_b32_dpp v4, v178 row_shl:15 row_mask:0xf bank_mask:0xf bound_ctrl:1
	v_mov_b32_dpp v0, v184 row_shl:15 row_mask:0xf bank_mask:0xf bound_ctrl:1
	v_mov_b32_dpp v1, v185 row_shl:15 row_mask:0xf bank_mask:0xf bound_ctrl:1
	v_mov_b32_dpp v5, v179 row_shl:15 row_mask:0xf bank_mask:0xf bound_ctrl:1
	v_cvt_pk_bf16_f32 v47, v2, v3
	v_mov_b32_dpp v0, v188 row_shr:1 row_mask:0xf bank_mask:0xf
	v_mov_b32_dpp v2, v184 row_shl:14 row_mask:0xf bank_mask:0xf bound_ctrl:1
	v_mov_b32_dpp v1, v189 row_shr:1 row_mask:0xf bank_mask:0xf
	v_mov_b32_dpp v3, v185 row_shl:14 row_mask:0xf bank_mask:0xf bound_ctrl:1
	v_mov_b32_dpp v4, v186 row_shr:1 row_mask:0xf bank_mask:0xf
	v_mov_b32_dpp v5, v187 row_shr:1 row_mask:0xf bank_mask:0xf
	v_pk_fma_f32 v[12:13], v[186:187], v[36:37], v[40:41]
	v_pk_fma_f32 v[42:43], v[188:189], v[34:35], v[38:39]
	v_mov_b32_dpp v2, v188 row_shr:2 row_mask:0xf bank_mask:0xf
	v_mov_b32_dpp v3, v189 row_shr:2 row_mask:0xf bank_mask:0xf
	v_mov_b32_dpp v10, v178 row_shl:14 row_mask:0xf bank_mask:0xf bound_ctrl:1
	v_mov_b32_dpp v11, v179 row_shl:14 row_mask:0xf bank_mask:0xf bound_ctrl:1
	v_pk_fma_f32 v[4:5], v[32:33], v[4:5], v[12:13]
	v_pk_fma_f32 v[0:1], v[30:31], v[0:1], v[42:43]
	v_mov_b32_dpp v12, v174 row_shl:15 row_mask:0xf bank_mask:0xf bound_ctrl:1
	v_mov_b32_dpp v13, v175 row_shl:15 row_mask:0xf bank_mask:0xf bound_ctrl:1
	v_mov_b32_dpp v10, v186 row_shr:2 row_mask:0xf bank_mask:0xf
	v_mov_b32_dpp v11, v187 row_shr:2 row_mask:0xf bank_mask:0xf
	v_or_b32_e32 v216, 4, v58
	v_ashrrev_i32_e32 v217, 31, v216
	v_lshlrev_b64 v[216:217], 2, v[216:217]
	v_lshl_add_u64 v[218:219], s[34:35], 0, v[216:217]
	global_load_dwordx4 v[184:187], v[218:219], off
	v_lshl_add_u64 v[218:219], s[20:21], 0, v[216:217]
	global_load_dwordx4 v[188:191], v[218:219], off
	v_lshl_add_u64 v[218:219], s[22:23], 0, v[216:217]
	v_lshl_add_u64 v[216:217], s[18:19], 0, v[216:217]
	global_load_dwordx4 v[192:195], v[218:219], off
	global_load_dwordx4 v[196:199], v[216:217], off
	v_lshl_add_u64 v[216:217], v[58:59], 2, v[144:145]
	v_lshl_add_u64 v[218:219], s[34:35], 0, v[216:217]
	global_load_dwordx4 v[200:203], v[218:219], off
	v_lshl_add_u64 v[218:219], s[20:21], 0, v[216:217]
	global_load_dwordx4 v[204:207], v[218:219], off
	v_lshl_add_u64 v[218:219], s[22:23], 0, v[216:217]
	global_load_dwordx4 v[208:211], v[218:219], off
	v_lshl_add_u64 v[216:217], s[18:19], 0, v[216:217]
	global_load_dwordx4 v[212:215], v[216:217], off
	v_pk_fma_f32 v[0:1], v[26:27], v[2:3], v[0:1]
	v_mov_b32_dpp v12, v180 row_shr:1 row_mask:0xf bank_mask:0xf
	v_mov_b32_dpp v42, v174 row_shl:14 row_mask:0xf bank_mask:0xf bound_ctrl:1
	v_mov_b32_dpp v13, v181 row_shr:1 row_mask:0xf bank_mask:0xf
	v_mov_b32_dpp v43, v175 row_shl:14 row_mask:0xf bank_mask:0xf bound_ctrl:1
	v_pk_fma_f32 v[44:45], v[180:181], v[20:21], v[24:25]
	v_pk_fma_f32 v[2:3], v[28:29], v[10:11], v[4:5]
	v_mov_b32_dpp v42, v180 row_shr:2 row_mask:0xf bank_mask:0xf
	v_mov_b32_dpp v43, v181 row_shr:2 row_mask:0xf bank_mask:0xf
	v_pk_fma_f32 v[12:13], v[16:17], v[12:13], v[44:45]
	v_pk_mul_f32 v[44:45], v[0:1], v[0:1]
	v_pk_fma_f32 v[12:13], v[8:9], v[42:43], v[12:13]
	v_pk_mul_f32 v[42:43], v[2:3], v[2:3]
	v_pk_fma_f32 v[44:45], v[44:45], s[42:43], 1.0 op_sel_hi:[1,0,0]
	v_pk_fma_f32 v[42:43], v[42:43], s[42:43], 1.0 op_sel_hi:[1,0,0]
	v_pk_mul_f32 v[44:45], v[0:1], v[44:45]
	v_pk_mul_f32 v[42:43], v[2:3], v[42:43]
	v_pk_mul_f32 v[44:45], v[44:45], s[44:45] op_sel_hi:[1,0]
	v_pk_mul_f32 v[42:43], v[42:43], s[44:45] op_sel_hi:[1,0]
	v_exp_f32_e32 v44, v44
	v_exp_f32_e32 v45, v45
	v_exp_f32_e32 v42, v42
	v_exp_f32_e32 v43, v43
	v_mov_b32_dpp v4, v176 row_shl:15 row_mask:0xf bank_mask:0xf bound_ctrl:1
	v_pk_add_f32 v[44:45], v[44:45], 1.0 op_sel_hi:[1,0]
	v_mov_b32_dpp v5, v177 row_shl:15 row_mask:0xf bank_mask:0xf bound_ctrl:1
	v_rcp_f32_e32 v44, v44
	v_rcp_f32_e32 v45, v45
	v_pk_add_f32 v[42:43], v[42:43], 1.0 op_sel_hi:[1,0]
	v_mov_b32_dpp v4, v182 row_shr:1 row_mask:0xf bank_mask:0xf
	v_rcp_f32_e32 v42, v42
	v_rcp_f32_e32 v43, v43
	v_mov_b32_dpp v10, v176 row_shl:14 row_mask:0xf bank_mask:0xf bound_ctrl:1
	v_mov_b32_dpp v5, v183 row_shr:1 row_mask:0xf bank_mask:0xf
	v_mov_b32_dpp v11, v177 row_shl:14 row_mask:0xf bank_mask:0xf bound_ctrl:1
	v_mov_b32_dpp v10, v182 row_shr:2 row_mask:0xf bank_mask:0xf
	v_pk_fma_f32 v[4:5], v[14:15], v[4:5], v[52:53]
	v_mov_b32_dpp v11, v183 row_shr:2 row_mask:0xf bank_mask:0xf
	v_pk_fma_f32 v[4:5], v[6:7], v[10:11], v[4:5]
	v_pk_mul_f32 v[0:1], v[0:1], v[44:45]
	v_pk_mul_f32 v[2:3], v[2:3], v[42:43]
	v_pk_mul_f32 v[0:1], v[4:5], v[0:1]
	v_pk_mul_f32 v[2:3], v[12:13], v[2:3]
	v_cvt_pk_bf16_f32 v44, v0, v1
	v_mov_b32_dpp v4, v170 row_shl:14 row_mask:0xf bank_mask:0xf bound_ctrl:1
	v_mov_b32_dpp v0, v170 row_shl:15 row_mask:0xf bank_mask:0xf bound_ctrl:1
	v_mov_b32_dpp v1, v171 row_shl:15 row_mask:0xf bank_mask:0xf bound_ctrl:1
	v_mov_b32_dpp v5, v171 row_shl:14 row_mask:0xf bank_mask:0xf bound_ctrl:1
	v_mov_b32_dpp v42, v172 row_shl:15 row_mask:0xf bank_mask:0xf bound_ctrl:1
	v_mov_b32_dpp v43, v173 row_shl:15 row_mask:0xf bank_mask:0xf bound_ctrl:1
	v_cvt_pk_bf16_f32 v45, v2, v3
	v_mov_b32_e32 v2, v0
	v_mov_b32_e32 v10, v4
	v_mov_b32_e32 v3, v1
	v_mov_b32_e32 v11, v5
	v_mov_b32_e32 v12, v42
	v_mov_b32_dpp v52, v172 row_shl:14 row_mask:0xf bank_mask:0xf bound_ctrl:1
	v_mov_b32_e32 v13, v43
	v_mov_b32_dpp v53, v173 row_shl:14 row_mask:0xf bank_mask:0xf bound_ctrl:1
	v_mov_b32_dpp v2, v170 row_shr:1 row_mask:0xf bank_mask:0xf
	v_mov_b32_dpp v10, v170 row_shr:2 row_mask:0xf bank_mask:0xf
	v_mov_b32_dpp v3, v171 row_shr:1 row_mask:0xf bank_mask:0xf
	v_mov_b32_dpp v11, v171 row_shr:2 row_mask:0xf bank_mask:0xf
	v_mov_b32_dpp v12, v172 row_shr:1 row_mask:0xf bank_mask:0xf
	v_mov_b32_e32 v54, v52
	v_mov_b32_dpp v13, v173 row_shr:1 row_mask:0xf bank_mask:0xf
	v_mov_b32_e32 v55, v53
	v_pk_fma_f32 v[56:57], v[172:173], v[36:37], v[40:41]
	v_pk_fma_f32 v[170:171], v[170:171], v[34:35], v[38:39]
	v_mov_b32_dpp v54, v172 row_shr:2 row_mask:0xf bank_mask:0xf
	v_mov_b32_dpp v55, v173 row_shr:2 row_mask:0xf bank_mask:0xf
	v_pk_fma_f32 v[12:13], v[32:33], v[12:13], v[56:57]
	v_pk_fma_f32 v[2:3], v[30:31], v[2:3], v[170:171]
	v_mov_b32_dpp v56, v166 row_shl:14 row_mask:0xf bank_mask:0xf bound_ctrl:1
	v_pk_fma_f32 v[2:3], v[26:27], v[10:11], v[2:3]
	v_pk_fma_f32 v[10:11], v[28:29], v[54:55], v[12:13]
	v_mov_b32_dpp v54, v166 row_shl:15 row_mask:0xf bank_mask:0xf bound_ctrl:1
	v_mov_b32_dpp v55, v167 row_shl:15 row_mask:0xf bank_mask:0xf bound_ctrl:1
	v_mov_b32_dpp v57, v167 row_shl:14 row_mask:0xf bank_mask:0xf bound_ctrl:1
	v_mov_b32_dpp v172, v168 row_shl:15 row_mask:0xf bank_mask:0xf bound_ctrl:1
	v_mov_b32_dpp v176, v168 row_shl:14 row_mask:0xf bank_mask:0xf bound_ctrl:1
	v_mov_b32_dpp v173, v169 row_shl:15 row_mask:0xf bank_mask:0xf bound_ctrl:1
	v_mov_b32_dpp v177, v169 row_shl:14 row_mask:0xf bank_mask:0xf bound_ctrl:1
	v_mov_b32_e32 v12, v54
	v_mov_b32_e32 v170, v56
	v_mov_b32_e32 v13, v55
	v_mov_b32_e32 v171, v57
	v_mov_b32_e32 v174, v172
	v_mov_b32_e32 v178, v176
	v_mov_b32_e32 v175, v173
	v_mov_b32_e32 v179, v177
	v_mov_b32_dpp v12, v166 row_shr:1 row_mask:0xf bank_mask:0xf
	v_mov_b32_dpp v170, v166 row_shr:2 row_mask:0xf bank_mask:0xf
	v_mov_b32_dpp v13, v167 row_shr:1 row_mask:0xf bank_mask:0xf
	v_mov_b32_dpp v171, v167 row_shr:2 row_mask:0xf bank_mask:0xf
	v_mov_b32_dpp v174, v168 row_shr:1 row_mask:0xf bank_mask:0xf
	v_mov_b32_dpp v178, v168 row_shr:2 row_mask:0xf bank_mask:0xf
	v_mov_b32_dpp v175, v169 row_shr:1 row_mask:0xf bank_mask:0xf
	v_mov_b32_dpp v179, v169 row_shr:2 row_mask:0xf bank_mask:0xf
	v_pk_fma_f32 v[168:169], v[168:169], v[20:21], v[24:25]
	v_pk_fma_f32 v[166:167], v[166:167], v[18:19], v[22:23]
	v_mov_b32_dpp v0, v164 row_shr:1 row_mask:0xf bank_mask:0xf
	v_pk_fma_f32 v[12:13], v[14:15], v[12:13], v[166:167]
	v_pk_fma_f32 v[166:167], v[16:17], v[174:175], v[168:169]
	v_pk_mul_f32 v[168:169], v[10:11], v[10:11]
	v_pk_mul_f32 v[174:175], v[2:3], v[2:3]
	v_pk_fma_f32 v[168:169], v[168:169], s[42:43], 1.0 op_sel_hi:[1,0,0]
	v_pk_fma_f32 v[174:175], v[174:175], s[42:43], 1.0 op_sel_hi:[1,0,0]
	v_pk_mul_f32 v[168:169], v[10:11], v[168:169]
	v_pk_mul_f32 v[174:175], v[2:3], v[174:175]
	v_pk_mul_f32 v[168:169], v[168:169], s[44:45] op_sel_hi:[1,0]
	v_pk_mul_f32 v[174:175], v[174:175], s[44:45] op_sel_hi:[1,0]
	v_exp_f32_e32 v168, v168
	v_exp_f32_e32 v169, v169
	v_exp_f32_e32 v174, v174
	v_exp_f32_e32 v175, v175
	v_pk_fma_f32 v[166:167], v[8:9], v[178:179], v[166:167]
	v_pk_add_f32 v[168:169], v[168:169], 1.0 op_sel_hi:[1,0]
	v_pk_fma_f32 v[12:13], v[6:7], v[170:171], v[12:13]
	v_pk_add_f32 v[174:175], v[174:175], 1.0 op_sel_hi:[1,0]
	v_rcp_f32_e32 v168, v168
	v_rcp_f32_e32 v169, v169
	v_rcp_f32_e32 v174, v174
	v_rcp_f32_e32 v175, v175
	v_mov_b32_dpp v1, v165 row_shr:1 row_mask:0xf bank_mask:0xf
	v_pk_mul_f32 v[10:11], v[10:11], v[168:169]
	v_mov_b32_dpp v4, v164 row_shr:2 row_mask:0xf bank_mask:0xf
	v_pk_mul_f32 v[2:3], v[2:3], v[174:175]
	v_pk_mul_f32 v[10:11], v[166:167], v[10:11]
	v_pk_mul_f32 v[2:3], v[12:13], v[2:3]
	v_mov_b32_dpp v5, v165 row_shr:2 row_mask:0xf bank_mask:0xf
	v_cvt_pk_bf16_f32 v12, v2, v3
	v_cvt_pk_bf16_f32 v13, v10, v11
	v_pk_fma_f32 v[10:11], v[164:165], v[34:35], v[38:39]
	v_mov_b32_dpp v42, v160 row_shr:1 row_mask:0xf bank_mask:0xf
	v_mov_b32_dpp v43, v161 row_shr:1 row_mask:0xf bank_mask:0xf
	v_pk_fma_f32 v[2:3], v[160:161], v[36:37], v[40:41]
	v_pk_fma_f32 v[0:1], v[30:31], v[0:1], v[10:11]
	v_mov_b32_dpp v52, v160 row_shr:2 row_mask:0xf bank_mask:0xf
	v_mov_b32_dpp v53, v161 row_shr:2 row_mask:0xf bank_mask:0xf
	v_pk_fma_f32 v[2:3], v[32:33], v[42:43], v[2:3]
	v_pk_fma_f32 v[0:1], v[26:27], v[4:5], v[0:1]
	v_pk_fma_f32 v[2:3], v[28:29], v[52:53], v[2:3]
	v_pk_mul_f32 v[52:53], v[0:1], v[0:1]
	v_pk_mul_f32 v[42:43], v[2:3], v[2:3]
	v_pk_fma_f32 v[52:53], v[52:53], s[42:43], 1.0 op_sel_hi:[1,0,0]
	v_pk_fma_f32 v[42:43], v[42:43], s[42:43], 1.0 op_sel_hi:[1,0,0]
	v_pk_mul_f32 v[52:53], v[0:1], v[52:53]
	v_pk_mul_f32 v[42:43], v[2:3], v[42:43]
	v_pk_mul_f32 v[52:53], v[52:53], s[44:45] op_sel_hi:[1,0]
	v_pk_mul_f32 v[42:43], v[42:43], s[44:45] op_sel_hi:[1,0]
	v_exp_f32_e32 v52, v52
	v_exp_f32_e32 v53, v53
	v_exp_f32_e32 v42, v42
	v_exp_f32_e32 v43, v43
	v_mov_b32_dpp v54, v162 row_shr:1 row_mask:0xf bank_mask:0xf
	v_pk_add_f32 v[52:53], v[52:53], 1.0 op_sel_hi:[1,0]
	v_mov_b32_dpp v55, v163 row_shr:1 row_mask:0xf bank_mask:0xf
	v_rcp_f32_e32 v52, v52
	v_rcp_f32_e32 v53, v53
	v_pk_add_f32 v[42:43], v[42:43], 1.0 op_sel_hi:[1,0]
	v_pk_fma_f32 v[10:11], v[162:163], v[18:19], v[22:23]
	v_rcp_f32_e32 v42, v42
	v_rcp_f32_e32 v43, v43
	v_mov_b32_dpp v56, v162 row_shr:2 row_mask:0xf bank_mask:0xf
	v_mov_b32_dpp v57, v163 row_shr:2 row_mask:0xf bank_mask:0xf
	v_mov_b32_dpp v172, v158 row_shr:1 row_mask:0xf bank_mask:0xf
	v_mov_b32_dpp v173, v159 row_shr:1 row_mask:0xf bank_mask:0xf
	v_pk_fma_f32 v[4:5], v[158:159], v[20:21], v[24:25]
	v_pk_fma_f32 v[10:11], v[14:15], v[54:55], v[10:11]
	v_mov_b32_dpp v176, v158 row_shr:2 row_mask:0xf bank_mask:0xf
	v_mov_b32_dpp v177, v159 row_shr:2 row_mask:0xf bank_mask:0xf
	v_pk_fma_f32 v[4:5], v[16:17], v[172:173], v[4:5]
	v_pk_fma_f32 v[10:11], v[6:7], v[56:57], v[10:11]
	v_pk_mul_f32 v[0:1], v[0:1], v[52:53]
	v_pk_fma_f32 v[4:5], v[8:9], v[176:177], v[4:5]
	v_pk_mul_f32 v[0:1], v[10:11], v[0:1]
	v_pk_mul_f32 v[2:3], v[2:3], v[42:43]
	v_mov_b32_dpp v10, v160 row_shl:15 row_mask:0xf bank_mask:0xf bound_ctrl:1
	v_pk_mul_f32 v[2:3], v[4:5], v[2:3]
	v_cvt_pk_bf16_f32 v4, v0, v1
	v_mov_b32_dpp v0, v164 row_shl:15 row_mask:0xf bank_mask:0xf bound_ctrl:1
	v_mov_b32_dpp v1, v165 row_shl:15 row_mask:0xf bank_mask:0xf bound_ctrl:1
	v_mov_b32_dpp v11, v161 row_shl:15 row_mask:0xf bank_mask:0xf bound_ctrl:1
	v_cvt_pk_bf16_f32 v5, v2, v3
	v_mov_b32_dpp v0, v152 row_shr:1 row_mask:0xf bank_mask:0xf
	v_mov_b32_dpp v2, v164 row_shl:14 row_mask:0xf bank_mask:0xf bound_ctrl:1
	v_mov_b32_dpp v1, v153 row_shr:1 row_mask:0xf bank_mask:0xf
	v_mov_b32_dpp v3, v165 row_shl:14 row_mask:0xf bank_mask:0xf bound_ctrl:1
	v_mov_b32_dpp v10, v150 row_shr:1 row_mask:0xf bank_mask:0xf
	v_mov_b32_dpp v11, v151 row_shr:1 row_mask:0xf bank_mask:0xf
	v_pk_fma_f32 v[52:53], v[150:151], v[36:37], v[40:41]
	v_pk_fma_f32 v[54:55], v[152:153], v[34:35], v[38:39]
	v_mov_b32_dpp v2, v152 row_shr:2 row_mask:0xf bank_mask:0xf
	v_mov_b32_dpp v3, v153 row_shr:2 row_mask:0xf bank_mask:0xf
	v_mov_b32_dpp v42, v160 row_shl:14 row_mask:0xf bank_mask:0xf bound_ctrl:1
	v_mov_b32_dpp v43, v161 row_shl:14 row_mask:0xf bank_mask:0xf bound_ctrl:1
	v_pk_fma_f32 v[10:11], v[32:33], v[10:11], v[52:53]
	v_pk_fma_f32 v[0:1], v[30:31], v[0:1], v[54:55]
	v_mov_b32_dpp v52, v158 row_shl:15 row_mask:0xf bank_mask:0xf bound_ctrl:1
	v_mov_b32_dpp v53, v159 row_shl:15 row_mask:0xf bank_mask:0xf bound_ctrl:1
	v_mov_b32_dpp v42, v150 row_shr:2 row_mask:0xf bank_mask:0xf
	v_mov_b32_dpp v43, v151 row_shr:2 row_mask:0xf bank_mask:0xf
	v_pk_fma_f32 v[0:1], v[26:27], v[2:3], v[0:1]
	v_mov_b32_dpp v52, v116 row_shr:1 row_mask:0xf bank_mask:0xf
	v_mov_b32_dpp v54, v158 row_shl:14 row_mask:0xf bank_mask:0xf bound_ctrl:1
	v_mov_b32_dpp v53, v117 row_shr:1 row_mask:0xf bank_mask:0xf
	v_mov_b32_dpp v55, v159 row_shl:14 row_mask:0xf bank_mask:0xf bound_ctrl:1
	v_pk_fma_f32 v[56:57], v[116:117], v[20:21], v[24:25]
	v_pk_fma_f32 v[2:3], v[28:29], v[42:43], v[10:11]
	v_mov_b32_dpp v54, v116 row_shr:2 row_mask:0xf bank_mask:0xf
	v_mov_b32_dpp v55, v117 row_shr:2 row_mask:0xf bank_mask:0xf
	v_pk_fma_f32 v[52:53], v[16:17], v[52:53], v[56:57]
	v_pk_mul_f32 v[56:57], v[0:1], v[0:1]
	v_pk_fma_f32 v[52:53], v[8:9], v[54:55], v[52:53]
	v_pk_mul_f32 v[54:55], v[2:3], v[2:3]
	v_pk_fma_f32 v[56:57], v[56:57], s[42:43], 1.0 op_sel_hi:[1,0,0]
	v_pk_fma_f32 v[54:55], v[54:55], s[42:43], 1.0 op_sel_hi:[1,0,0]
	v_pk_mul_f32 v[56:57], v[0:1], v[56:57]
	v_pk_mul_f32 v[54:55], v[2:3], v[54:55]
	v_pk_mul_f32 v[56:57], v[56:57], s[44:45] op_sel_hi:[1,0]
	v_pk_mul_f32 v[54:55], v[54:55], s[44:45] op_sel_hi:[1,0]
	v_exp_f32_e32 v56, v56
	v_exp_f32_e32 v57, v57
	v_exp_f32_e32 v54, v54
	v_exp_f32_e32 v55, v55
	v_mov_b32_dpp v10, v162 row_shl:15 row_mask:0xf bank_mask:0xf bound_ctrl:1
	v_pk_add_f32 v[56:57], v[56:57], 1.0 op_sel_hi:[1,0]
	v_mov_b32_dpp v11, v163 row_shl:15 row_mask:0xf bank_mask:0xf bound_ctrl:1
	v_rcp_f32_e32 v56, v56
	v_rcp_f32_e32 v57, v57
	v_pk_add_f32 v[54:55], v[54:55], 1.0 op_sel_hi:[1,0]
	v_mov_b32_dpp v10, v118 row_shr:1 row_mask:0xf bank_mask:0xf
	v_rcp_f32_e32 v54, v54
	v_rcp_f32_e32 v55, v55
	v_mov_b32_dpp v42, v162 row_shl:14 row_mask:0xf bank_mask:0xf bound_ctrl:1
	v_mov_b32_dpp v11, v119 row_shr:1 row_mask:0xf bank_mask:0xf
	v_mov_b32_dpp v43, v163 row_shl:14 row_mask:0xf bank_mask:0xf bound_ctrl:1
	v_pk_fma_f32 v[158:159], v[118:119], v[18:19], v[22:23]
	v_mov_b32_dpp v42, v118 row_shr:2 row_mask:0xf bank_mask:0xf
	v_mov_b32_dpp v43, v119 row_shr:2 row_mask:0xf bank_mask:0xf
	v_pk_fma_f32 v[10:11], v[14:15], v[10:11], v[158:159]
	v_pk_mul_f32 v[0:1], v[0:1], v[56:57]
	v_pk_fma_f32 v[10:11], v[6:7], v[42:43], v[10:11]
	v_pk_mul_f32 v[2:3], v[2:3], v[54:55]
	v_pk_mul_f32 v[0:1], v[10:11], v[0:1]
	v_pk_mul_f32 v[10:11], v[52:53], v[2:3]
	v_cvt_pk_bf16_f32 v2, v0, v1
	v_mov_b32_dpp v42, v150 row_shl:15 row_mask:0xf bank_mask:0xf bound_ctrl:1
	v_mov_b32_dpp v0, v152 row_shl:15 row_mask:0xf bank_mask:0xf bound_ctrl:1
	v_mov_b32_dpp v1, v153 row_shl:15 row_mask:0xf bank_mask:0xf bound_ctrl:1
	v_cvt_pk_bf16_f32 v3, v10, v11
	v_mov_b32_dpp v10, v152 row_shl:14 row_mask:0xf bank_mask:0xf bound_ctrl:1
	v_mov_b32_dpp v0, v156 row_shr:1 row_mask:0xf bank_mask:0xf
	v_mov_b32_dpp v1, v157 row_shr:1 row_mask:0xf bank_mask:0xf
	v_mov_b32_dpp v11, v153 row_shl:14 row_mask:0xf bank_mask:0xf bound_ctrl:1
	v_mov_b32_dpp v43, v151 row_shl:15 row_mask:0xf bank_mask:0xf bound_ctrl:1
	v_pk_fma_f32 v[34:35], v[156:157], v[34:35], v[38:39]
	v_mov_b32_dpp v10, v156 row_shr:2 row_mask:0xf bank_mask:0xf
	v_mov_b32_dpp v11, v157 row_shr:2 row_mask:0xf bank_mask:0xf
	v_mov_b32_dpp v42, v154 row_shr:1 row_mask:0xf bank_mask:0xf
	v_mov_b32_dpp v52, v150 row_shl:14 row_mask:0xf bank_mask:0xf bound_ctrl:1
	v_mov_b32_dpp v43, v155 row_shr:1 row_mask:0xf bank_mask:0xf
	v_mov_b32_dpp v53, v151 row_shl:14 row_mask:0xf bank_mask:0xf bound_ctrl:1
	v_pk_fma_f32 v[36:37], v[154:155], v[36:37], v[40:41]
	v_pk_fma_f32 v[0:1], v[30:31], v[0:1], v[34:35]
	v_mov_b32_dpp v52, v154 row_shr:2 row_mask:0xf bank_mask:0xf
	v_mov_b32_dpp v53, v155 row_shr:2 row_mask:0xf bank_mask:0xf
	v_pk_fma_f32 v[32:33], v[32:33], v[42:43], v[36:37]
	v_pk_fma_f32 v[0:1], v[26:27], v[10:11], v[0:1]
	v_mov_b32_dpp v26, v118 row_shl:15 row_mask:0xf bank_mask:0xf bound_ctrl:1
	v_mov_b32_dpp v27, v119 row_shl:15 row_mask:0xf bank_mask:0xf bound_ctrl:1
	v_mov_b32_dpp v30, v116 row_shl:15 row_mask:0xf bank_mask:0xf bound_ctrl:1
	v_mov_b32_dpp v31, v117 row_shl:15 row_mask:0xf bank_mask:0xf bound_ctrl:1
	v_pk_fma_f32 v[10:11], v[28:29], v[52:53], v[32:33]
	v_mov_b32_dpp v26, v148 row_shr:1 row_mask:0xf bank_mask:0xf
	v_mov_b32_dpp v27, v149 row_shr:1 row_mask:0xf bank_mask:0xf
	v_mov_b32_dpp v30, v146 row_shr:1 row_mask:0xf bank_mask:0xf
	v_mov_b32_dpp v32, v116 row_shl:14 row_mask:0xf bank_mask:0xf bound_ctrl:1
	v_mov_b32_dpp v31, v147 row_shr:1 row_mask:0xf bank_mask:0xf
	v_mov_b32_dpp v33, v117 row_shl:14 row_mask:0xf bank_mask:0xf bound_ctrl:1
	v_pk_fma_f32 v[20:21], v[146:147], v[20:21], v[24:25]
	v_pk_fma_f32 v[18:19], v[148:149], v[18:19], v[22:23]
	v_mov_b32_dpp v32, v146 row_shr:2 row_mask:0xf bank_mask:0xf
	v_mov_b32_dpp v33, v147 row_shr:2 row_mask:0xf bank_mask:0xf
	v_pk_fma_f32 v[14:15], v[14:15], v[26:27], v[18:19]
	v_pk_fma_f32 v[16:17], v[16:17], v[30:31], v[20:21]
	v_pk_mul_f32 v[18:19], v[0:1], v[0:1]
	v_pk_fma_f32 v[8:9], v[8:9], v[32:33], v[16:17]
	v_pk_mul_f32 v[16:17], v[10:11], v[10:11]
	v_pk_fma_f32 v[18:19], v[18:19], s[42:43], 1.0 op_sel_hi:[1,0,0]
	v_pk_fma_f32 v[16:17], v[16:17], s[42:43], 1.0 op_sel_hi:[1,0,0]
	v_pk_mul_f32 v[18:19], v[0:1], v[18:19]
	v_pk_mul_f32 v[16:17], v[10:11], v[16:17]
	v_pk_mul_f32 v[18:19], v[18:19], s[44:45] op_sel_hi:[1,0]
	v_pk_mul_f32 v[16:17], v[16:17], s[44:45] op_sel_hi:[1,0]
	v_exp_f32_e32 v18, v18
	v_exp_f32_e32 v19, v19
	v_exp_f32_e32 v16, v16
	v_exp_f32_e32 v17, v17
	v_mov_b32_dpp v28, v118 row_shl:14 row_mask:0xf bank_mask:0xf bound_ctrl:1
	v_pk_add_f32 v[18:19], v[18:19], 1.0 op_sel_hi:[1,0]
	v_mov_b32_dpp v29, v119 row_shl:14 row_mask:0xf bank_mask:0xf bound_ctrl:1
	v_rcp_f32_e32 v18, v18
	v_rcp_f32_e32 v19, v19
	v_pk_add_f32 v[16:17], v[16:17], 1.0 op_sel_hi:[1,0]
	v_mov_b32_dpp v28, v148 row_shr:2 row_mask:0xf bank_mask:0xf
	v_rcp_f32_e32 v16, v16
	v_rcp_f32_e32 v17, v17
	v_mov_b32_dpp v29, v149 row_shr:2 row_mask:0xf bank_mask:0xf
	v_pk_fma_f32 v[6:7], v[6:7], v[28:29], v[14:15]
	v_pk_mul_f32 v[0:1], v[0:1], v[18:19]
	v_mov_b32_dpp v52, v124 row_shl:15 row_mask:0xf bank_mask:0xf bound_ctrl:1
	v_pk_mul_f32 v[0:1], v[6:7], v[0:1]
	v_pk_mul_f32 v[6:7], v[10:11], v[16:17]
	v_cvt_pk_bf16_f32 v0, v0, v1
	v_mov_b32_dpp v53, v125 row_shl:15 row_mask:0xf bank_mask:0xf bound_ctrl:1
	v_pk_mul_f32 v[6:7], v[8:9], v[6:7]
	v_mov_b32_dpp v14, v126 row_shl:14 row_mask:0xf bank_mask:0xf bound_ctrl:1
	v_cvt_pk_bf16_f32 v1, v6, v7
	v_mov_b32_dpp v15, v127 row_shl:14 row_mask:0xf bank_mask:0xf bound_ctrl:1
	v_mov_b32_dpp v6, v126 row_shl:15 row_mask:0xf bank_mask:0xf bound_ctrl:1
	v_mov_b32_dpp v7, v127 row_shl:15 row_mask:0xf bank_mask:0xf bound_ctrl:1
	v_mov_b32_dpp v52, v124 row_shr:1 row_mask:0xf bank_mask:0xf
	v_mov_b32_dpp v6, v126 row_shr:1 row_mask:0xf bank_mask:0xf
	v_mov_b32_dpp v7, v127 row_shr:1 row_mask:0xf bank_mask:0xf
	v_mov_b32_dpp v53, v125 row_shr:1 row_mask:0xf bank_mask:0xf
	v_mov_b32_dpp v14, v126 row_shr:2 row_mask:0xf bank_mask:0xf
	v_mov_b32_dpp v15, v127 row_shr:2 row_mask:0xf bank_mask:0xf
	v_mov_b32_dpp v54, v124 row_shl:14 row_mask:0xf bank_mask:0xf bound_ctrl:1
	v_mov_b32_dpp v55, v125 row_shl:14 row_mask:0xf bank_mask:0xf bound_ctrl:1
	s_waitcnt vmcnt(6)
	v_pk_fma_f32 v[56:57], v[124:125], v[186:187], v[190:191]
	v_pk_fma_f32 v[116:117], v[126:127], v[184:185], v[188:189]
	v_mov_b32_dpp v54, v124 row_shr:2 row_mask:0xf bank_mask:0xf
	s_waitcnt vmcnt(5)
	v_pk_fma_f32 v[52:53], v[194:195], v[52:53], v[56:57]
	v_pk_fma_f32 v[6:7], v[192:193], v[6:7], v[116:117]
	v_mov_b32_dpp v56, v120 row_shl:15 row_mask:0xf bank_mask:0xf bound_ctrl:1
	v_mov_b32_dpp v57, v121 row_shl:15 row_mask:0xf bank_mask:0xf bound_ctrl:1
	v_mov_b32_dpp v55, v125 row_shr:2 row_mask:0xf bank_mask:0xf
	s_waitcnt vmcnt(4)
	v_pk_fma_f32 v[6:7], v[196:197], v[14:15], v[6:7]
	v_mov_b32_dpp v56, v120 row_shr:1 row_mask:0xf bank_mask:0xf
	v_mov_b32_dpp v116, v120 row_shl:14 row_mask:0xf bank_mask:0xf bound_ctrl:1
	v_mov_b32_dpp v57, v121 row_shr:1 row_mask:0xf bank_mask:0xf
	v_mov_b32_dpp v117, v121 row_shl:14 row_mask:0xf bank_mask:0xf bound_ctrl:1
	s_waitcnt vmcnt(2)
	v_pk_fma_f32 v[118:119], v[120:121], v[202:203], v[206:207]
	v_pk_fma_f32 v[52:53], v[198:199], v[54:55], v[52:53]
	v_mov_b32_dpp v116, v120 row_shr:2 row_mask:0xf bank_mask:0xf
	v_mov_b32_dpp v117, v121 row_shr:2 row_mask:0xf bank_mask:0xf
	s_waitcnt vmcnt(1)
	v_pk_fma_f32 v[56:57], v[210:211], v[56:57], v[118:119]
	v_pk_mul_f32 v[118:119], v[6:7], v[6:7]
	s_waitcnt vmcnt(0)
	v_pk_fma_f32 v[56:57], v[214:215], v[116:117], v[56:57]
	v_pk_mul_f32 v[116:117], v[52:53], v[52:53]
	v_pk_fma_f32 v[118:119], v[118:119], s[42:43], 1.0 op_sel_hi:[1,0,0]
	v_pk_fma_f32 v[116:117], v[116:117], s[42:43], 1.0 op_sel_hi:[1,0,0]
	v_pk_mul_f32 v[118:119], v[6:7], v[118:119]
	v_pk_mul_f32 v[116:117], v[52:53], v[116:117]
	v_pk_mul_f32 v[118:119], v[118:119], s[44:45] op_sel_hi:[1,0]
	v_pk_mul_f32 v[116:117], v[116:117], s[44:45] op_sel_hi:[1,0]
	v_exp_f32_e32 v118, v118
	v_exp_f32_e32 v119, v119
	v_exp_f32_e32 v116, v116
	v_exp_f32_e32 v117, v117
	v_mov_b32_dpp v14, v122 row_shl:15 row_mask:0xf bank_mask:0xf bound_ctrl:1
	v_pk_add_f32 v[118:119], v[118:119], 1.0 op_sel_hi:[1,0]
	v_mov_b32_dpp v15, v123 row_shl:15 row_mask:0xf bank_mask:0xf bound_ctrl:1
	v_rcp_f32_e32 v118, v118
	v_rcp_f32_e32 v119, v119
	v_pk_add_f32 v[116:117], v[116:117], 1.0 op_sel_hi:[1,0]
	v_mov_b32_dpp v14, v122 row_shr:1 row_mask:0xf bank_mask:0xf
	v_rcp_f32_e32 v116, v116
	v_rcp_f32_e32 v117, v117
	v_mov_b32_dpp v54, v122 row_shl:14 row_mask:0xf bank_mask:0xf bound_ctrl:1
	v_mov_b32_dpp v15, v123 row_shr:1 row_mask:0xf bank_mask:0xf
	v_mov_b32_dpp v55, v123 row_shl:14 row_mask:0xf bank_mask:0xf bound_ctrl:1
	v_pk_fma_f32 v[146:147], v[122:123], v[200:201], v[204:205]
	v_mov_b32_dpp v54, v122 row_shr:2 row_mask:0xf bank_mask:0xf
	v_mov_b32_dpp v55, v123 row_shr:2 row_mask:0xf bank_mask:0xf
	v_pk_fma_f32 v[14:15], v[208:209], v[14:15], v[146:147]
	v_pk_mul_f32 v[6:7], v[6:7], v[118:119]
	v_pk_fma_f32 v[14:15], v[212:213], v[54:55], v[14:15]
	s_nop 0
	v_pk_mul_f32 v[6:7], v[14:15], v[6:7]
	v_pk_mul_f32 v[14:15], v[52:53], v[116:117]
	v_cvt_pk_bf16_f32 v52, v6, v7
	s_nop 0
	v_pk_mul_f32 v[14:15], v[56:57], v[14:15]
	s_nop 0
	v_cvt_pk_bf16_f32 v53, v14, v15
	s_and_saveexec_b64 s[52:53], s[26:27]
	s_cbranch_execz .LBB0_1741
	v_add_u32_e32 v14, -2, v231
	v_mov_b64_e32 v[6:7], s[16:17]
	v_mad_i64_i32 v[6:7], s[26:27], v14, s77, v[6:7]
	v_lshl_add_u64 v[6:7], v[58:59], 1, v[6:7]
	global_store_dwordx4 v[6:7], v[50:53], off
.LBB0_1741:
	s_or_b64 exec, exec, s[52:53]
	s_nop 0
	v_mov_b32_dpp v52, v124 row_shl:15 row_mask:0xf bank_mask:0xf bound_ctrl:1
	v_mov_b32_dpp v53, v125 row_shl:15 row_mask:0xf bank_mask:0xf bound_ctrl:1
	v_mov_b32_dpp v14, v126 row_shl:15 row_mask:0xf bank_mask:0xf bound_ctrl:1
	v_mov_b32_dpp v15, v127 row_shl:15 row_mask:0xf bank_mask:0xf bound_ctrl:1
	v_mov_b32_dpp v52, v112 row_shr:1 row_mask:0xf bank_mask:0xf
	v_mov_b32_dpp v53, v113 row_shr:1 row_mask:0xf bank_mask:0xf
	v_pk_fma_f32 v[56:57], v[112:113], v[186:187], v[190:191]
	v_mov_b32_dpp v14, v114 row_shr:1 row_mask:0xf bank_mask:0xf
	v_mov_b32_dpp v50, v126 row_shl:14 row_mask:0xf bank_mask:0xf bound_ctrl:1
	v_mov_b32_dpp v15, v115 row_shr:1 row_mask:0xf bank_mask:0xf
	v_mov_b32_dpp v51, v127 row_shl:14 row_mask:0xf bank_mask:0xf bound_ctrl:1
	v_mov_b32_dpp v54, v124 row_shl:14 row_mask:0xf bank_mask:0xf bound_ctrl:1
	v_mov_b32_dpp v55, v125 row_shl:14 row_mask:0xf bank_mask:0xf bound_ctrl:1
	v_pk_fma_f32 v[116:117], v[114:115], v[184:185], v[188:189]
	v_pk_fma_f32 v[52:53], v[194:195], v[52:53], v[56:57]
	v_mov_b32_dpp v56, v120 row_shl:15 row_mask:0xf bank_mask:0xf bound_ctrl:1
	v_mov_b32_dpp v57, v121 row_shl:15 row_mask:0xf bank_mask:0xf bound_ctrl:1
	v_mov_b32_dpp v50, v114 row_shr:2 row_mask:0xf bank_mask:0xf
	v_mov_b32_dpp v51, v115 row_shr:2 row_mask:0xf bank_mask:0xf
	v_mov_b32_dpp v54, v112 row_shr:2 row_mask:0xf bank_mask:0xf
	v_mov_b32_dpp v55, v113 row_shr:2 row_mask:0xf bank_mask:0xf
	v_pk_fma_f32 v[14:15], v[192:193], v[14:15], v[116:117]
	v_mov_b32_dpp v56, v108 row_shr:1 row_mask:0xf bank_mask:0xf
	v_mov_b32_dpp v116, v120 row_shl:14 row_mask:0xf bank_mask:0xf bound_ctrl:1
	v_mov_b32_dpp v57, v109 row_shr:1 row_mask:0xf bank_mask:0xf
	v_mov_b32_dpp v117, v121 row_shl:14 row_mask:0xf bank_mask:0xf bound_ctrl:1
	v_pk_fma_f32 v[118:119], v[108:109], v[202:203], v[206:207]
	v_pk_fma_f32 v[14:15], v[196:197], v[50:51], v[14:15]
	v_pk_fma_f32 v[50:51], v[198:199], v[54:55], v[52:53]
	v_mov_b32_dpp v116, v108 row_shr:2 row_mask:0xf bank_mask:0xf
	v_mov_b32_dpp v117, v109 row_shr:2 row_mask:0xf bank_mask:0xf
	v_pk_fma_f32 v[56:57], v[210:211], v[56:57], v[118:119]
	v_pk_mul_f32 v[118:119], v[14:15], v[14:15]
	v_pk_fma_f32 v[56:57], v[214:215], v[116:117], v[56:57]
	v_pk_mul_f32 v[116:117], v[50:51], v[50:51]
	v_pk_fma_f32 v[118:119], v[118:119], s[42:43], 1.0 op_sel_hi:[1,0,0]
	v_pk_fma_f32 v[116:117], v[116:117], s[42:43], 1.0 op_sel_hi:[1,0,0]
	v_pk_mul_f32 v[118:119], v[14:15], v[118:119]
	v_pk_mul_f32 v[116:117], v[50:51], v[116:117]
	v_pk_mul_f32 v[118:119], v[118:119], s[44:45] op_sel_hi:[1,0]
	v_pk_mul_f32 v[116:117], v[116:117], s[44:45] op_sel_hi:[1,0]
	v_exp_f32_e32 v118, v118
	v_exp_f32_e32 v119, v119
	v_exp_f32_e32 v116, v116
	v_exp_f32_e32 v117, v117
	v_mov_b32_dpp v52, v122 row_shl:15 row_mask:0xf bank_mask:0xf bound_ctrl:1
	v_pk_add_f32 v[118:119], v[118:119], 1.0 op_sel_hi:[1,0]
	v_mov_b32_dpp v53, v123 row_shl:15 row_mask:0xf bank_mask:0xf bound_ctrl:1
	v_pk_add_f32 v[116:117], v[116:117], 1.0 op_sel_hi:[1,0]
	v_rcp_f32_e32 v118, v118
	v_rcp_f32_e32 v119, v119
	v_rcp_f32_e32 v116, v116
	v_rcp_f32_e32 v117, v117
	s_add_i32 s26, s47, 16
	v_mov_b32_dpp v52, v110 row_shr:1 row_mask:0xf bank_mask:0xf
	v_mov_b32_dpp v54, v122 row_shl:14 row_mask:0xf bank_mask:0xf bound_ctrl:1
	v_mov_b32_dpp v53, v111 row_shr:1 row_mask:0xf bank_mask:0xf
	v_mov_b32_dpp v55, v123 row_shl:14 row_mask:0xf bank_mask:0xf bound_ctrl:1
	v_pk_fma_f32 v[120:121], v[110:111], v[200:201], v[204:205]
	v_add_u32_e32 v6, s26, v230
	v_mov_b32_dpp v54, v110 row_shr:2 row_mask:0xf bank_mask:0xf
	v_mov_b32_dpp v55, v111 row_shr:2 row_mask:0xf bank_mask:0xf
	v_pk_fma_f32 v[52:53], v[208:209], v[52:53], v[120:121]
	v_pk_mul_f32 v[14:15], v[14:15], v[118:119]
	v_pk_fma_f32 v[52:53], v[212:213], v[54:55], v[52:53]
	v_pk_mul_f32 v[50:51], v[50:51], v[116:117]
	v_cmp_gt_i32_e32 vcc, s76, v6
	v_pk_mul_f32 v[14:15], v[52:53], v[14:15]
	v_pk_mul_f32 v[52:53], v[56:57], v[50:51]
	v_cvt_pk_bf16_f32 v50, v14, v15
	s_nop 0
	v_cvt_pk_bf16_f32 v51, v52, v53
	s_and_saveexec_b64 s[52:53], vcc
	s_cbranch_execz .LBB0_1743
	v_add_u32_e32 v14, -2, v6
	v_mov_b64_e32 v[6:7], s[16:17]
	v_mad_i64_i32 v[6:7], s[54:55], v14, s77, v[6:7]
	v_lshl_add_u64 v[6:7], v[58:59], 1, v[6:7]
	global_store_dwordx4 v[6:7], v[48:51], off
.LBB0_1743:
	s_or_b64 exec, exec, s[52:53]
	s_nop 0
	v_mov_b32_dpp v50, v112 row_shl:15 row_mask:0xf bank_mask:0xf bound_ctrl:1
	v_mov_b32_dpp v51, v113 row_shl:15 row_mask:0xf bank_mask:0xf bound_ctrl:1
	v_mov_b32_dpp v14, v114 row_shl:15 row_mask:0xf bank_mask:0xf bound_ctrl:1
	v_mov_b32_dpp v15, v115 row_shl:15 row_mask:0xf bank_mask:0xf bound_ctrl:1
	v_mov_b32_dpp v50, v98 row_shr:1 row_mask:0xf bank_mask:0xf
	v_mov_b32_dpp v51, v99 row_shr:1 row_mask:0xf bank_mask:0xf
	v_pk_fma_f32 v[54:55], v[98:99], v[186:187], v[190:191]
	v_mov_b32_dpp v14, v102 row_shr:1 row_mask:0xf bank_mask:0xf
	v_mov_b32_dpp v48, v114 row_shl:14 row_mask:0xf bank_mask:0xf bound_ctrl:1
	v_mov_b32_dpp v15, v103 row_shr:1 row_mask:0xf bank_mask:0xf
	v_mov_b32_dpp v49, v115 row_shl:14 row_mask:0xf bank_mask:0xf bound_ctrl:1
	v_mov_b32_dpp v52, v112 row_shl:14 row_mask:0xf bank_mask:0xf bound_ctrl:1
	v_mov_b32_dpp v53, v113 row_shl:14 row_mask:0xf bank_mask:0xf bound_ctrl:1
	v_pk_fma_f32 v[56:57], v[102:103], v[184:185], v[188:189]
	v_pk_fma_f32 v[50:51], v[194:195], v[50:51], v[54:55]
	v_mov_b32_dpp v54, v108 row_shl:15 row_mask:0xf bank_mask:0xf bound_ctrl:1
	v_mov_b32_dpp v55, v109 row_shl:15 row_mask:0xf bank_mask:0xf bound_ctrl:1
	v_mov_b32_dpp v48, v102 row_shr:2 row_mask:0xf bank_mask:0xf
	v_mov_b32_dpp v49, v103 row_shr:2 row_mask:0xf bank_mask:0xf
	v_mov_b32_dpp v52, v98 row_shr:2 row_mask:0xf bank_mask:0xf
	v_mov_b32_dpp v53, v99 row_shr:2 row_mask:0xf bank_mask:0xf
	v_pk_fma_f32 v[14:15], v[192:193], v[14:15], v[56:57]
	v_mov_b32_dpp v54, v92 row_shr:1 row_mask:0xf bank_mask:0xf
	v_mov_b32_dpp v56, v108 row_shl:14 row_mask:0xf bank_mask:0xf bound_ctrl:1
	v_mov_b32_dpp v55, v93 row_shr:1 row_mask:0xf bank_mask:0xf
	v_mov_b32_dpp v57, v109 row_shl:14 row_mask:0xf bank_mask:0xf bound_ctrl:1
	v_pk_fma_f32 v[108:109], v[92:93], v[202:203], v[206:207]
	v_pk_fma_f32 v[14:15], v[196:197], v[48:49], v[14:15]
	v_pk_fma_f32 v[48:49], v[198:199], v[52:53], v[50:51]
	v_mov_b32_dpp v56, v92 row_shr:2 row_mask:0xf bank_mask:0xf
	v_mov_b32_dpp v57, v93 row_shr:2 row_mask:0xf bank_mask:0xf
	v_pk_fma_f32 v[54:55], v[210:211], v[54:55], v[108:109]
	v_pk_mul_f32 v[108:109], v[14:15], v[14:15]
	v_pk_fma_f32 v[54:55], v[214:215], v[56:57], v[54:55]
	v_pk_mul_f32 v[56:57], v[48:49], v[48:49]
	v_pk_fma_f32 v[108:109], v[108:109], s[42:43], 1.0 op_sel_hi:[1,0,0]
	v_pk_fma_f32 v[56:57], v[56:57], s[42:43], 1.0 op_sel_hi:[1,0,0]
	v_pk_mul_f32 v[108:109], v[14:15], v[108:109]
	v_pk_mul_f32 v[56:57], v[48:49], v[56:57]
	v_pk_mul_f32 v[108:109], v[108:109], s[44:45] op_sel_hi:[1,0]
	v_pk_mul_f32 v[56:57], v[56:57], s[44:45] op_sel_hi:[1,0]
	v_exp_f32_e32 v108, v108
	v_exp_f32_e32 v109, v109
	v_exp_f32_e32 v56, v56
	v_exp_f32_e32 v57, v57
	v_mov_b32_dpp v50, v110 row_shl:15 row_mask:0xf bank_mask:0xf bound_ctrl:1
	v_pk_add_f32 v[108:109], v[108:109], 1.0 op_sel_hi:[1,0]
	v_mov_b32_dpp v51, v111 row_shl:15 row_mask:0xf bank_mask:0xf bound_ctrl:1
	v_pk_add_f32 v[56:57], v[56:57], 1.0 op_sel_hi:[1,0]
	v_rcp_f32_e32 v108, v108
	v_rcp_f32_e32 v109, v109
	v_rcp_f32_e32 v56, v56
	v_rcp_f32_e32 v57, v57
	s_add_i32 s27, s47, 32
	v_mov_b32_dpp v50, v94 row_shr:1 row_mask:0xf bank_mask:0xf
	v_mov_b32_dpp v52, v110 row_shl:14 row_mask:0xf bank_mask:0xf bound_ctrl:1
	v_mov_b32_dpp v51, v95 row_shr:1 row_mask:0xf bank_mask:0xf
	v_mov_b32_dpp v53, v111 row_shl:14 row_mask:0xf bank_mask:0xf bound_ctrl:1
	v_pk_fma_f32 v[110:111], v[94:95], v[200:201], v[204:205]
	v_add_u32_e32 v6, s27, v230
	v_mov_b32_dpp v52, v94 row_shr:2 row_mask:0xf bank_mask:0xf
	v_mov_b32_dpp v53, v95 row_shr:2 row_mask:0xf bank_mask:0xf
	v_pk_fma_f32 v[50:51], v[208:209], v[50:51], v[110:111]
	v_pk_mul_f32 v[14:15], v[14:15], v[108:109]
	v_pk_fma_f32 v[50:51], v[212:213], v[52:53], v[50:51]
	v_pk_mul_f32 v[48:49], v[48:49], v[56:57]
	v_cmp_gt_i32_e32 vcc, s76, v6
	v_pk_mul_f32 v[14:15], v[50:51], v[14:15]
	v_pk_mul_f32 v[50:51], v[54:55], v[48:49]
	v_cvt_pk_bf16_f32 v48, v14, v15
	s_nop 0
	v_cvt_pk_bf16_f32 v49, v50, v51
	s_and_saveexec_b64 s[52:53], vcc
	s_cbranch_execz .LBB0_1745
	v_add_u32_e32 v14, -2, v6
	v_mov_b64_e32 v[6:7], s[16:17]
	v_mad_i64_i32 v[6:7], s[54:55], v14, s77, v[6:7]
	v_lshl_add_u64 v[6:7], v[58:59], 1, v[6:7]
	global_store_dwordx4 v[6:7], v[46:49], off
.LBB0_1745:
	s_or_b64 exec, exec, s[52:53]
	s_nop 0
	v_mov_b32_dpp v48, v98 row_shl:15 row_mask:0xf bank_mask:0xf bound_ctrl:1
	v_mov_b32_dpp v49, v99 row_shl:15 row_mask:0xf bank_mask:0xf bound_ctrl:1
	v_mov_b32_dpp v14, v102 row_shl:15 row_mask:0xf bank_mask:0xf bound_ctrl:1
	v_mov_b32_dpp v15, v103 row_shl:15 row_mask:0xf bank_mask:0xf bound_ctrl:1
	v_mov_b32_dpp v48, v104 row_shr:1 row_mask:0xf bank_mask:0xf
	v_mov_b32_dpp v49, v105 row_shr:1 row_mask:0xf bank_mask:0xf
	v_pk_fma_f32 v[52:53], v[104:105], v[186:187], v[190:191]
	v_mov_b32_dpp v14, v106 row_shr:1 row_mask:0xf bank_mask:0xf
	v_mov_b32_dpp v46, v102 row_shl:14 row_mask:0xf bank_mask:0xf bound_ctrl:1
	v_mov_b32_dpp v15, v107 row_shr:1 row_mask:0xf bank_mask:0xf
	v_mov_b32_dpp v47, v103 row_shl:14 row_mask:0xf bank_mask:0xf bound_ctrl:1
	v_mov_b32_dpp v50, v98 row_shl:14 row_mask:0xf bank_mask:0xf bound_ctrl:1
	v_mov_b32_dpp v51, v99 row_shl:14 row_mask:0xf bank_mask:0xf bound_ctrl:1
	v_pk_fma_f32 v[54:55], v[106:107], v[184:185], v[188:189]
	v_pk_fma_f32 v[48:49], v[194:195], v[48:49], v[52:53]
	v_mov_b32_dpp v52, v92 row_shl:15 row_mask:0xf bank_mask:0xf bound_ctrl:1
	v_mov_b32_dpp v53, v93 row_shl:15 row_mask:0xf bank_mask:0xf bound_ctrl:1
	v_mov_b32_dpp v46, v106 row_shr:2 row_mask:0xf bank_mask:0xf
	v_mov_b32_dpp v47, v107 row_shr:2 row_mask:0xf bank_mask:0xf
	v_mov_b32_dpp v50, v104 row_shr:2 row_mask:0xf bank_mask:0xf
	v_mov_b32_dpp v51, v105 row_shr:2 row_mask:0xf bank_mask:0xf
	v_pk_fma_f32 v[14:15], v[192:193], v[14:15], v[54:55]
	v_mov_b32_dpp v52, v96 row_shr:1 row_mask:0xf bank_mask:0xf
	v_mov_b32_dpp v54, v92 row_shl:14 row_mask:0xf bank_mask:0xf bound_ctrl:1
	v_mov_b32_dpp v53, v97 row_shr:1 row_mask:0xf bank_mask:0xf
	v_mov_b32_dpp v55, v93 row_shl:14 row_mask:0xf bank_mask:0xf bound_ctrl:1
	v_pk_fma_f32 v[56:57], v[96:97], v[202:203], v[206:207]
	v_pk_fma_f32 v[14:15], v[196:197], v[46:47], v[14:15]
	v_pk_fma_f32 v[46:47], v[198:199], v[50:51], v[48:49]
	v_mov_b32_dpp v54, v96 row_shr:2 row_mask:0xf bank_mask:0xf
	v_mov_b32_dpp v55, v97 row_shr:2 row_mask:0xf bank_mask:0xf
	v_pk_fma_f32 v[52:53], v[210:211], v[52:53], v[56:57]
	v_pk_mul_f32 v[56:57], v[14:15], v[14:15]
	v_pk_fma_f32 v[52:53], v[214:215], v[54:55], v[52:53]
	v_pk_mul_f32 v[54:55], v[46:47], v[46:47]
	v_pk_fma_f32 v[56:57], v[56:57], s[42:43], 1.0 op_sel_hi:[1,0,0]
	v_pk_fma_f32 v[54:55], v[54:55], s[42:43], 1.0 op_sel_hi:[1,0,0]
	v_pk_mul_f32 v[56:57], v[14:15], v[56:57]
	v_pk_mul_f32 v[54:55], v[46:47], v[54:55]
	v_pk_mul_f32 v[56:57], v[56:57], s[44:45] op_sel_hi:[1,0]
	v_pk_mul_f32 v[54:55], v[54:55], s[44:45] op_sel_hi:[1,0]
	v_exp_f32_e32 v56, v56
	v_exp_f32_e32 v57, v57
	v_exp_f32_e32 v54, v54
	v_exp_f32_e32 v55, v55
	v_mov_b32_dpp v48, v94 row_shl:15 row_mask:0xf bank_mask:0xf bound_ctrl:1
	v_pk_add_f32 v[56:57], v[56:57], 1.0 op_sel_hi:[1,0]
	v_mov_b32_dpp v49, v95 row_shl:15 row_mask:0xf bank_mask:0xf bound_ctrl:1
	v_pk_add_f32 v[54:55], v[54:55], 1.0 op_sel_hi:[1,0]
	v_rcp_f32_e32 v56, v56
	v_rcp_f32_e32 v57, v57
	v_rcp_f32_e32 v54, v54
	v_rcp_f32_e32 v55, v55
	s_add_i32 s54, s47, 48
	v_mov_b32_dpp v48, v100 row_shr:1 row_mask:0xf bank_mask:0xf
	v_mov_b32_dpp v50, v94 row_shl:14 row_mask:0xf bank_mask:0xf bound_ctrl:1
	v_mov_b32_dpp v49, v101 row_shr:1 row_mask:0xf bank_mask:0xf
	v_mov_b32_dpp v51, v95 row_shl:14 row_mask:0xf bank_mask:0xf bound_ctrl:1
	v_pk_fma_f32 v[92:93], v[100:101], v[200:201], v[204:205]
	v_add_u32_e32 v6, s54, v230
	v_mov_b32_dpp v50, v100 row_shr:2 row_mask:0xf bank_mask:0xf
	v_mov_b32_dpp v51, v101 row_shr:2 row_mask:0xf bank_mask:0xf
	v_pk_fma_f32 v[48:49], v[208:209], v[48:49], v[92:93]
	v_pk_mul_f32 v[14:15], v[14:15], v[56:57]
	v_pk_fma_f32 v[48:49], v[212:213], v[50:51], v[48:49]
	v_pk_mul_f32 v[46:47], v[46:47], v[54:55]
	v_cmp_gt_i32_e32 vcc, s76, v6
	v_pk_mul_f32 v[14:15], v[48:49], v[14:15]
	v_pk_mul_f32 v[48:49], v[52:53], v[46:47]
	v_cvt_pk_bf16_f32 v46, v14, v15
	s_nop 0
	v_cvt_pk_bf16_f32 v47, v48, v49
	s_and_saveexec_b64 s[52:53], vcc
	s_cbranch_execz .LBB0_1747
	v_add_u32_e32 v14, -2, v6
	v_mov_b64_e32 v[6:7], s[16:17]
	v_mad_i64_i32 v[6:7], s[70:71], v14, s77, v[6:7]
	v_lshl_add_u64 v[6:7], v[58:59], 1, v[6:7]
	global_store_dwordx4 v[6:7], v[44:47], off
.LBB0_1747:
	s_or_b64 exec, exec, s[52:53]
	v_mov_b32_dpp v14, v90 row_shl:15 row_mask:0xf bank_mask:0xf bound_ctrl:1
	v_mov_b32_dpp v15, v91 row_shl:15 row_mask:0xf bank_mask:0xf bound_ctrl:1
	v_mov_b32_dpp v46, v88 row_shl:15 row_mask:0xf bank_mask:0xf bound_ctrl:1
	v_mov_b32_dpp v47, v89 row_shl:15 row_mask:0xf bank_mask:0xf bound_ctrl:1
	v_mov_b32_dpp v14, v90 row_shr:1 row_mask:0xf bank_mask:0xf
	v_mov_b32_dpp v44, v90 row_shl:14 row_mask:0xf bank_mask:0xf bound_ctrl:1
	v_mov_b32_dpp v15, v91 row_shr:1 row_mask:0xf bank_mask:0xf
	v_mov_b32_dpp v45, v91 row_shl:14 row_mask:0xf bank_mask:0xf bound_ctrl:1
	v_mov_b32_dpp v46, v88 row_shr:1 row_mask:0xf bank_mask:0xf
	v_mov_b32_dpp v47, v89 row_shr:1 row_mask:0xf bank_mask:0xf
	v_pk_fma_f32 v[50:51], v[88:89], v[186:187], v[190:191]
	v_pk_fma_f32 v[52:53], v[90:91], v[184:185], v[188:189]
	v_mov_b32_dpp v44, v90 row_shr:2 row_mask:0xf bank_mask:0xf
	v_mov_b32_dpp v45, v91 row_shr:2 row_mask:0xf bank_mask:0xf
	v_mov_b32_dpp v48, v88 row_shl:14 row_mask:0xf bank_mask:0xf bound_ctrl:1
	v_mov_b32_dpp v49, v89 row_shl:14 row_mask:0xf bank_mask:0xf bound_ctrl:1
	v_pk_fma_f32 v[46:47], v[194:195], v[46:47], v[50:51]
	v_pk_fma_f32 v[14:15], v[192:193], v[14:15], v[52:53]
	v_mov_b32_dpp v50, v84 row_shl:15 row_mask:0xf bank_mask:0xf bound_ctrl:1
	v_mov_b32_dpp v51, v85 row_shl:15 row_mask:0xf bank_mask:0xf bound_ctrl:1
	v_mov_b32_dpp v48, v88 row_shr:2 row_mask:0xf bank_mask:0xf
	v_mov_b32_dpp v49, v89 row_shr:2 row_mask:0xf bank_mask:0xf
	v_pk_fma_f32 v[14:15], v[196:197], v[44:45], v[14:15]
	v_mov_b32_dpp v50, v84 row_shr:1 row_mask:0xf bank_mask:0xf
	v_mov_b32_dpp v52, v84 row_shl:14 row_mask:0xf bank_mask:0xf bound_ctrl:1
	v_mov_b32_dpp v51, v85 row_shr:1 row_mask:0xf bank_mask:0xf
	v_mov_b32_dpp v53, v85 row_shl:14 row_mask:0xf bank_mask:0xf bound_ctrl:1
	v_pk_fma_f32 v[54:55], v[84:85], v[202:203], v[206:207]
	v_pk_fma_f32 v[44:45], v[198:199], v[48:49], v[46:47]
	v_mov_b32_dpp v52, v84 row_shr:2 row_mask:0xf bank_mask:0xf
	v_mov_b32_dpp v53, v85 row_shr:2 row_mask:0xf bank_mask:0xf
	v_pk_fma_f32 v[50:51], v[210:211], v[50:51], v[54:55]
	v_pk_mul_f32 v[54:55], v[14:15], v[14:15]
	v_pk_fma_f32 v[50:51], v[214:215], v[52:53], v[50:51]
	v_pk_mul_f32 v[52:53], v[44:45], v[44:45]
	v_pk_fma_f32 v[54:55], v[54:55], s[42:43], 1.0 op_sel_hi:[1,0,0]
	v_pk_fma_f32 v[52:53], v[52:53], s[42:43], 1.0 op_sel_hi:[1,0,0]
	v_pk_mul_f32 v[54:55], v[14:15], v[54:55]
	v_pk_mul_f32 v[52:53], v[44:45], v[52:53]
	v_pk_mul_f32 v[54:55], v[54:55], s[44:45] op_sel_hi:[1,0]
	v_pk_mul_f32 v[52:53], v[52:53], s[44:45] op_sel_hi:[1,0]
	v_exp_f32_e32 v54, v54
	v_exp_f32_e32 v55, v55
	v_exp_f32_e32 v52, v52
	v_exp_f32_e32 v53, v53
	v_mov_b32_dpp v46, v86 row_shl:15 row_mask:0xf bank_mask:0xf bound_ctrl:1
	v_pk_add_f32 v[54:55], v[54:55], 1.0 op_sel_hi:[1,0]
	v_mov_b32_dpp v47, v87 row_shl:15 row_mask:0xf bank_mask:0xf bound_ctrl:1
	v_rcp_f32_e32 v54, v54
	v_rcp_f32_e32 v55, v55
	v_pk_add_f32 v[52:53], v[52:53], 1.0 op_sel_hi:[1,0]
	v_mov_b32_dpp v46, v86 row_shr:1 row_mask:0xf bank_mask:0xf
	v_rcp_f32_e32 v52, v52
	v_rcp_f32_e32 v53, v53
	v_mov_b32_dpp v48, v86 row_shl:14 row_mask:0xf bank_mask:0xf bound_ctrl:1
	v_mov_b32_dpp v47, v87 row_shr:1 row_mask:0xf bank_mask:0xf
	v_mov_b32_dpp v49, v87 row_shl:14 row_mask:0xf bank_mask:0xf bound_ctrl:1
	v_pk_fma_f32 v[56:57], v[86:87], v[200:201], v[204:205]
	v_add_u32_e32 v6, s47, v229
	v_mov_b32_dpp v48, v86 row_shr:2 row_mask:0xf bank_mask:0xf
	v_mov_b32_dpp v49, v87 row_shr:2 row_mask:0xf bank_mask:0xf
	v_pk_fma_f32 v[46:47], v[208:209], v[46:47], v[56:57]
	v_pk_mul_f32 v[14:15], v[14:15], v[54:55]
	v_pk_fma_f32 v[46:47], v[212:213], v[48:49], v[46:47]
	v_cmp_gt_i32_e32 vcc, s76, v6
	v_pk_mul_f32 v[14:15], v[46:47], v[14:15]
	v_pk_mul_f32 v[44:45], v[44:45], v[52:53]
	s_and_b64 s[52:53], s[10:11], vcc
	v_pk_mul_f32 v[44:45], v[50:51], v[44:45]
	v_cvt_pk_bf16_f32 v14, v14, v15
	s_nop 0
	v_cvt_pk_bf16_f32 v15, v44, v45
	s_and_saveexec_b64 s[10:11], s[52:53]
	s_cbranch_execz .LBB0_1749
	v_add_u32_e32 v44, -2, v6
	v_mov_b64_e32 v[6:7], s[16:17]
	v_mad_i64_i32 v[6:7], s[52:53], v44, s77, v[6:7]
	v_lshl_add_u64 v[6:7], v[58:59], 1, v[6:7]
	global_store_dwordx4 v[6:7], v[12:15], off
.LBB0_1749:
	s_or_b64 exec, exec, s[10:11]
	v_mov_b32_dpp v6, v90 row_shl:15 row_mask:0xf bank_mask:0xf bound_ctrl:1
	v_mov_b32_dpp v7, v91 row_shl:15 row_mask:0xf bank_mask:0xf bound_ctrl:1
	v_mov_b32_dpp v44, v88 row_shl:15 row_mask:0xf bank_mask:0xf bound_ctrl:1
	v_mov_b32_dpp v45, v89 row_shl:15 row_mask:0xf bank_mask:0xf bound_ctrl:1
	v_mov_b32_dpp v6, v82 row_shr:1 row_mask:0xf bank_mask:0xf
	v_mov_b32_dpp v14, v90 row_shl:14 row_mask:0xf bank_mask:0xf bound_ctrl:1
	v_mov_b32_dpp v7, v83 row_shr:1 row_mask:0xf bank_mask:0xf
	v_mov_b32_dpp v15, v91 row_shl:14 row_mask:0xf bank_mask:0xf bound_ctrl:1
	v_mov_b32_dpp v44, v80 row_shr:1 row_mask:0xf bank_mask:0xf
	v_mov_b32_dpp v45, v81 row_shr:1 row_mask:0xf bank_mask:0xf
	v_pk_fma_f32 v[48:49], v[80:81], v[186:187], v[190:191]
	v_pk_fma_f32 v[50:51], v[82:83], v[184:185], v[188:189]
	v_mov_b32_dpp v14, v82 row_shr:2 row_mask:0xf bank_mask:0xf
	v_mov_b32_dpp v15, v83 row_shr:2 row_mask:0xf bank_mask:0xf
	v_mov_b32_dpp v46, v88 row_shl:14 row_mask:0xf bank_mask:0xf bound_ctrl:1
	v_mov_b32_dpp v47, v89 row_shl:14 row_mask:0xf bank_mask:0xf bound_ctrl:1
	v_pk_fma_f32 v[44:45], v[194:195], v[44:45], v[48:49]
	v_pk_fma_f32 v[6:7], v[192:193], v[6:7], v[50:51]
	v_mov_b32_dpp v48, v84 row_shl:15 row_mask:0xf bank_mask:0xf bound_ctrl:1
	v_mov_b32_dpp v49, v85 row_shl:15 row_mask:0xf bank_mask:0xf bound_ctrl:1
	v_mov_b32_dpp v46, v80 row_shr:2 row_mask:0xf bank_mask:0xf
	v_mov_b32_dpp v47, v81 row_shr:2 row_mask:0xf bank_mask:0xf
	v_pk_fma_f32 v[6:7], v[196:197], v[14:15], v[6:7]
	v_mov_b32_dpp v48, v76 row_shr:1 row_mask:0xf bank_mask:0xf
	v_mov_b32_dpp v50, v84 row_shl:14 row_mask:0xf bank_mask:0xf bound_ctrl:1
	v_mov_b32_dpp v49, v77 row_shr:1 row_mask:0xf bank_mask:0xf
	v_mov_b32_dpp v51, v85 row_shl:14 row_mask:0xf bank_mask:0xf bound_ctrl:1
	v_pk_fma_f32 v[52:53], v[76:77], v[202:203], v[206:207]
	v_pk_fma_f32 v[14:15], v[198:199], v[46:47], v[44:45]
	v_mov_b32_dpp v50, v76 row_shr:2 row_mask:0xf bank_mask:0xf
	v_mov_b32_dpp v51, v77 row_shr:2 row_mask:0xf bank_mask:0xf
	v_pk_fma_f32 v[48:49], v[210:211], v[48:49], v[52:53]
	v_pk_mul_f32 v[52:53], v[6:7], v[6:7]
	v_pk_fma_f32 v[48:49], v[214:215], v[50:51], v[48:49]
	v_pk_mul_f32 v[50:51], v[14:15], v[14:15]
	v_pk_fma_f32 v[52:53], v[52:53], s[42:43], 1.0 op_sel_hi:[1,0,0]
	v_pk_fma_f32 v[50:51], v[50:51], s[42:43], 1.0 op_sel_hi:[1,0,0]
	v_pk_mul_f32 v[52:53], v[6:7], v[52:53]
	v_pk_mul_f32 v[50:51], v[14:15], v[50:51]
	v_pk_mul_f32 v[52:53], v[52:53], s[44:45] op_sel_hi:[1,0]
	v_pk_mul_f32 v[50:51], v[50:51], s[44:45] op_sel_hi:[1,0]
	v_exp_f32_e32 v52, v52
	v_exp_f32_e32 v53, v53
	v_exp_f32_e32 v50, v50
	v_exp_f32_e32 v51, v51
	v_mov_b32_dpp v44, v86 row_shl:15 row_mask:0xf bank_mask:0xf bound_ctrl:1
	v_pk_add_f32 v[52:53], v[52:53], 1.0 op_sel_hi:[1,0]
	v_mov_b32_dpp v45, v87 row_shl:15 row_mask:0xf bank_mask:0xf bound_ctrl:1
	v_rcp_f32_e32 v52, v52
	v_rcp_f32_e32 v53, v53
	v_pk_add_f32 v[50:51], v[50:51], 1.0 op_sel_hi:[1,0]
	v_mov_b32_dpp v44, v78 row_shr:1 row_mask:0xf bank_mask:0xf
	v_rcp_f32_e32 v50, v50
	v_rcp_f32_e32 v51, v51
	v_mov_b32_dpp v46, v86 row_shl:14 row_mask:0xf bank_mask:0xf bound_ctrl:1
	v_mov_b32_dpp v45, v79 row_shr:1 row_mask:0xf bank_mask:0xf
	v_mov_b32_dpp v47, v87 row_shl:14 row_mask:0xf bank_mask:0xf bound_ctrl:1
	v_pk_fma_f32 v[54:55], v[78:79], v[200:201], v[204:205]
	v_mov_b32_dpp v46, v78 row_shr:2 row_mask:0xf bank_mask:0xf
	v_mov_b32_dpp v47, v79 row_shr:2 row_mask:0xf bank_mask:0xf
	v_pk_fma_f32 v[44:45], v[208:209], v[44:45], v[54:55]
	v_add_u32_e32 v12, s26, v229
	v_pk_fma_f32 v[44:45], v[212:213], v[46:47], v[44:45]
	v_pk_mul_f32 v[6:7], v[6:7], v[52:53]
	v_pk_mul_f32 v[14:15], v[14:15], v[50:51]
	v_pk_mul_f32 v[6:7], v[44:45], v[6:7]
	v_cmp_gt_i32_e32 vcc, s76, v12
	v_pk_mul_f32 v[14:15], v[48:49], v[14:15]
	v_cvt_pk_bf16_f32 v6, v6, v7
	s_nop 0
	v_cvt_pk_bf16_f32 v7, v14, v15
	s_and_saveexec_b64 s[10:11], vcc
	s_cbranch_execz .LBB0_1751
	v_add_u32_e32 v14, -2, v12
	v_mov_b64_e32 v[12:13], s[16:17]
	v_mad_i64_i32 v[12:13], s[52:53], v14, s77, v[12:13]
	v_lshl_add_u64 v[12:13], v[58:59], 1, v[12:13]
	global_store_dwordx4 v[12:13], v[4:7], off
.LBB0_1751:
	s_or_b64 exec, exec, s[10:11]
	s_nop 0
	v_mov_b32_dpp v4, v82 row_shl:15 row_mask:0xf bank_mask:0xf bound_ctrl:1
	v_mov_b32_dpp v5, v83 row_shl:15 row_mask:0xf bank_mask:0xf bound_ctrl:1
	v_mov_b32_dpp v14, v80 row_shl:15 row_mask:0xf bank_mask:0xf bound_ctrl:1
	v_mov_b32_dpp v15, v81 row_shl:15 row_mask:0xf bank_mask:0xf bound_ctrl:1
	v_mov_b32_dpp v4, v70 row_shr:1 row_mask:0xf bank_mask:0xf
	v_mov_b32_dpp v12, v82 row_shl:14 row_mask:0xf bank_mask:0xf bound_ctrl:1
	v_mov_b32_dpp v5, v71 row_shr:1 row_mask:0xf bank_mask:0xf
	v_mov_b32_dpp v13, v83 row_shl:14 row_mask:0xf bank_mask:0xf bound_ctrl:1
	v_mov_b32_dpp v14, v68 row_shr:1 row_mask:0xf bank_mask:0xf
	v_mov_b32_dpp v15, v69 row_shr:1 row_mask:0xf bank_mask:0xf
	v_pk_fma_f32 v[46:47], v[68:69], v[186:187], v[190:191]
	v_pk_fma_f32 v[48:49], v[70:71], v[184:185], v[188:189]
	v_mov_b32_dpp v12, v70 row_shr:2 row_mask:0xf bank_mask:0xf
	v_mov_b32_dpp v13, v71 row_shr:2 row_mask:0xf bank_mask:0xf
	v_mov_b32_dpp v44, v80 row_shl:14 row_mask:0xf bank_mask:0xf bound_ctrl:1
	v_mov_b32_dpp v45, v81 row_shl:14 row_mask:0xf bank_mask:0xf bound_ctrl:1
	v_pk_fma_f32 v[14:15], v[194:195], v[14:15], v[46:47]
	v_pk_fma_f32 v[4:5], v[192:193], v[4:5], v[48:49]
	v_mov_b32_dpp v46, v76 row_shl:15 row_mask:0xf bank_mask:0xf bound_ctrl:1
	v_mov_b32_dpp v47, v77 row_shl:15 row_mask:0xf bank_mask:0xf bound_ctrl:1
	v_mov_b32_dpp v44, v68 row_shr:2 row_mask:0xf bank_mask:0xf
	v_mov_b32_dpp v45, v69 row_shr:2 row_mask:0xf bank_mask:0xf
	v_pk_fma_f32 v[4:5], v[196:197], v[12:13], v[4:5]
	v_mov_b32_dpp v46, v60 row_shr:1 row_mask:0xf bank_mask:0xf
	v_mov_b32_dpp v48, v76 row_shl:14 row_mask:0xf bank_mask:0xf bound_ctrl:1
	v_mov_b32_dpp v47, v61 row_shr:1 row_mask:0xf bank_mask:0xf
	v_mov_b32_dpp v49, v77 row_shl:14 row_mask:0xf bank_mask:0xf bound_ctrl:1
	v_pk_fma_f32 v[50:51], v[60:61], v[202:203], v[206:207]
	v_pk_fma_f32 v[12:13], v[198:199], v[44:45], v[14:15]
	v_mov_b32_dpp v48, v60 row_shr:2 row_mask:0xf bank_mask:0xf
	v_mov_b32_dpp v49, v61 row_shr:2 row_mask:0xf bank_mask:0xf
	v_pk_fma_f32 v[46:47], v[210:211], v[46:47], v[50:51]
	v_pk_mul_f32 v[50:51], v[4:5], v[4:5]
	v_pk_fma_f32 v[46:47], v[214:215], v[48:49], v[46:47]
	v_pk_mul_f32 v[48:49], v[12:13], v[12:13]
	v_pk_fma_f32 v[50:51], v[50:51], s[42:43], 1.0 op_sel_hi:[1,0,0]
	v_pk_fma_f32 v[48:49], v[48:49], s[42:43], 1.0 op_sel_hi:[1,0,0]
	v_pk_mul_f32 v[50:51], v[4:5], v[50:51]
	v_pk_mul_f32 v[48:49], v[12:13], v[48:49]
	v_pk_mul_f32 v[50:51], v[50:51], s[44:45] op_sel_hi:[1,0]
	v_pk_mul_f32 v[48:49], v[48:49], s[44:45] op_sel_hi:[1,0]
	v_exp_f32_e32 v50, v50
	v_exp_f32_e32 v51, v51
	v_exp_f32_e32 v48, v48
	v_exp_f32_e32 v49, v49
	v_mov_b32_dpp v14, v78 row_shl:15 row_mask:0xf bank_mask:0xf bound_ctrl:1
	v_pk_add_f32 v[50:51], v[50:51], 1.0 op_sel_hi:[1,0]
	v_mov_b32_dpp v15, v79 row_shl:15 row_mask:0xf bank_mask:0xf bound_ctrl:1
	v_rcp_f32_e32 v50, v50
	v_rcp_f32_e32 v51, v51
	v_pk_add_f32 v[48:49], v[48:49], 1.0 op_sel_hi:[1,0]
	v_mov_b32_dpp v14, v62 row_shr:1 row_mask:0xf bank_mask:0xf
	v_rcp_f32_e32 v48, v48
	v_rcp_f32_e32 v49, v49
	v_mov_b32_dpp v44, v78 row_shl:14 row_mask:0xf bank_mask:0xf bound_ctrl:1
	v_mov_b32_dpp v15, v63 row_shr:1 row_mask:0xf bank_mask:0xf
	v_mov_b32_dpp v45, v79 row_shl:14 row_mask:0xf bank_mask:0xf bound_ctrl:1
	v_pk_fma_f32 v[52:53], v[62:63], v[200:201], v[204:205]
	v_mov_b32_dpp v44, v62 row_shr:2 row_mask:0xf bank_mask:0xf
	v_mov_b32_dpp v45, v63 row_shr:2 row_mask:0xf bank_mask:0xf
	v_pk_fma_f32 v[14:15], v[208:209], v[14:15], v[52:53]
	v_add_u32_e32 v6, s27, v229
	v_pk_fma_f32 v[14:15], v[212:213], v[44:45], v[14:15]
	v_pk_mul_f32 v[4:5], v[4:5], v[50:51]
	v_pk_mul_f32 v[12:13], v[12:13], v[48:49]
	v_pk_mul_f32 v[4:5], v[14:15], v[4:5]
	v_cmp_gt_i32_e32 vcc, s76, v6
	v_pk_mul_f32 v[12:13], v[46:47], v[12:13]
	v_cvt_pk_bf16_f32 v4, v4, v5
	s_nop 0
	v_cvt_pk_bf16_f32 v5, v12, v13
	s_and_saveexec_b64 s[10:11], vcc
	s_cbranch_execz .LBB0_1753
	v_add_u32_e32 v12, -2, v6
	v_mov_b64_e32 v[6:7], s[16:17]
	v_mad_i64_i32 v[6:7], s[26:27], v12, s77, v[6:7]
	v_lshl_add_u64 v[6:7], v[58:59], 1, v[6:7]
	global_store_dwordx4 v[6:7], v[2:5], off
.LBB0_1753:
	s_or_b64 exec, exec, s[10:11]
	s_nop 0
	v_mov_b32_dpp v2, v70 row_shl:15 row_mask:0xf bank_mask:0xf bound_ctrl:1
	v_mov_b32_dpp v3, v71 row_shl:15 row_mask:0xf bank_mask:0xf bound_ctrl:1
	v_mov_b32_dpp v12, v68 row_shl:15 row_mask:0xf bank_mask:0xf bound_ctrl:1
	v_mov_b32_dpp v13, v69 row_shl:15 row_mask:0xf bank_mask:0xf bound_ctrl:1
	v_mov_b32_dpp v2, v74 row_shr:1 row_mask:0xf bank_mask:0xf
	v_mov_b32_dpp v6, v70 row_shl:14 row_mask:0xf bank_mask:0xf bound_ctrl:1
	v_mov_b32_dpp v3, v75 row_shr:1 row_mask:0xf bank_mask:0xf
	v_mov_b32_dpp v7, v71 row_shl:14 row_mask:0xf bank_mask:0xf bound_ctrl:1
	v_mov_b32_dpp v12, v72 row_shr:1 row_mask:0xf bank_mask:0xf
	v_mov_b32_dpp v14, v68 row_shl:14 row_mask:0xf bank_mask:0xf bound_ctrl:1
	v_mov_b32_dpp v13, v73 row_shr:1 row_mask:0xf bank_mask:0xf
	v_mov_b32_dpp v15, v69 row_shl:14 row_mask:0xf bank_mask:0xf bound_ctrl:1
	v_pk_fma_f32 v[38:39], v[72:73], v[186:187], v[190:191]
	v_pk_fma_f32 v[36:37], v[74:75], v[184:185], v[188:189]
	v_mov_b32_dpp v6, v74 row_shr:2 row_mask:0xf bank_mask:0xf
	v_mov_b32_dpp v7, v75 row_shr:2 row_mask:0xf bank_mask:0xf
	v_mov_b32_dpp v14, v72 row_shr:2 row_mask:0xf bank_mask:0xf
	v_mov_b32_dpp v15, v73 row_shr:2 row_mask:0xf bank_mask:0xf
	v_pk_fma_f32 v[12:13], v[194:195], v[12:13], v[38:39]
	v_pk_fma_f32 v[2:3], v[192:193], v[2:3], v[36:37]
	v_pk_fma_f32 v[22:23], v[64:65], v[202:203], v[206:207]
	v_pk_fma_f32 v[2:3], v[196:197], v[6:7], v[2:3]
	v_pk_fma_f32 v[6:7], v[198:199], v[14:15], v[12:13]
	v_mov_b32_dpp v12, v62 row_shl:15 row_mask:0xf bank_mask:0xf bound_ctrl:1
	v_mov_b32_dpp v13, v63 row_shl:15 row_mask:0xf bank_mask:0xf bound_ctrl:1
	v_mov_b32_dpp v28, v60 row_shl:15 row_mask:0xf bank_mask:0xf bound_ctrl:1
	v_mov_b32_dpp v29, v61 row_shl:15 row_mask:0xf bank_mask:0xf bound_ctrl:1
	v_mov_b32_dpp v12, v66 row_shr:1 row_mask:0xf bank_mask:0xf
	v_mov_b32_dpp v13, v67 row_shr:1 row_mask:0xf bank_mask:0xf
	v_mov_b32_dpp v28, v64 row_shr:1 row_mask:0xf bank_mask:0xf
	v_mov_b32_dpp v30, v60 row_shl:14 row_mask:0xf bank_mask:0xf bound_ctrl:1
	v_mov_b32_dpp v29, v65 row_shr:1 row_mask:0xf bank_mask:0xf
	v_mov_b32_dpp v31, v61 row_shl:14 row_mask:0xf bank_mask:0xf bound_ctrl:1
	v_pk_fma_f32 v[20:21], v[66:67], v[200:201], v[204:205]
	v_mov_b32_dpp v30, v64 row_shr:2 row_mask:0xf bank_mask:0xf
	v_mov_b32_dpp v31, v65 row_shr:2 row_mask:0xf bank_mask:0xf
	v_pk_fma_f32 v[12:13], v[208:209], v[12:13], v[20:21]
	v_pk_fma_f32 v[16:17], v[210:211], v[28:29], v[22:23]
	v_pk_mul_f32 v[18:19], v[2:3], v[2:3]
	v_pk_fma_f32 v[10:11], v[214:215], v[30:31], v[16:17]
	v_pk_mul_f32 v[16:17], v[6:7], v[6:7]
	v_pk_fma_f32 v[18:19], v[18:19], s[42:43], 1.0 op_sel_hi:[1,0,0]
	v_pk_fma_f32 v[16:17], v[16:17], s[42:43], 1.0 op_sel_hi:[1,0,0]
	v_pk_mul_f32 v[18:19], v[2:3], v[18:19]
	v_pk_mul_f32 v[16:17], v[6:7], v[16:17]
	v_pk_mul_f32 v[18:19], v[18:19], s[44:45] op_sel_hi:[1,0]
	v_pk_mul_f32 v[16:17], v[16:17], s[44:45] op_sel_hi:[1,0]
	v_exp_f32_e32 v18, v18
	v_exp_f32_e32 v19, v19
	v_exp_f32_e32 v16, v16
	v_exp_f32_e32 v17, v17
	v_mov_b32_dpp v14, v62 row_shl:14 row_mask:0xf bank_mask:0xf bound_ctrl:1
	v_pk_add_f32 v[18:19], v[18:19], 1.0 op_sel_hi:[1,0]
	v_mov_b32_dpp v15, v63 row_shl:14 row_mask:0xf bank_mask:0xf bound_ctrl:1
	v_rcp_f32_e32 v18, v18
	v_rcp_f32_e32 v19, v19
	v_pk_add_f32 v[16:17], v[16:17], 1.0 op_sel_hi:[1,0]
	v_mov_b32_dpp v14, v66 row_shr:2 row_mask:0xf bank_mask:0xf
	v_rcp_f32_e32 v16, v16
	v_rcp_f32_e32 v17, v17
	v_mov_b32_dpp v15, v67 row_shr:2 row_mask:0xf bank_mask:0xf
	v_add_u32_e32 v5, s54, v229
	v_pk_fma_f32 v[8:9], v[212:213], v[14:15], v[12:13]
	v_pk_mul_f32 v[2:3], v[2:3], v[18:19]
	v_pk_mul_f32 v[6:7], v[6:7], v[16:17]
	v_pk_mul_f32 v[2:3], v[8:9], v[2:3]
	v_cmp_gt_i32_e32 vcc, s76, v5
	v_pk_mul_f32 v[6:7], v[10:11], v[6:7]
	v_cvt_pk_bf16_f32 v2, v2, v3
	s_nop 0
	v_cvt_pk_bf16_f32 v3, v6, v7
	s_and_saveexec_b64 s[10:11], vcc
	v_add_u32_e32 v4, -2, v5
	s_or_b64 s[12:13], s[12:13], exec
	s_or_b64 exec, exec, s[10:11]
